# rmsnorm 4-row blocks (P0,R1,R2,R3): gain vectors loaded once, per-row reloads and store-only vmcnt waits removed
# speedup vs baseline: 1.0226x; 1.0226x over previous
.LBB0_22:
	s_add_u32 s36, s22, 0x9800000
	s_mov_b32 s8, 0
	s_addc_u32 s37, s23, 0
	s_ashr_i32 s9, s8, 31
	s_lshl_b64 s[8:9], s[8:9], 3
	s_add_u32 s8, s0, s8
	s_addc_u32 s9, s1, s9
	s_mov_b32 s10, 1
	s_load_dwordx2 s[8:9], s[8:9], 0x0
	s_ashr_i32 s11, s10, 31
	s_lshl_b64 s[10:11], s[10:11], 3
	s_add_u32 s10, s0, s10
	s_addc_u32 s11, s1, s11
	s_mov_b32 s12, 5
	s_load_dwordx2 s[10:11], s[10:11], 0x0
	s_ashr_i32 s13, s12, 31
	s_lshl_b64 s[12:13], s[12:13], 3
	s_add_u32 s12, s0, s12
	s_addc_u32 s13, s1, s13
	s_load_dwordx2 s[14:15], s[12:13], 0x0
	s_ashr_i32 s5, s4, 31
	s_lshl_b64 s[4:5], s[4:5], 3
	s_add_u32 s4, s0, s4
	s_addc_u32 s5, s1, s5
	s_load_dwordx2 s[34:35], s[4:5], 0x0
	s_mov_b32 s4, 17
	s_ashr_i32 s5, s4, 31
	s_lshl_b64 s[4:5], s[4:5], 3
	s_add_u32 s4, s0, s4
	s_addc_u32 s5, s1, s5
	s_mul_i32 s3, s26, 24
	s_load_dwordx2 s[38:39], s[4:5], 0x0
	s_add_i32 s12, s24, s3
	s_mov_b32 s4, s12
	v_writelane_b32 v226, s4, 1
	s_cmpk_lt_i32 s12, 0x2000
	v_mbcnt_lo_u32_b32 v165, -1, 0
	v_writelane_b32 v226, s5, 2
	s_cselect_b64 s[4:5], -1, 0
	v_writelane_b32 v226, s4, 3
	s_and_b64 vcc, exec, s[4:5]
	v_lshlrev_b32_e32 v126, 3, v128
	s_mov_b32 s40, s24
	v_writelane_b32 v226, s5, 4
	s_cbranch_vccz .LBB0_24
	s_ashr_i32 s25, s24, 31
	s_lshl_b64 s[4:5], s[24:25], 13
	s_waitcnt lgkmcnt(0)
	s_add_u32 s4, s8, s4
	v_lshlrev_b32_e32 v130, 4, v128
	s_addc_u32 s5, s9, s5
	v_or_b32_e32 v1, 0x1400, v130
	global_load_dwordx4 v[18:21], v130, s[4:5]
	global_load_dwordx4 v[74:77], v130, s[4:5] offset:1024
	global_load_dwordx4 v[14:17], v130, s[4:5] offset:2048
	global_load_dwordx4 v[2:5], v1, s[4:5]
	v_or_b32_e32 v34, 0x1000, v130
	global_load_dwordx4 v[6:9], v34, s[4:5]
	global_load_dwordx4 v[10:13], v130, s[4:5] offset:3072
	v_or_b32_e32 v35, 0x1800, v130
	v_or_b32_e32 v78, 0x1c00, v130
	global_load_dwordx4 v[118:121], v35, s[4:5]
	global_load_dwordx4 v[110:113], v78, s[4:5]
	s_lshl_b32 s3, s26, 4
	v_readlane_b32 s28, v226, 1
	s_sub_i32 s42, s28, s3
	s_ashr_i32 s43, s42, 31
	s_lshl_b64 s[4:5], s[42:43], 13
	s_add_u32 s4, s8, s4
	s_addc_u32 s5, s9, s5
	global_load_dwordx4 v[102:105], v130, s[4:5]
	global_load_dwordx4 v[114:117], v130, s[4:5] offset:1024
	global_load_dwordx4 v[106:109], v130, s[4:5] offset:2048
	v_add_u32_e32 v204, 0x1000, v130
	global_load_dwordx4 v[166:169], v130, s[34:35]
	global_load_dwordx4 v[170:173], v130, s[34:35] offset:1024
	global_load_dwordx4 v[174:177], v130, s[34:35] offset:2048
	global_load_dwordx4 v[178:181], v130, s[34:35] offset:3072
	global_load_dwordx4 v[182:185], v204, s[34:35]
	global_load_dwordx4 v[186:189], v204, s[34:35] offset:1024
	global_load_dwordx4 v[190:193], v204, s[34:35] offset:2048
	global_load_dwordx4 v[200:203], v204, s[34:35] offset:3072
	global_load_dwordx4 v[94:97], v1, s[4:5]
	global_load_dwordx4 v[98:101], v34, s[4:5]
	global_load_dwordx4 v[90:93], v35, s[4:5]
	global_load_dwordx4 v[62:65], v78, s[4:5]
	global_load_dwordx4 v[122:125], v130, s[4:5] offset:3072
	s_add_i32 s4, s42, s18
	s_ashr_i32 s5, s4, 31
	s_lshl_b64 s[40:41], s[4:5], 13
	s_mov_b32 s46, 0x358637bd
	s_add_u32 s44, s8, s40
	s_mov_b32 s40, 0x3a000000
	v_mov_b64_e32 v[132:133], s[46:47]
	s_mov_b32 s3, 0x800000
	v_readlane_b32 s29, v226, 2
	s_addc_u32 s45, s9, s41
	s_ashr_i32 s29, s28, 31
	s_lshl_b64 s[46:47], s[28:29], 13
	s_add_u32 s46, s8, s46
	s_addc_u32 s47, s9, s47
	v_mov_b32_e32 v131, 0
	s_movk_i32 s12, 0x1000
	s_waitcnt vmcnt(23)
	v_mov_b32_e32 v28, v19
	s_waitcnt vmcnt(22)
	v_mov_b32_e32 v29, v75
	s_waitcnt vmcnt(21)
	v_pk_mul_f32 v[30:31], v[16:17], v[16:17]
	v_pk_mul_f32 v[32:33], v[14:15], v[14:15]
	s_waitcnt vmcnt(20)
	v_pk_mul_f32 v[36:37], v[4:5], v[4:5]
	v_pk_mul_f32 v[38:39], v[2:3], v[2:3]
	v_mov_b32_e32 v42, v21
	v_mov_b32_e32 v43, v77
	v_mov_b32_e32 v26, v18
	v_mov_b32_e32 v27, v74
	v_mov_b32_e32 v40, v20
	v_mov_b32_e32 v41, v76
	v_pk_mov_b32 v[52:53], v[32:33], v[30:31] op_sel:[1,0]
	v_mov_b32_e32 v33, v31
	v_pk_mov_b32 v[30:31], v[38:39], v[36:37] op_sel:[1,0]
	v_mov_b32_e32 v39, v37
	v_pk_mul_f32 v[28:29], v[28:29], v[28:29]
	v_pk_mul_f32 v[36:37], v[42:43], v[42:43]
	v_pk_fma_f32 v[26:27], v[26:27], v[26:27], v[28:29]
	v_pk_fma_f32 v[28:29], v[40:41], v[40:41], v[36:37]
	s_waitcnt vmcnt(18)
	v_mul_f32_e32 v44, v11, v11
	v_mul_f32_e32 v46, v13, v13
	v_pk_add_f32 v[32:33], v[52:53], v[32:33]
	v_pk_add_f32 v[26:27], v[26:27], v[28:29]
	v_mul_f32_e32 v51, v8, v8
	v_mul_f32_e32 v54, v9, v9
	v_mul_f32_e32 v57, v7, v7
	v_mul_f32_e32 v58, v6, v6
	v_pk_fma_f32 v[42:43], v[10:11], v[10:11], v[44:45] op_sel_hi:[1,1,0]
	v_pk_fma_f32 v[44:45], v[12:13], v[12:13], v[46:47] op_sel_hi:[1,1,0]
	v_pk_add_f32 v[32:33], v[32:33], v[32:33] op_sel:[0,1] op_sel_hi:[1,0]
	v_pk_add_f32 v[26:27], v[26:27], v[26:27] op_sel:[0,1] op_sel_hi:[1,0]
	v_mov_b32_e32 v43, v51
	v_mov_b32_e32 v45, v54
	v_mov_b32_e32 v33, v57
	v_mov_b32_e32 v27, v58
	v_pk_add_f32 v[28:29], v[42:43], v[44:45]
	v_pk_add_f32 v[26:27], v[26:27], v[32:33]
	v_pk_add_f32 v[30:31], v[30:31], v[38:39]
	v_pk_add_f32 v[26:27], v[26:27], v[28:29]
	s_waitcnt vmcnt(16)
	v_mul_f32_e32 v59, v111, v111
	v_mul_f32_e32 v60, v110, v110
	v_pk_add_f32 v[30:31], v[30:31], v[30:31] op_sel:[0,1] op_sel_hi:[1,0]
	v_pk_add_f32 v[26:27], v[26:27], v[26:27] op_sel:[0,1] op_sel_hi:[1,0]
	v_mov_b32_e32 v31, v59
	v_mov_b32_e32 v27, v60
	v_mul_f32_e32 v48, v119, v119
	v_mul_f32_e32 v50, v121, v121
	s_waitcnt vmcnt(15)
	v_mov_b32_e32 v40, v103
	s_waitcnt vmcnt(14)
	v_mov_b32_e32 v41, v115
	v_pk_add_f32 v[26:27], v[26:27], v[30:31]
	v_mov_b32_e32 v30, v105
	v_mov_b32_e32 v31, v117
	v_mul_f32_e32 v55, v112, v112
	v_mul_f32_e32 v56, v113, v113
	v_pk_fma_f32 v[46:47], v[118:119], v[118:119], v[48:49] op_sel_hi:[1,1,0]
	v_pk_fma_f32 v[48:49], v[120:121], v[120:121], v[50:51] op_sel_hi:[1,1,0]
	v_mov_b32_e32 v38, v102
	v_mov_b32_e32 v39, v114
	v_mov_b32_e32 v42, v104
	v_pk_mul_f32 v[32:33], v[40:41], v[40:41]
	v_mov_b32_e32 v43, v116
	v_pk_mul_f32 v[30:31], v[30:31], v[30:31]
	v_mov_b32_e32 v47, v55
	v_mov_b32_e32 v49, v56
	v_pk_fma_f32 v[28:29], v[38:39], v[38:39], v[32:33]
	v_pk_fma_f32 v[30:31], v[42:43], v[42:43], v[30:31]
	v_pk_add_f32 v[36:37], v[46:47], v[48:49]
	v_pk_add_f32 v[28:29], v[28:29], v[30:31]
	s_waitcnt vmcnt(13)
	v_pk_mul_f32 v[30:31], v[108:109], v[108:109]
	v_pk_mul_f32 v[32:33], v[106:107], v[106:107]
	v_pk_add_f32 v[26:27], v[26:27], v[36:37]
	v_pk_mov_b32 v[36:37], v[32:33], v[30:31] op_sel:[1,0]
	v_mov_b32_e32 v33, v31
	v_pk_add_f32 v[30:31], v[36:37], v[32:33]
	v_pk_add_f32 v[28:29], v[28:29], v[28:29] op_sel:[0,1] op_sel_hi:[1,0]
	v_pk_add_f32 v[30:31], v[30:31], v[30:31] op_sel:[0,1] op_sel_hi:[1,0]
	s_waitcnt vmcnt(3)
	v_mov_b32_e32 v22, v166
	v_mov_b32_e32 v23, v167
	v_mov_b32_e32 v24, v168
	v_mov_b32_e32 v25, v169
	v_mul_f32_e32 v29, v98, v98
	v_mul_f32_e32 v31, v99, v99
	v_pk_add_f32 v[28:29], v[28:29], v[30:31]
	s_waitcnt vmcnt(0)
	v_mul_f32_e32 v30, v123, v123
	v_mul_f32_e32 v32, v125, v125
	v_pk_fma_f32 v[30:31], v[122:123], v[122:123], v[30:31] op_sel_hi:[1,1,0]
	v_pk_fma_f32 v[32:33], v[124:125], v[124:125], v[32:33] op_sel_hi:[1,1,0]
	v_mul_f32_e32 v31, v100, v100
	v_mul_f32_e32 v33, v101, v101
	v_pk_add_f32 v[30:31], v[30:31], v[32:33]
	v_pk_mul_f32 v[32:33], v[94:95], v[94:95]
	v_pk_add_f32 v[28:29], v[28:29], v[30:31]
	v_pk_mul_f32 v[30:31], v[96:97], v[96:97]
	v_pk_add_f32 v[28:29], v[28:29], v[28:29] op_sel:[0,1] op_sel_hi:[1,0]
	v_pk_mov_b32 v[36:37], v[32:33], v[30:31] op_sel:[1,0]
	v_mov_b32_e32 v33, v31
	v_pk_add_f32 v[30:31], v[36:37], v[32:33]
	v_mul_f32_e32 v29, v62, v62
	v_pk_add_f32 v[30:31], v[30:31], v[30:31] op_sel:[0,1] op_sel_hi:[1,0]
	v_mul_f32_e32 v32, v93, v93
	v_mul_f32_e32 v31, v63, v63
	v_pk_add_f32 v[28:29], v[28:29], v[30:31]
	v_mul_f32_e32 v30, v91, v91
	v_pk_fma_f32 v[30:31], v[90:91], v[90:91], v[30:31] op_sel_hi:[1,1,0]
	v_pk_fma_f32 v[32:33], v[92:93], v[92:93], v[32:33] op_sel_hi:[1,1,0]
	v_mul_f32_e32 v31, v64, v64
	v_mul_f32_e32 v33, v65, v65
	v_pk_add_f32 v[30:31], v[30:31], v[32:33]
	global_load_dwordx4 v[54:57], v130, s[44:45]
	v_pk_add_f32 v[28:29], v[28:29], v[30:31]
	v_mov_b32_e32 v31, v26
	v_mov_b32_e32 v30, v28
	v_mov_b32_e32 v26, v29
	v_pk_add_f32 v[26:27], v[30:31], v[26:27]
	v_mbcnt_hi_u32_b32 v30, -1, v165
	v_and_b32_e32 v28, 64, v30
	v_add_u32_e32 v31, 64, v28
	v_xor_b32_e32 v28, 1, v30
	v_cmp_lt_i32_e32 vcc, v28, v31
	s_nop 1
	v_cndmask_b32_e32 v28, v30, v28, vcc
	v_lshlrev_b32_e32 v127, 2, v28
	ds_bpermute_b32 v29, v127, v27
	ds_bpermute_b32 v28, v127, v26
	s_waitcnt lgkmcnt(0)
	v_pk_add_f32 v[26:27], v[26:27], v[28:29]
	v_xor_b32_e32 v28, 2, v30
	v_cmp_lt_i32_e32 vcc, v28, v31
	s_nop 1
	v_cndmask_b32_e32 v28, v30, v28, vcc
	v_lshlrev_b32_e32 v129, 2, v28
	ds_bpermute_b32 v29, v129, v27
	ds_bpermute_b32 v28, v129, v26
	s_waitcnt lgkmcnt(0)
	v_pk_add_f32 v[26:27], v[26:27], v[28:29]
	v_xor_b32_e32 v28, 4, v30
	v_cmp_lt_i32_e32 vcc, v28, v31
	s_nop 1
	v_cndmask_b32_e32 v28, v30, v28, vcc
	v_lshlrev_b32_e32 v137, 2, v28
	ds_bpermute_b32 v29, v137, v27
	ds_bpermute_b32 v28, v137, v26
	s_waitcnt lgkmcnt(0)
	v_pk_add_f32 v[26:27], v[26:27], v[28:29]
	v_xor_b32_e32 v28, 8, v30
	v_cmp_lt_i32_e32 vcc, v28, v31
	s_nop 1
	v_cndmask_b32_e32 v28, v30, v28, vcc
	v_lshlrev_b32_e32 v138, 2, v28
	ds_bpermute_b32 v29, v138, v27
	ds_bpermute_b32 v28, v138, v26
	s_waitcnt lgkmcnt(0)
	v_pk_add_f32 v[26:27], v[26:27], v[28:29]
	v_xor_b32_e32 v28, 16, v30
	v_cmp_lt_i32_e32 vcc, v28, v31
	s_nop 1
	v_cndmask_b32_e32 v28, v30, v28, vcc
	v_lshlrev_b32_e32 v139, 2, v28
	ds_bpermute_b32 v29, v139, v27
	ds_bpermute_b32 v28, v139, v26
	s_waitcnt lgkmcnt(0)
	v_pk_add_f32 v[26:27], v[26:27], v[28:29]
	v_xor_b32_e32 v28, 32, v30
	v_cmp_lt_i32_e32 vcc, v28, v31
	s_nop 1
	v_cndmask_b32_e32 v28, v30, v28, vcc
	v_lshlrev_b32_e32 v140, 2, v28
	ds_bpermute_b32 v29, v140, v27
	ds_bpermute_b32 v28, v140, v26
	s_waitcnt lgkmcnt(0)
	v_pk_add_f32 v[26:27], v[26:27], v[28:29]
	s_nop 0
	v_pk_fma_f32 v[134:135], v[26:27], s[40:41], v[132:133] op_sel_hi:[1,0,0]
	s_nop 0
	v_mul_f32_e32 v26, 0x4b800000, v135
	v_cmp_gt_f32_e32 vcc, s3, v135
	s_nop 1
	v_cndmask_b32_e32 v26, v135, v26, vcc
	v_rsq_f32_e32 v26, v26
	s_nop 0
	v_mul_f32_e32 v27, 0x45800000, v26
	v_cndmask_b32_e32 v136, v26, v27, vcc
	v_pk_mul_f32 v[18:19], v[18:19], v[136:137] op_sel_hi:[1,0]
	v_pk_mul_f32 v[20:21], v[20:21], v[136:137] op_sel_hi:[1,0]
	v_pk_mul_f32 v[144:145], v[22:23], v[18:19]
	v_pk_mul_f32 v[142:143], v[24:25], v[20:21]
	global_load_dwordx4 v[70:73], v34, s[44:45]
	global_load_dwordx4 v[30:33], v34, s[46:47]
	global_load_dwordx4 v[66:69], v1, s[44:45]
	global_load_dwordx4 v[26:29], v1, s[46:47]
	global_load_dwordx4 v[58:61], v35, s[44:45]
	global_load_dwordx4 v[22:25], v35, s[46:47]
	global_load_dwordx4 v[50:53], v78, s[44:45]
	global_load_dwordx4 v[18:21], v78, s[46:47]
	global_load_dwordx4 v[86:89], v130, s[44:45] offset:1024
	global_load_dwordx4 v[82:85], v130, s[44:45] offset:2048
	s_nop 0
	global_load_dwordx4 v[78:81], v130, s[44:45] offset:3072
	global_load_dwordx4 v[46:49], v130, s[46:47]
	global_load_dwordx4 v[42:45], v130, s[46:47] offset:1024
	global_load_dwordx4 v[38:41], v130, s[46:47] offset:2048
	global_load_dwordx4 v[34:37], v130, s[46:47] offset:3072
	s_lshl_b64 s[44:45], s[24:25], 12
	s_add_u32 s44, s36, s44
	s_addc_u32 s45, s37, s45
	v_cvt_pk_bf16_f32 v144, v144, v145
	v_cvt_pk_bf16_f32 v145, v142, v143
	global_store_dwordx2 v126, v[144:145], s[44:45]
	v_pk_mul_f32 v[74:75], v[74:75], v[136:137] op_sel_hi:[1,0]
	v_pk_mul_f32 v[76:77], v[76:77], v[136:137] op_sel_hi:[1,0]
	v_pk_mul_f32 v[14:15], v[14:15], v[136:137] op_sel_hi:[1,0]
	v_pk_mul_f32 v[16:17], v[16:17], v[136:137] op_sel_hi:[1,0]
	v_pk_mul_f32 v[10:11], v[10:11], v[136:137] op_sel_hi:[1,0]
	v_pk_mul_f32 v[12:13], v[12:13], v[136:137] op_sel_hi:[1,0]
	v_pk_mul_f32 v[6:7], v[6:7], v[136:137] op_sel_hi:[1,0]
	v_pk_mul_f32 v[8:9], v[8:9], v[136:137] op_sel_hi:[1,0]
	v_pk_mul_f32 v[2:3], v[2:3], v[136:137] op_sel_hi:[1,0]
	v_pk_mul_f32 v[4:5], v[4:5], v[136:137] op_sel_hi:[1,0]
	v_mul_f32_e32 v1, 0x4b800000, v134
	s_lshl_b64 s[42:43], s[42:43], 12
	s_add_u32 s42, s36, s42
	s_addc_u32 s43, s37, s43
	s_lshl_b64 s[4:5], s[4:5], 12
	s_add_u32 s4, s36, s4
	s_addc_u32 s5, s37, s5
	s_waitcnt vmcnt(1)
	v_mov_b32_e32 v142, v170
	v_mov_b32_e32 v143, v171
	v_mov_b32_e32 v144, v172
	v_mov_b32_e32 v145, v173
	v_pk_mul_f32 v[74:75], v[142:143], v[74:75]
	v_pk_mul_f32 v[76:77], v[144:145], v[76:77]
	v_cvt_pk_bf16_f32 v74, v74, v75
	s_nop 0
	v_cvt_pk_bf16_f32 v75, v76, v77
	global_store_dwordx2 v126, v[74:75], s[44:45] offset:512
	v_mov_b32_e32 v74, v174
	v_mov_b32_e32 v75, v175
	v_mov_b32_e32 v76, v176
	v_mov_b32_e32 v77, v177
	v_pk_mul_f32 v[14:15], v[14:15], v[74:75]
	v_pk_mul_f32 v[16:17], v[16:17], v[76:77]
	v_cvt_pk_bf16_f32 v14, v14, v15
	s_nop 0
	v_cvt_pk_bf16_f32 v15, v16, v17
	global_store_dwordx2 v126, v[14:15], s[44:45] offset:1024
	v_lshl_add_u64 v[14:15], s[34:35], 0, v[130:131]
	v_add_co_u32_e32 v14, vcc, s12, v14
	v_pk_mul_f32 v[16:17], v[66:67], v[66:67]
	s_nop 0
	v_addc_co_u32_e32 v15, vcc, 0, v15, vcc
	v_cmp_gt_f32_e32 vcc, s3, v134
	v_mov_b32_e32 v74, v178
	v_mov_b32_e32 v75, v179
	v_mov_b32_e32 v76, v180
	v_mov_b32_e32 v77, v181
	v_pk_mul_f32 v[10:11], v[10:11], v[74:75]
	v_pk_mul_f32 v[12:13], v[12:13], v[76:77]
	v_cvt_pk_bf16_f32 v10, v10, v11
	v_cndmask_b32_e32 v1, v134, v1, vcc
	v_cvt_pk_bf16_f32 v11, v12, v13
	global_store_dwordx2 v126, v[10:11], s[44:45] offset:1536
	v_rsq_f32_e32 v1, v1
	v_mov_b32_e32 v76, v55
	v_mov_b32_e32 v77, v87
	v_mov_b32_e32 v74, v54
	v_mov_b32_e32 v75, v86
	v_mov_b32_e32 v10, v182
	v_mov_b32_e32 v11, v183
	v_mov_b32_e32 v12, v184
	v_mov_b32_e32 v13, v185
	v_pk_mul_f32 v[6:7], v[6:7], v[10:11]
	v_pk_mul_f32 v[8:9], v[8:9], v[12:13]
	v_cvt_pk_bf16_f32 v6, v6, v7
	v_pk_mul_f32 v[12:13], v[68:69], v[68:69]
	v_cvt_pk_bf16_f32 v7, v8, v9
	global_store_dwordx2 v126, v[6:7], s[44:45] offset:2048
	v_mov_b32_e32 v6, v186
	v_mov_b32_e32 v7, v187
	v_mov_b32_e32 v8, v188
	v_mov_b32_e32 v9, v189
	v_pk_mul_f32 v[2:3], v[2:3], v[6:7]
	v_pk_mul_f32 v[4:5], v[4:5], v[8:9]
	v_cvt_pk_bf16_f32 v2, v2, v3
	v_pk_mul_f32 v[6:7], v[118:119], v[136:137] op_sel_hi:[1,0]
	v_cvt_pk_bf16_f32 v3, v4, v5
	global_store_dwordx2 v126, v[2:3], s[44:45] offset:2560
	v_pk_mul_f32 v[8:9], v[120:121], v[136:137] op_sel_hi:[1,0]
	v_mul_f32_e32 v118, v31, v31
	v_mul_f32_e32 v119, v30, v30
	v_mul_f32_e32 v120, v19, v19
	v_mul_f32_e32 v121, v18, v18
	v_mov_b32_e32 v2, v190
	v_mov_b32_e32 v3, v191
	v_mov_b32_e32 v4, v192
	v_mov_b32_e32 v5, v193
	v_pk_mul_f32 v[2:3], v[6:7], v[2:3]
	v_pk_mul_f32 v[4:5], v[8:9], v[4:5]
	v_cvt_pk_bf16_f32 v2, v2, v3
	v_pk_mul_f32 v[6:7], v[110:111], v[136:137] op_sel_hi:[1,0]
	v_cvt_pk_bf16_f32 v3, v4, v5
	global_store_dwordx2 v126, v[2:3], s[44:45] offset:3072
	v_pk_mul_f32 v[8:9], v[112:113], v[136:137] op_sel_hi:[1,0]
	v_mul_f32_e32 v111, v70, v70
	v_mul_f32_e32 v110, v25, v25
	v_mov_b32_e32 v2, v200
	v_mov_b32_e32 v3, v201
	v_mov_b32_e32 v4, v202
	v_mov_b32_e32 v5, v203
	v_pk_mul_f32 v[2:3], v[6:7], v[2:3]
	v_pk_mul_f32 v[4:5], v[8:9], v[4:5]
	v_cvt_pk_bf16_f32 v2, v2, v3
	v_mul_f32_e32 v6, 0x45800000, v1
	v_cvt_pk_bf16_f32 v3, v4, v5
	global_store_dwordx2 v126, v[2:3], s[44:45] offset:3584
	v_cndmask_b32_e32 v6, v1, v6, vcc
	v_pk_mul_f32 v[8:9], v[102:103], v[6:7] op_sel_hi:[1,0]
	v_pk_mul_f32 v[10:11], v[104:105], v[6:7] op_sel_hi:[1,0]
	v_mul_f32_e32 v1, v72, v72
	v_mul_f32_e32 v104, v53, v53
	v_mul_f32_e32 v105, v71, v71
	v_mov_b32_e32 v2, v166
	v_mov_b32_e32 v3, v167
	v_mov_b32_e32 v4, v168
	v_mov_b32_e32 v5, v169
	v_pk_mul_f32 v[2:3], v[8:9], v[2:3]
	v_pk_mul_f32 v[4:5], v[10:11], v[4:5]
	v_cvt_pk_bf16_f32 v2, v2, v3
	v_pk_mul_f32 v[8:9], v[114:115], v[6:7] op_sel_hi:[1,0]
	v_cvt_pk_bf16_f32 v3, v4, v5
	global_store_dwordx2 v126, v[2:3], s[42:43]
	v_pk_mul_f32 v[10:11], v[116:117], v[6:7] op_sel_hi:[1,0]
	v_mul_f32_e32 v114, v51, v51
	v_mul_f32_e32 v115, v50, v50
	v_mul_f32_e32 v116, v20, v20
	v_mul_f32_e32 v117, v21, v21
	v_mov_b32_e32 v2, v170
	v_mov_b32_e32 v3, v171
	v_mov_b32_e32 v4, v172
	v_mov_b32_e32 v5, v173
	v_pk_mul_f32 v[2:3], v[8:9], v[2:3]
	v_pk_mul_f32 v[4:5], v[10:11], v[4:5]
	v_cvt_pk_bf16_f32 v2, v2, v3
	v_pk_mul_f32 v[8:9], v[106:107], v[6:7] op_sel_hi:[1,0]
	v_cvt_pk_bf16_f32 v3, v4, v5
	global_store_dwordx2 v126, v[2:3], s[42:43] offset:512
	v_pk_mul_f32 v[10:11], v[108:109], v[6:7] op_sel_hi:[1,0]
	v_mul_f32_e32 v106, v37, v37
	v_mul_f32_e32 v108, v23, v23
	v_mov_b32_e32 v2, v174
	v_mov_b32_e32 v3, v175
	v_mov_b32_e32 v4, v176
	v_mov_b32_e32 v5, v177
	v_pk_mul_f32 v[2:3], v[8:9], v[2:3]
	v_pk_mul_f32 v[4:5], v[10:11], v[4:5]
	v_cvt_pk_bf16_f32 v2, v2, v3
	v_pk_mul_f32 v[8:9], v[122:123], v[6:7] op_sel_hi:[1,0]
	v_cvt_pk_bf16_f32 v3, v4, v5
	global_store_dwordx2 v126, v[2:3], s[42:43] offset:1024
	v_pk_mul_f32 v[10:11], v[124:125], v[6:7] op_sel_hi:[1,0]
	v_mov_b32_e32 v2, v178
	v_mov_b32_e32 v3, v179
	v_mov_b32_e32 v4, v180
	v_mov_b32_e32 v5, v181
	v_pk_mul_f32 v[2:3], v[8:9], v[2:3]
	v_pk_mul_f32 v[4:5], v[10:11], v[4:5]
	v_cvt_pk_bf16_f32 v2, v2, v3
	v_pk_mul_f32 v[8:9], v[98:99], v[6:7] op_sel_hi:[1,0]
	v_cvt_pk_bf16_f32 v3, v4, v5
	global_store_dwordx2 v126, v[2:3], s[42:43] offset:1536
	v_pk_mul_f32 v[10:11], v[100:101], v[6:7] op_sel_hi:[1,0]
	v_mul_f32_e32 v98, v79, v79
	v_mul_f32_e32 v100, v81, v81
	v_mul_f32_e32 v101, v52, v52
	v_mov_b32_e32 v2, v182
	v_mov_b32_e32 v3, v183
	v_mov_b32_e32 v4, v184
	v_mov_b32_e32 v5, v185
	v_pk_mul_f32 v[2:3], v[8:9], v[2:3]
	v_pk_mul_f32 v[4:5], v[10:11], v[4:5]
	v_cvt_pk_bf16_f32 v2, v2, v3
	v_pk_mul_f32 v[8:9], v[94:95], v[6:7] op_sel_hi:[1,0]
	v_cvt_pk_bf16_f32 v3, v4, v5
	global_store_dwordx2 v126, v[2:3], s[42:43] offset:2048
	v_pk_mul_f32 v[10:11], v[96:97], v[6:7] op_sel_hi:[1,0]
	v_mul_f32_e32 v7, v73, v73
	v_pk_mul_f32 v[90:91], v[90:91], v[6:7] op_sel_hi:[1,0]
	v_pk_mul_f32 v[92:93], v[92:93], v[6:7] op_sel_hi:[1,0]
	v_mov_b32_e32 v96, v57
	v_mov_b32_e32 v97, v89
	v_mov_b32_e32 v94, v56
	v_mov_b32_e32 v95, v88
	v_mov_b32_e32 v2, v186
	v_mov_b32_e32 v3, v187
	v_mov_b32_e32 v4, v188
	v_mov_b32_e32 v5, v189
	v_pk_mul_f32 v[2:3], v[8:9], v[2:3]
	v_pk_mul_f32 v[4:5], v[10:11], v[4:5]
	v_cvt_pk_bf16_f32 v2, v2, v3
	v_pk_mul_f32 v[8:9], v[84:85], v[84:85]
	v_cvt_pk_bf16_f32 v3, v4, v5
	global_store_dwordx2 v126, v[2:3], s[42:43] offset:2560
	v_pk_mul_f32 v[10:11], v[82:83], v[82:83]
	v_mov_b32_e32 v2, v190
	v_mov_b32_e32 v3, v191
	v_mov_b32_e32 v4, v192
	v_mov_b32_e32 v5, v193
	v_pk_mul_f32 v[2:3], v[90:91], v[2:3]
	v_pk_mul_f32 v[4:5], v[92:93], v[4:5]
	v_cvt_pk_bf16_f32 v2, v2, v3
	v_mul_f32_e32 v90, v59, v59
	v_cvt_pk_bf16_f32 v3, v4, v5
	global_store_dwordx2 v126, v[2:3], s[42:43] offset:3072
	v_mul_f32_e32 v92, v61, v61
	v_pk_mov_b32 v[102:103], v[10:11], v[8:9] op_sel:[1,0]
	v_mov_b32_e32 v11, v9
	v_pk_mov_b32 v[8:9], v[16:17], v[12:13] op_sel:[1,0]
	v_mov_b32_e32 v17, v13
	v_pk_mul_f32 v[12:13], v[76:77], v[76:77]
	v_pk_mul_f32 v[76:77], v[96:97], v[96:97]
	v_pk_fma_f32 v[96:97], v[78:79], v[78:79], v[98:99] op_sel_hi:[1,1,0]
	v_pk_fma_f32 v[98:99], v[80:81], v[80:81], v[100:101] op_sel_hi:[1,1,0]
	v_pk_fma_f32 v[90:91], v[58:59], v[58:59], v[90:91] op_sel_hi:[1,1,0]
	v_pk_fma_f32 v[92:93], v[60:61], v[60:61], v[92:93] op_sel_hi:[1,1,0]
	v_pk_fma_f32 v[12:13], v[74:75], v[74:75], v[12:13]
	v_pk_fma_f32 v[74:75], v[94:95], v[94:95], v[76:77]
	v_pk_add_f32 v[10:11], v[102:103], v[10:11]
	v_mov_b32_e32 v97, v1
	v_mov_b32_e32 v99, v7
	v_mov_b32_e32 v91, v101
	v_mov_b32_e32 v93, v104
	v_pk_add_f32 v[8:9], v[8:9], v[16:17]
	v_pk_add_f32 v[12:13], v[12:13], v[74:75]
	v_pk_add_f32 v[16:17], v[96:97], v[98:99]
	v_pk_add_f32 v[74:75], v[90:91], v[92:93]
	v_pk_mul_f32 v[76:77], v[40:41], v[40:41]
	v_pk_mul_f32 v[90:91], v[38:39], v[38:39]
	v_pk_mul_f32 v[92:93], v[28:29], v[28:29]
	v_pk_mul_f32 v[94:95], v[26:27], v[26:27]
	v_mov_b32_e32 v98, v47
	v_mov_b32_e32 v99, v43
	v_mov_b32_e32 v102, v49
	v_mov_b32_e32 v103, v45
	v_pk_add_f32 v[10:11], v[10:11], v[10:11] op_sel:[0,1] op_sel_hi:[1,0]
	v_mul_f32_e32 v104, v35, v35
	v_mul_f32_e32 v7, v33, v33
	v_pk_mov_b32 v[112:113], v[90:91], v[76:77] op_sel:[1,0]
	v_mov_b32_e32 v91, v77
	v_pk_mov_b32 v[76:77], v[94:95], v[92:93] op_sel:[1,0]
	v_mov_b32_e32 v95, v93
	v_pk_mul_f32 v[92:93], v[98:99], v[98:99]
	v_pk_mul_f32 v[98:99], v[102:103], v[102:103]
	v_mov_b32_e32 v11, v105
	v_pk_fma_f32 v[102:103], v[34:35], v[34:35], v[104:105] op_sel_hi:[1,1,0]
	v_pk_fma_f32 v[104:105], v[36:37], v[36:37], v[106:107] op_sel_hi:[1,1,0]
	v_pk_mul_f32 v[62:63], v[62:63], v[6:7] op_sel_hi:[1,0]
	v_mov_b32_e32 v105, v7
	v_pk_mul_f32 v[6:7], v[64:65], v[6:7] op_sel_hi:[1,0]
	v_mov_b32_e32 v96, v46
	v_mov_b32_e32 v97, v42
	v_mov_b32_e32 v100, v48
	v_mov_b32_e32 v101, v44
	v_pk_add_f32 v[12:13], v[12:13], v[12:13] op_sel:[0,1] op_sel_hi:[1,0]
	v_pk_fma_f32 v[92:93], v[96:97], v[96:97], v[92:93]
	v_pk_fma_f32 v[96:97], v[100:101], v[100:101], v[98:99]
	v_mov_b32_e32 v13, v111
	v_pk_add_f32 v[90:91], v[112:113], v[90:91]
	v_mul_f32_e32 v1, v32, v32
	v_pk_add_f32 v[64:65], v[90:91], v[90:91] op_sel:[0,1] op_sel_hi:[1,0]
	v_pk_add_f32 v[8:9], v[8:9], v[8:9] op_sel:[0,1] op_sel_hi:[1,0]
	v_mov_b32_e32 v103, v1
	v_mov_b32_e32 v65, v118
	v_mov_b32_e32 v9, v114
	v_pk_add_f32 v[76:77], v[76:77], v[94:95]
	v_pk_fma_f32 v[106:107], v[22:23], v[22:23], v[108:109] op_sel_hi:[1,1,0]
	v_pk_fma_f32 v[108:109], v[24:25], v[24:25], v[110:111] op_sel_hi:[1,1,0]
	v_pk_add_f32 v[76:77], v[76:77], v[76:77] op_sel:[0,1] op_sel_hi:[1,0]
	v_mov_b32_e32 v107, v116
	v_mov_b32_e32 v109, v117
	v_mov_b32_e32 v77, v120
	v_mov_b32_e32 v2, v200
	v_mov_b32_e32 v3, v201
	v_mov_b32_e32 v4, v202
	v_mov_b32_e32 v5, v203
	v_pk_mul_f32 v[2:3], v[62:63], v[2:3]
	v_pk_mul_f32 v[4:5], v[6:7], v[4:5]
	v_cvt_pk_bf16_f32 v2, v2, v3
	v_pk_add_f32 v[6:7], v[12:13], v[10:11]
	v_cvt_pk_bf16_f32 v3, v4, v5
	global_store_dwordx2 v126, v[2:3], s[42:43] offset:3584
	v_pk_add_f32 v[10:11], v[92:93], v[96:97]
	v_pk_add_f32 v[6:7], v[6:7], v[16:17]
	v_pk_add_f32 v[10:11], v[10:11], v[10:11] op_sel:[0,1] op_sel_hi:[1,0]
	v_pk_add_f32 v[6:7], v[6:7], v[6:7] op_sel:[0,1] op_sel_hi:[1,0]
	v_mov_b32_e32 v11, v119
	v_pk_add_f32 v[12:13], v[102:103], v[104:105]
	v_pk_add_f32 v[10:11], v[10:11], v[64:65]
	v_mov_b32_e32 v7, v115
	v_pk_add_f32 v[6:7], v[6:7], v[8:9]
	v_pk_add_f32 v[8:9], v[10:11], v[12:13]
	v_pk_add_f32 v[62:63], v[106:107], v[108:109]
	v_pk_add_f32 v[8:9], v[8:9], v[8:9] op_sel:[0,1] op_sel_hi:[1,0]
	v_pk_add_f32 v[6:7], v[6:7], v[74:75]
	v_mov_b32_e32 v9, v121
	v_pk_add_f32 v[8:9], v[8:9], v[76:77]
	v_mov_b32_e32 v11, v6
	v_pk_add_f32 v[8:9], v[8:9], v[62:63]
	s_nop 0
	v_mov_b32_e32 v10, v8
	v_mov_b32_e32 v6, v9
	v_pk_add_f32 v[6:7], v[10:11], v[6:7]
	ds_bpermute_b32 v9, v127, v7
	ds_bpermute_b32 v8, v127, v6
	s_waitcnt lgkmcnt(0)
	v_pk_add_f32 v[6:7], v[6:7], v[8:9]
	ds_bpermute_b32 v9, v129, v7
	ds_bpermute_b32 v8, v129, v6
	s_waitcnt lgkmcnt(0)
	v_pk_add_f32 v[6:7], v[6:7], v[8:9]
	ds_bpermute_b32 v9, v137, v7
	ds_bpermute_b32 v8, v137, v6
	s_waitcnt lgkmcnt(0)
	v_pk_add_f32 v[6:7], v[6:7], v[8:9]
	ds_bpermute_b32 v9, v138, v7
	ds_bpermute_b32 v8, v138, v6
	s_waitcnt lgkmcnt(0)
	v_pk_add_f32 v[6:7], v[6:7], v[8:9]
	ds_bpermute_b32 v9, v139, v7
	ds_bpermute_b32 v8, v139, v6
	s_waitcnt lgkmcnt(0)
	v_pk_add_f32 v[6:7], v[6:7], v[8:9]
	ds_bpermute_b32 v9, v140, v7
	ds_bpermute_b32 v8, v140, v6
	s_waitcnt lgkmcnt(0)
	v_pk_add_f32 v[6:7], v[6:7], v[8:9]
	s_nop 0
	v_pk_fma_f32 v[6:7], v[6:7], s[40:41], v[132:133] op_sel_hi:[1,0,0]
	s_nop 0
	v_mul_f32_e32 v1, 0x4b800000, v7
	v_cmp_gt_f32_e32 vcc, s3, v7
	s_nop 1
	v_cndmask_b32_e32 v1, v7, v1, vcc
	v_rsq_f32_e32 v1, v1
	s_nop 0
	v_mul_f32_e32 v7, 0x45800000, v1
	v_cndmask_b32_e32 v8, v1, v7, vcc
	v_pk_mul_f32 v[10:11], v[54:55], v[8:9] op_sel_hi:[1,0]
	v_pk_mul_f32 v[12:13], v[56:57], v[8:9] op_sel_hi:[1,0]
	v_mul_f32_e32 v1, 0x4b800000, v6
	v_mov_b32_e32 v2, v166
	v_mov_b32_e32 v3, v167
	v_mov_b32_e32 v4, v168
	v_mov_b32_e32 v5, v169
	v_pk_mul_f32 v[2:3], v[10:11], v[2:3]
	v_pk_mul_f32 v[4:5], v[12:13], v[4:5]
	v_cvt_pk_bf16_f32 v2, v2, v3
	v_pk_mul_f32 v[10:11], v[86:87], v[8:9] op_sel_hi:[1,0]
	v_cvt_pk_bf16_f32 v3, v4, v5
	global_store_dwordx2 v126, v[2:3], s[4:5]
	v_pk_mul_f32 v[12:13], v[88:89], v[8:9] op_sel_hi:[1,0]
	v_cmp_gt_f32_e32 vcc, s3, v6
	v_mov_b32_e32 v2, v170
	v_mov_b32_e32 v3, v171
	v_mov_b32_e32 v4, v172
	v_mov_b32_e32 v5, v173
	v_pk_mul_f32 v[2:3], v[10:11], v[2:3]
	v_pk_mul_f32 v[4:5], v[12:13], v[4:5]
	v_cvt_pk_bf16_f32 v2, v2, v3
	v_pk_mul_f32 v[10:11], v[82:83], v[8:9] op_sel_hi:[1,0]
	v_cvt_pk_bf16_f32 v3, v4, v5
	global_store_dwordx2 v126, v[2:3], s[4:5] offset:512
	v_pk_mul_f32 v[12:13], v[84:85], v[8:9] op_sel_hi:[1,0]
	v_cndmask_b32_e32 v1, v6, v1, vcc
	v_rsq_f32_e32 v1, v1
	v_mov_b32_e32 v2, v174
	v_mov_b32_e32 v3, v175
	v_mov_b32_e32 v4, v176
	v_mov_b32_e32 v5, v177
	v_pk_mul_f32 v[2:3], v[10:11], v[2:3]
	v_pk_mul_f32 v[4:5], v[12:13], v[4:5]
	v_cvt_pk_bf16_f32 v2, v2, v3
	v_pk_mul_f32 v[10:11], v[78:79], v[8:9] op_sel_hi:[1,0]
	v_cvt_pk_bf16_f32 v3, v4, v5
	global_store_dwordx2 v126, v[2:3], s[4:5] offset:1024
	v_pk_mul_f32 v[12:13], v[80:81], v[8:9] op_sel_hi:[1,0]
	v_mul_f32_e32 v6, 0x45800000, v1
	v_cndmask_b32_e32 v6, v1, v6, vcc
	v_mov_b32_e32 v2, v178
	v_mov_b32_e32 v3, v179
	v_mov_b32_e32 v4, v180
	v_mov_b32_e32 v5, v181
	v_pk_mul_f32 v[2:3], v[10:11], v[2:3]
	v_pk_mul_f32 v[4:5], v[12:13], v[4:5]
	v_cvt_pk_bf16_f32 v2, v2, v3
	v_pk_mul_f32 v[10:11], v[70:71], v[8:9] op_sel_hi:[1,0]
	v_cvt_pk_bf16_f32 v3, v4, v5
	global_store_dwordx2 v126, v[2:3], s[4:5] offset:1536
	v_pk_mul_f32 v[12:13], v[72:73], v[8:9] op_sel_hi:[1,0]
	v_mov_b32_e32 v2, v182
	v_mov_b32_e32 v3, v183
	v_mov_b32_e32 v4, v184
	v_mov_b32_e32 v5, v185
	v_pk_mul_f32 v[2:3], v[10:11], v[2:3]
	v_pk_mul_f32 v[4:5], v[12:13], v[4:5]
	v_cvt_pk_bf16_f32 v2, v2, v3
	v_pk_mul_f32 v[10:11], v[66:67], v[8:9] op_sel_hi:[1,0]
	v_cvt_pk_bf16_f32 v3, v4, v5
	global_store_dwordx2 v126, v[2:3], s[4:5] offset:2048
	v_pk_mul_f32 v[12:13], v[68:69], v[8:9] op_sel_hi:[1,0]
	v_mov_b32_e32 v2, v186
	v_mov_b32_e32 v3, v187
	v_mov_b32_e32 v4, v188
	v_mov_b32_e32 v5, v189
	v_pk_mul_f32 v[2:3], v[10:11], v[2:3]
	v_pk_mul_f32 v[4:5], v[12:13], v[4:5]
	v_cvt_pk_bf16_f32 v2, v2, v3
	v_pk_mul_f32 v[10:11], v[58:59], v[8:9] op_sel_hi:[1,0]
	v_cvt_pk_bf16_f32 v3, v4, v5
	global_store_dwordx2 v126, v[2:3], s[4:5] offset:2560
	v_pk_mul_f32 v[12:13], v[60:61], v[8:9] op_sel_hi:[1,0]
	v_mov_b32_e32 v2, v190
	v_mov_b32_e32 v3, v191
	v_mov_b32_e32 v4, v192
	v_mov_b32_e32 v5, v193
	v_pk_mul_f32 v[2:3], v[10:11], v[2:3]
	v_pk_mul_f32 v[4:5], v[12:13], v[4:5]
	v_cvt_pk_bf16_f32 v2, v2, v3
	v_pk_mul_f32 v[10:11], v[50:51], v[8:9] op_sel_hi:[1,0]
	v_cvt_pk_bf16_f32 v3, v4, v5
	global_store_dwordx2 v126, v[2:3], s[4:5] offset:3072
	v_pk_mul_f32 v[8:9], v[52:53], v[8:9] op_sel_hi:[1,0]
	v_mov_b32_e32 v2, v200
	v_mov_b32_e32 v3, v201
	v_mov_b32_e32 v4, v202
	v_mov_b32_e32 v5, v203
	v_pk_mul_f32 v[2:3], v[10:11], v[2:3]
	v_pk_mul_f32 v[4:5], v[8:9], v[4:5]
	v_cvt_pk_bf16_f32 v2, v2, v3
	v_pk_mul_f32 v[8:9], v[46:47], v[6:7] op_sel_hi:[1,0]
	v_cvt_pk_bf16_f32 v3, v4, v5
	global_store_dwordx2 v126, v[2:3], s[4:5] offset:3584
	s_mov_b32 s4, s28
	v_writelane_b32 v226, s4, 1
	v_pk_mul_f32 v[10:11], v[48:49], v[6:7] op_sel_hi:[1,0]
	v_mov_b32_e32 v2, v166
	v_mov_b32_e32 v3, v167
	v_mov_b32_e32 v4, v168
	v_mov_b32_e32 v5, v169
	v_pk_mul_f32 v[2:3], v[8:9], v[2:3]
	v_writelane_b32 v226, s5, 2
	s_lshl_b64 s[4:5], s[28:29], 12
	s_add_u32 s4, s36, s4
	s_addc_u32 s5, s37, s5
	v_pk_mul_f32 v[4:5], v[10:11], v[4:5]
	v_cvt_pk_bf16_f32 v2, v2, v3
	v_pk_mul_f32 v[8:9], v[42:43], v[6:7] op_sel_hi:[1,0]
	v_cvt_pk_bf16_f32 v3, v4, v5
	global_store_dwordx2 v126, v[2:3], s[4:5]
	v_pk_mul_f32 v[10:11], v[44:45], v[6:7] op_sel_hi:[1,0]
	s_lshl_b32 s3, s26, 5
	s_add_i32 s40, s24, s3
	v_mov_b32_e32 v2, v170
	v_mov_b32_e32 v3, v171
	v_mov_b32_e32 v4, v172
	v_mov_b32_e32 v5, v173
	v_pk_mul_f32 v[2:3], v[8:9], v[2:3]
	v_pk_mul_f32 v[4:5], v[10:11], v[4:5]
	v_cvt_pk_bf16_f32 v2, v2, v3
	v_pk_mul_f32 v[8:9], v[38:39], v[6:7] op_sel_hi:[1,0]
	v_cvt_pk_bf16_f32 v3, v4, v5
	global_store_dwordx2 v126, v[2:3], s[4:5] offset:512
	v_pk_mul_f32 v[10:11], v[40:41], v[6:7] op_sel_hi:[1,0]
	v_mov_b32_e32 v2, v174
	v_mov_b32_e32 v3, v175
	v_mov_b32_e32 v4, v176
	v_mov_b32_e32 v5, v177
	v_pk_mul_f32 v[2:3], v[8:9], v[2:3]
	v_pk_mul_f32 v[4:5], v[10:11], v[4:5]
	v_cvt_pk_bf16_f32 v2, v2, v3
	v_pk_mul_f32 v[8:9], v[34:35], v[6:7] op_sel_hi:[1,0]
	v_cvt_pk_bf16_f32 v3, v4, v5
	global_store_dwordx2 v126, v[2:3], s[4:5] offset:1024
	v_pk_mul_f32 v[10:11], v[36:37], v[6:7] op_sel_hi:[1,0]
	v_mov_b32_e32 v2, v178
	v_mov_b32_e32 v3, v179
	v_mov_b32_e32 v4, v180
	v_mov_b32_e32 v5, v181
	v_pk_mul_f32 v[2:3], v[8:9], v[2:3]
	v_pk_mul_f32 v[4:5], v[10:11], v[4:5]
	v_cvt_pk_bf16_f32 v2, v2, v3
	v_pk_mul_f32 v[8:9], v[30:31], v[6:7] op_sel_hi:[1,0]
	v_cvt_pk_bf16_f32 v3, v4, v5
	global_store_dwordx2 v126, v[2:3], s[4:5] offset:1536
	v_pk_mul_f32 v[10:11], v[32:33], v[6:7] op_sel_hi:[1,0]
	v_mov_b32_e32 v2, v182
	v_mov_b32_e32 v3, v183
	v_mov_b32_e32 v4, v184
	v_mov_b32_e32 v5, v185
	v_pk_mul_f32 v[2:3], v[8:9], v[2:3]
	v_pk_mul_f32 v[4:5], v[10:11], v[4:5]
	v_cvt_pk_bf16_f32 v2, v2, v3
	v_pk_mul_f32 v[8:9], v[26:27], v[6:7] op_sel_hi:[1,0]
	v_cvt_pk_bf16_f32 v3, v4, v5
	global_store_dwordx2 v126, v[2:3], s[4:5] offset:2048
	v_pk_mul_f32 v[10:11], v[28:29], v[6:7] op_sel_hi:[1,0]
	v_mov_b32_e32 v2, v186
	v_mov_b32_e32 v3, v187
	v_mov_b32_e32 v4, v188
	v_mov_b32_e32 v5, v189
	v_pk_mul_f32 v[2:3], v[8:9], v[2:3]
	v_pk_mul_f32 v[4:5], v[10:11], v[4:5]
	v_cvt_pk_bf16_f32 v2, v2, v3
	v_pk_mul_f32 v[8:9], v[22:23], v[6:7] op_sel_hi:[1,0]
	v_cvt_pk_bf16_f32 v3, v4, v5
	global_store_dwordx2 v126, v[2:3], s[4:5] offset:2560
	v_pk_mul_f32 v[10:11], v[24:25], v[6:7] op_sel_hi:[1,0]
	v_mov_b32_e32 v2, v190
	v_mov_b32_e32 v3, v191
	v_mov_b32_e32 v4, v192
	v_mov_b32_e32 v5, v193
	v_pk_mul_f32 v[2:3], v[8:9], v[2:3]
	v_pk_mul_f32 v[4:5], v[10:11], v[4:5]
	v_cvt_pk_bf16_f32 v2, v2, v3
	v_pk_mul_f32 v[8:9], v[18:19], v[6:7] op_sel_hi:[1,0]
	v_cvt_pk_bf16_f32 v3, v4, v5
	global_store_dwordx2 v126, v[2:3], s[4:5] offset:3072
	v_pk_mul_f32 v[6:7], v[20:21], v[6:7] op_sel_hi:[1,0]
	v_mov_b32_e32 v2, v200
	v_mov_b32_e32 v3, v201
	v_mov_b32_e32 v4, v202
	v_mov_b32_e32 v5, v203
	v_pk_mul_f32 v[2:3], v[8:9], v[2:3]
	v_pk_mul_f32 v[4:5], v[6:7], v[4:5]
	v_cvt_pk_bf16_f32 v2, v2, v3
	s_nop 0
	v_cvt_pk_bf16_f32 v3, v4, v5
	global_store_dwordx2 v126, v[2:3], s[4:5] offset:3584

.LBB0_630:
	s_or_b64 exec, exec, s[4:5]
	s_waitcnt lgkmcnt(0)
	v_mov_b32_e32 v0, v164
	s_barrier
	s_add_u32 s8, s34, 0x20200000
	s_mov_b32 s4, 16
	s_addc_u32 s9, s35, 0
	s_ashr_i32 s5, s4, 31
	s_lshl_b64 s[4:5], s[4:5], 3
	s_add_u32 s4, s0, s4
	s_addc_u32 s5, s1, s5
	s_load_dwordx2 s[14:15], s[4:5], 0x0
	s_add_u32 s6, s34, 0x9800000
	s_mov_b32 s4, 1
	s_addc_u32 s7, s35, 0
	s_ashr_i32 s5, s4, 31
	s_lshl_b64 s[4:5], s[4:5], 3
	s_add_u32 s4, s0, s4
	s_addc_u32 s5, s1, s5
	s_load_dwordx2 s[10:11], s[4:5], 0x0
	v_readlane_b32 s12, v226, 3
	v_readlane_b32 s13, v226, 4
	v_and_b32_e32 v45, 63, v0
	s_andn2_b64 vcc, exec, s[12:13]
	v_cndmask_b32_e64 v0, 0, 1, s[12:13]
	v_cmp_ne_u32_e64 s[4:5], 1, v0
	v_lshlrev_b32_e32 v40, 4, v45
	v_lshlrev_b32_e32 v44, 5, v45
	s_mov_b32 s52, s24
	s_cbranch_vccnz .LBB0_632
	v_mov_b32_e32 v41, 0
	s_ashr_i32 s25, s24, 31
	v_lshl_add_u64 v[0:1], s[8:9], 0, v[40:41]
	s_lshl_b64 s[50:51], s[24:25], 12
	v_lshl_add_u64 v[2:3], v[0:1], 0, s[50:51]
	s_add_i32 s12, s24, s18
	flat_load_dwordx4 v[28:31], v[2:3] offset:1024
	flat_load_dwordx4 v[32:35], v[2:3] offset:2048
	flat_load_dwordx4 v[24:27], v[2:3] offset:3072
	flat_load_dwordx4 v[36:39], v[2:3]
	s_ashr_i32 s13, s12, 31
	s_lshl_b64 s[46:47], s[12:13], 12
	v_lshl_add_u64 v[2:3], v[0:1], 0, s[46:47]
	flat_load_dwordx4 v[46:49], v[2:3]
	flat_load_dwordx4 v[50:53], v[2:3] offset:1024
	flat_load_dwordx4 v[108:111], v[2:3] offset:2048
	flat_load_dwordx4 v[12:15], v[2:3] offset:3072
	v_readlane_b32 s28, v226, 1
	v_readlane_b32 s29, v226, 2
	s_add_i32 s40, s12, s18
	s_mov_b32 s12, s28
	s_ashr_i32 s29, s28, 31
	v_writelane_b32 v226, s12, 1
	s_ashr_i32 s41, s40, 31
	s_lshl_b64 s[44:45], s[40:41], 12
	v_writelane_b32 v226, s13, 2
	s_lshl_b64 s[12:13], s[28:29], 12
	v_lshl_add_u64 v[4:5], v[0:1], 0, s[12:13]
	v_lshl_add_u64 v[0:1], v[0:1], 0, s[44:45]
	flat_load_dwordx4 v[20:23], v[0:1]
	flat_load_dwordx4 v[16:19], v[0:1] offset:1024
	flat_load_dwordx4 v[8:11], v[0:1] offset:2048
	s_nop 0
	flat_load_dwordx4 v[0:3], v[0:1] offset:3072
	s_waitcnt lgkmcnt(0)
	v_add_u32_e32 v204, 0x1000, v44
	global_load_dwordx4 v[166:169], v44, s[14:15]
	global_load_dwordx4 v[170:173], v44, s[14:15] offset:16
	global_load_dwordx4 v[174:177], v44, s[14:15] offset:2048
	global_load_dwordx4 v[178:181], v44, s[14:15] offset:2064
	global_load_dwordx4 v[182:185], v204, s[14:15]
	global_load_dwordx4 v[186:189], v204, s[14:15] offset:16
	global_load_dwordx4 v[190:193], v204, s[14:15] offset:2048
	global_load_dwordx4 v[200:203], v204, s[14:15] offset:2064
	s_mov_b32 s40, 0x358637bd
	s_mov_b32 s48, 0x3a000000
	s_mov_b32 s3, 0x800000
	v_mov_b32_e32 v105, v41
	s_waitcnt vmcnt(0)
	v_mov_b32_e32 v112, v170
	v_mov_b32_e32 v113, v171
	v_mov_b32_e32 v114, v172
	v_mov_b32_e32 v115, v173
	v_mov_b32_e32 v122, v166
	v_mov_b32_e32 v123, v167
	v_mov_b32_e32 v124, v168
	v_mov_b32_e32 v125, v169
	v_lshlrev_b32_e32 v87, 16, v30
	v_and_b32_e32 v93, 0xffff0000, v30
	v_lshlrev_b32_e32 v89, 16, v31
	v_and_b32_e32 v71, 0xffff0000, v36
	v_and_b32_e32 v70, 0xffff0000, v46
	v_lshlrev_b32_e32 v63, 16, v36
	v_and_b32_e32 v97, 0xffff0000, v31
	v_lshlrev_b32_e32 v62, 16, v46
	v_pk_mul_f32 v[30:31], v[70:71], v[70:71]
	v_lshlrev_b32_e32 v65, 16, v37
	v_and_b32_e32 v55, 0xffff0000, v33
	v_lshlrev_b32_e32 v59, 16, v32
	v_and_b32_e32 v67, 0xffff0000, v32
	v_lshlrev_b32_e32 v61, 16, v33
	v_lshlrev_b32_e32 v64, 16, v47
	v_pk_fma_f32 v[32:33], v[62:63], v[62:63], v[30:31]
	v_and_b32_e32 v77, 0xffff0000, v37
	v_and_b32_e32 v76, 0xffff0000, v47
	v_pk_fma_f32 v[32:33], v[64:65], v[64:65], v[32:33]
	v_lshlrev_b32_e32 v73, 16, v38
	v_lshlrev_b32_e32 v72, 16, v48
	v_pk_fma_f32 v[32:33], v[76:77], v[76:77], v[32:33]
	v_and_b32_e32 v85, 0xffff0000, v38
	v_and_b32_e32 v84, 0xffff0000, v48
	v_pk_fma_f32 v[32:33], v[72:73], v[72:73], v[32:33]
	v_lshlrev_b32_e32 v83, 16, v39
	v_lshlrev_b32_e32 v82, 16, v49
	v_pk_fma_f32 v[32:33], v[84:85], v[84:85], v[32:33]
	v_and_b32_e32 v95, 0xffff0000, v39
	v_and_b32_e32 v94, 0xffff0000, v49
	v_pk_fma_f32 v[32:33], v[82:83], v[82:83], v[32:33]
	v_lshlrev_b32_e32 v69, 16, v28
	v_lshlrev_b32_e32 v68, 16, v50
	v_pk_fma_f32 v[32:33], v[94:95], v[94:95], v[32:33]
	v_and_b32_e32 v57, 0xffff0000, v28
	v_and_b32_e32 v56, 0xffff0000, v50
	v_pk_fma_f32 v[32:33], v[68:69], v[68:69], v[32:33]
	v_lshlrev_b32_e32 v81, 16, v29
	v_lshlrev_b32_e32 v80, 16, v51
	v_pk_fma_f32 v[32:33], v[56:57], v[56:57], v[32:33]
	v_and_b32_e32 v91, 0xffff0000, v29
	v_and_b32_e32 v90, 0xffff0000, v51
	v_pk_fma_f32 v[32:33], v[80:81], v[80:81], v[32:33]
	v_lshlrev_b32_e32 v86, 16, v52
	v_pk_fma_f32 v[32:33], v[90:91], v[90:91], v[32:33]
	v_and_b32_e32 v92, 0xffff0000, v52
	v_pk_fma_f32 v[32:33], v[86:87], v[86:87], v[32:33]
	v_lshlrev_b32_e32 v88, 16, v53
	v_pk_fma_f32 v[32:33], v[92:93], v[92:93], v[32:33]
	v_and_b32_e32 v96, 0xffff0000, v53
	v_pk_fma_f32 v[32:33], v[88:89], v[88:89], v[32:33]
	v_lshlrev_b32_e32 v58, 16, v108
	v_pk_fma_f32 v[32:33], v[96:97], v[96:97], v[32:33]
	v_and_b32_e32 v66, 0xffff0000, v108
	v_pk_fma_f32 v[32:33], v[58:59], v[58:59], v[32:33]
	v_lshlrev_b32_e32 v60, 16, v109
	v_pk_fma_f32 v[32:33], v[66:67], v[66:67], v[32:33]
	v_and_b32_e32 v54, 0xffff0000, v109
	v_pk_fma_f32 v[32:33], v[60:61], v[60:61], v[32:33]
	v_lshlrev_b32_e32 v43, 16, v34
	v_lshlrev_b32_e32 v42, 16, v110
	v_pk_fma_f32 v[32:33], v[54:55], v[54:55], v[32:33]
	v_and_b32_e32 v79, 0xffff0000, v34
	v_and_b32_e32 v78, 0xffff0000, v110
	v_pk_fma_f32 v[32:33], v[42:43], v[42:43], v[32:33]
	v_lshlrev_b32_e32 v75, 16, v35
	v_lshlrev_b32_e32 v74, 16, v111
	v_pk_fma_f32 v[32:33], v[78:79], v[78:79], v[32:33]
	v_and_b32_e32 v99, 0xffff0000, v35
	v_and_b32_e32 v98, 0xffff0000, v111
	v_pk_fma_f32 v[32:33], v[74:75], v[74:75], v[32:33]
	v_lshlrev_b32_e32 v47, 16, v24
	v_pk_fma_f32 v[32:33], v[98:99], v[98:99], v[32:33]
	v_lshlrev_b32_e32 v46, 16, v12
	v_and_b32_e32 v100, 0xffff0000, v26
	v_lshlrev_b32_e32 v103, 16, v26
	v_and_b32_e32 v26, 0xffff0000, v14
	v_and_b32_e32 v49, 0xffff0000, v24
	v_and_b32_e32 v48, 0xffff0000, v12
	v_lshlrev_b32_e32 v50, 16, v13
	v_and_b32_e32 v24, 0xffff0000, v13
	v_pk_fma_f32 v[12:13], v[46:47], v[46:47], v[32:33]
	v_mov_b32_e32 v102, v100
	v_lshlrev_b32_e32 v53, 16, v14
	v_mov_b32_e32 v52, v26
	v_lshlrev_b32_e32 v51, 16, v25
	v_pk_fma_f32 v[12:13], v[48:49], v[48:49], v[12:13]
	v_pk_mul_f32 v[28:29], v[102:103], v[102:103]
	v_pk_mul_f32 v[30:31], v[52:53], v[52:53]
	v_and_b32_e32 v25, 0xffff0000, v25
	v_pk_fma_f32 v[12:13], v[50:51], v[50:51], v[12:13]
	v_mov_b32_e32 v32, v31
	v_pk_fma_f32 v[12:13], v[24:25], v[24:25], v[12:13]
	v_mov_b32_e32 v33, v29
	v_pk_add_f32 v[32:33], v[32:33], v[12:13]
	v_mbcnt_hi_u32_b32 v13, -1, v165
	v_and_b32_e32 v14, 64, v13
	v_and_b32_e32 v104, 0xffff0000, v27
	v_and_b32_e32 v12, 0xffff0000, v15
	v_add_u32_e32 v14, 64, v14
	v_xor_b32_e32 v29, 1, v13
	v_lshlrev_b32_e32 v107, 16, v27
	v_mov_b32_e32 v106, v104
	v_lshlrev_b32_e32 v111, 16, v15
	v_mov_b32_e32 v110, v12
	v_cmp_lt_i32_e32 vcc, v29, v14
	v_pk_mul_f32 v[6:7], v[106:107], v[106:107]
	v_pk_mul_f32 v[34:35], v[110:111], v[110:111]
	v_cndmask_b32_e32 v29, v13, v29, vcc
	v_mov_b32_e32 v31, v28
	v_lshlrev_b32_e32 v116, 2, v29
	v_pk_add_f32 v[28:29], v[30:31], v[32:33]
	v_mov_b32_e32 v30, v35
	v_mov_b32_e32 v31, v7
	v_pk_add_f32 v[28:29], v[30:31], v[28:29]
	v_mov_b32_e32 v35, v6
	v_pk_add_f32 v[6:7], v[34:35], v[28:29]
	ds_bpermute_b32 v29, v116, v7
	ds_bpermute_b32 v28, v116, v6
	v_xor_b32_e32 v30, 2, v13
	v_cmp_lt_i32_e32 vcc, v30, v14
	v_mov_b32_e32 v128, v65
	v_mov_b32_e32 v129, v77
	v_cndmask_b32_e32 v30, v13, v30, vcc
	v_lshlrev_b32_e32 v118, 2, v30
	s_waitcnt lgkmcnt(0)
	v_pk_add_f32 v[6:7], v[6:7], v[28:29]
	ds_bpermute_b32 v29, v118, v7
	ds_bpermute_b32 v28, v118, v6
	v_xor_b32_e32 v30, 4, v13
	v_cmp_lt_i32_e32 vcc, v30, v14
	v_mov_b32_e32 v134, v81
	v_mov_b32_e32 v135, v91
	v_cndmask_b32_e32 v30, v13, v30, vcc
	v_lshlrev_b32_e32 v119, 2, v30
	s_waitcnt lgkmcnt(0)
	v_pk_add_f32 v[6:7], v[6:7], v[28:29]
	ds_bpermute_b32 v29, v119, v7
	ds_bpermute_b32 v28, v119, v6
	v_xor_b32_e32 v30, 8, v13
	v_cmp_lt_i32_e32 vcc, v30, v14
	v_mov_b32_e32 v136, v87
	v_mov_b32_e32 v137, v93
	v_cndmask_b32_e32 v30, v13, v30, vcc
	v_lshlrev_b32_e32 v120, 2, v30
	s_waitcnt lgkmcnt(0)
	v_pk_add_f32 v[6:7], v[6:7], v[28:29]
	ds_bpermute_b32 v29, v120, v7
	ds_bpermute_b32 v28, v120, v6
	v_xor_b32_e32 v30, 16, v13
	v_cmp_lt_i32_e32 vcc, v30, v14
	v_mov_b32_e32 v138, v89
	v_mov_b32_e32 v139, v97
	v_cndmask_b32_e32 v30, v13, v30, vcc
	v_lshlrev_b32_e32 v121, 2, v30
	s_waitcnt lgkmcnt(0)
	v_pk_add_f32 v[6:7], v[6:7], v[28:29]
	ds_bpermute_b32 v29, v121, v7
	ds_bpermute_b32 v28, v121, v6
	v_xor_b32_e32 v30, 32, v13
	v_cmp_lt_i32_e32 vcc, v30, v14
	v_and_b32_e32 v101, s0, v27
	v_pk_mov_b32 v[100:101], v[102:103], v[100:101] op_sel:[1,0]
	v_cndmask_b32_e32 v13, v13, v30, vcc
	v_lshlrev_b32_e32 v117, 2, v13
	s_waitcnt lgkmcnt(0)
	v_pk_add_f32 v[108:109], v[6:7], v[28:29]
	ds_bpermute_b32 v127, v117, v109
	ds_bpermute_b32 v126, v117, v108
	flat_load_dwordx4 v[36:39], v[4:5]
	flat_load_dwordx4 v[32:35], v[4:5] offset:1024
	flat_load_dwordx4 v[28:31], v[4:5] offset:2048
	s_nop 0
	flat_load_dwordx4 v[4:7], v[4:5] offset:3072
	v_pk_mov_b32 v[102:103], v[106:107], v[104:105] op_sel:[1,0]
	v_mov_b32_e32 v65, v76
	v_mov_b32_e32 v81, v90
	s_waitcnt lgkmcnt(0)
	v_pk_add_f32 v[126:127], v[108:109], v[126:127]
	v_mov_b64_e32 v[108:109], s[40:41]
	v_pk_fma_f32 v[130:131], v[126:127], s[48:49], v[108:109] op_sel_hi:[1,0,0]
	v_mov_b32_e32 v126, v63
	v_mul_f32_e32 v13, 0x4b800000, v131
	v_cmp_gt_f32_e32 vcc, s3, v131
	v_mov_b32_e32 v127, v71
	s_add_u32 s40, s6, s50
	v_cndmask_b32_e32 v13, v131, v13, vcc
	v_rsq_f32_e32 v13, v13
	s_addc_u32 s41, s7, s51
	v_lshl_add_u64 v[132:133], s[40:41], 0, v[40:41]
	s_add_u32 s40, s6, s46
	v_mul_f32_e32 v14, 0x45800000, v13
	v_cndmask_b32_e32 v14, v13, v14, vcc
	v_pk_mul_f32 v[126:127], v[126:127], v[14:15] op_sel_hi:[1,0]
	v_pk_mul_f32 v[128:129], v[128:129], v[14:15] op_sel_hi:[1,0]
	v_pk_mul_f32 v[122:123], v[122:123], v[126:127]
	v_pk_mul_f32 v[124:125], v[124:125], v[128:129]
	v_mov_b32_e32 v126, v73
	v_mov_b32_e32 v127, v85
	v_mov_b32_e32 v128, v83
	v_mov_b32_e32 v129, v95
	v_pk_mul_f32 v[126:127], v[126:127], v[14:15] op_sel_hi:[1,0]
	v_pk_mul_f32 v[128:129], v[128:129], v[14:15] op_sel_hi:[1,0]
	v_pk_mul_f32 v[134:135], v[134:135], v[14:15] op_sel_hi:[1,0]
	v_pk_mul_f32 v[128:129], v[114:115], v[128:129]
	v_pk_mul_f32 v[114:115], v[112:113], v[126:127]
	v_cvt_pk_bf16_f32 v112, v122, v123
	v_cvt_pk_bf16_f32 v113, v124, v125
	v_pk_mul_f32 v[136:137], v[136:137], v[14:15] op_sel_hi:[1,0]
	v_cvt_pk_bf16_f32 v114, v114, v115
	v_cvt_pk_bf16_f32 v115, v128, v129
	global_store_dwordx4 v[132:133], v[112:115], off
	s_nop 1
	v_mov_b32_e32 v112, v69
	v_mov_b32_e32 v113, v57
	v_pk_mul_f32 v[112:113], v[112:113], v[14:15] op_sel_hi:[1,0]
	v_pk_mul_f32 v[138:139], v[138:139], v[14:15] op_sel_hi:[1,0]
	v_or_b32_e32 v114, 0x1000, v44
	v_or_b32_e32 v115, 0x1800, v44
	v_pk_mul_f32 v[100:101], v[14:15], v[100:101] op_sel_hi:[0,1]
	v_pk_mul_f32 v[102:103], v[14:15], v[102:103] op_sel_hi:[0,1]
	v_mul_f32_e32 v13, 0x4b800000, v130
	v_cmp_gt_f32_e32 vcc, s3, v130
	v_mov_b32_e32 v63, v70
	s_addc_u32 s41, s7, s47
	v_cndmask_b32_e32 v13, v130, v13, vcc
	v_rsq_f32_e32 v13, v13
	v_mov_b32_e32 v73, v84
	v_mov_b32_e32 v83, v94
	v_mov_b32_e32 v69, v56
	v_mov_b32_e32 v87, v92
	v_mov_b32_e32 v89, v96
	v_lshlrev_b32_e32 v85, 16, v20
	v_and_b32_e32 v93, 0xffff0000, v21
	v_and_b32_e32 v95, 0xffff0000, v22
	v_lshlrev_b32_e32 v91, 16, v23
	v_and_b32_e32 v27, s0, v15
	v_and_b32_e32 v97, 0xffff0000, v23
	s_waitcnt vmcnt(1)
	v_mov_b32_e32 v122, v174
	v_mov_b32_e32 v123, v175
	v_mov_b32_e32 v124, v176
	v_mov_b32_e32 v125, v177
	v_mov_b32_e32 v126, v178
	v_mov_b32_e32 v127, v179
	v_mov_b32_e32 v128, v180
	v_mov_b32_e32 v129, v181
	v_and_b32_e32 v94, 0xffff0000, v38
	v_lshlrev_b32_e32 v90, 16, v39
	v_and_b32_e32 v96, 0xffff0000, v39
	v_lshlrev_b32_e32 v84, 16, v36
	v_and_b32_e32 v92, 0xffff0000, v37
	v_pk_mul_f32 v[124:125], v[124:125], v[134:135]
	v_pk_mul_f32 v[112:113], v[122:123], v[112:113]
	v_pk_mul_f32 v[128:129], v[128:129], v[138:139]
	v_pk_mul_f32 v[126:127], v[126:127], v[136:137]
	v_cvt_pk_bf16_f32 v122, v112, v113
	v_cvt_pk_bf16_f32 v123, v124, v125
	v_mov_b32_e32 v134, v61
	v_cvt_pk_bf16_f32 v124, v126, v127
	v_cvt_pk_bf16_f32 v125, v128, v129
	global_store_dwordx4 v[132:133], v[122:125], off offset:1024
	s_nop 1
	s_nop 0
	v_mov_b32_e32 v135, v55
	v_mov_b32_e32 v112, v59
	v_mov_b32_e32 v113, v67
	v_mov_b32_e32 v136, v43
	v_mov_b32_e32 v137, v79
	v_mov_b32_e32 v138, v75
	v_mov_b32_e32 v139, v99
	v_pk_mul_f32 v[134:135], v[134:135], v[14:15] op_sel_hi:[1,0]
	v_pk_mul_f32 v[112:113], v[112:113], v[14:15] op_sel_hi:[1,0]
	v_pk_mul_f32 v[136:137], v[136:137], v[14:15] op_sel_hi:[1,0]
	v_pk_mul_f32 v[138:139], v[138:139], v[14:15] op_sel_hi:[1,0]
	v_mov_b32_e32 v43, v78
	v_mov_b32_e32 v59, v66
	v_mov_b32_e32 v61, v54
	v_mov_b32_e32 v75, v98
	v_and_b32_e32 v98, 0xffff0000, v2
	v_and_b32_e32 v67, 0xffff0000, v10
	v_and_b32_e32 v78, 0xffff0000, v35
	v_and_b32_e32 v66, 0xffff0000, v30
	v_and_b32_e32 v79, 0xffff0000, v19
	v_and_b32_e32 v99, s0, v3
	v_mov_b32_e32 v122, v182
	v_mov_b32_e32 v123, v183
	v_mov_b32_e32 v124, v184
	v_mov_b32_e32 v125, v185
	v_mov_b32_e32 v126, v186
	v_mov_b32_e32 v127, v187
	v_mov_b32_e32 v128, v188
	v_mov_b32_e32 v129, v189
	v_pk_mul_f32 v[124:125], v[134:135], v[124:125]
	v_pk_mul_f32 v[112:113], v[112:113], v[122:123]
	v_pk_mul_f32 v[128:129], v[138:139], v[128:129]
	v_pk_mul_f32 v[126:127], v[136:137], v[126:127]
	v_cvt_pk_bf16_f32 v122, v112, v113
	v_cvt_pk_bf16_f32 v123, v124, v125
	v_mov_b32_e32 v112, v47
	v_cvt_pk_bf16_f32 v124, v126, v127
	v_cvt_pk_bf16_f32 v125, v128, v129
	global_store_dwordx4 v[132:133], v[122:125], off offset:2048
	s_nop 1
	s_nop 0
	v_mov_b32_e32 v113, v49
	v_mov_b32_e32 v134, v51
	v_mov_b32_e32 v135, v25
	v_pk_mul_f32 v[104:105], v[112:113], v[14:15] op_sel_hi:[1,0]
	v_pk_mul_f32 v[106:107], v[134:135], v[14:15] op_sel_hi:[1,0]
	v_mul_f32_e32 v14, 0x45800000, v13
	v_cndmask_b32_e32 v130, v13, v14, vcc
	v_pk_mul_f32 v[62:63], v[62:63], v[130:131] op_sel_hi:[1,0]
	v_pk_mul_f32 v[64:65], v[64:65], v[130:131] op_sel_hi:[1,0]
	v_pk_mul_f32 v[70:71], v[72:73], v[130:131] op_sel_hi:[1,0]
	v_pk_mul_f32 v[72:73], v[82:83], v[130:131] op_sel_hi:[1,0]
	v_pk_mul_f32 v[56:57], v[68:69], v[130:131] op_sel_hi:[1,0]
	v_pk_mul_f32 v[68:69], v[80:81], v[130:131] op_sel_hi:[1,0]
	v_pk_mul_f32 v[76:77], v[86:87], v[130:131] op_sel_hi:[1,0]
	v_pk_mul_f32 v[80:81], v[88:89], v[130:131] op_sel_hi:[1,0]
	v_lshlrev_b32_e32 v88, 16, v38
	v_pk_mul_f32 v[38:39], v[42:43], v[130:131] op_sel_hi:[1,0]
	v_lshlrev_b32_e32 v86, 16, v37
	v_and_b32_e32 v82, 0xffff0000, v33
	v_pk_mul_f32 v[42:43], v[74:75], v[130:131] op_sel_hi:[1,0]
	v_and_b32_e32 v75, 0xffff0000, v8
	v_lshlrev_b32_e32 v87, 16, v21
	v_lshlrev_b32_e32 v89, 16, v22
	v_and_b32_e32 v14, 0xffff0000, v6
	v_mov_b32_e32 v13, v41
	v_mov_b32_e32 v47, v48
	v_and_b32_e32 v83, 0xffff0000, v17
	v_pk_mov_b32 v[12:13], v[110:111], v[12:13] op_sel:[1,0]
	v_mov_b32_e32 v51, v24
	v_pk_mul_f32 v[12:13], v[130:131], v[12:13] op_sel_hi:[0,1]
	v_and_b32_e32 v74, 0xffff0000, v28
	v_mov_b32_e32 v24, v87
	v_mov_b32_e32 v25, v93
	v_and_b32_e32 v15, s0, v7
	v_mov_b32_e32 v122, v190
	v_mov_b32_e32 v123, v191
	v_mov_b32_e32 v124, v192
	v_mov_b32_e32 v125, v193
	v_mov_b32_e32 v126, v200
	v_mov_b32_e32 v127, v201
	v_mov_b32_e32 v128, v202
	v_mov_b32_e32 v129, v203
	v_pk_mul_f32 v[106:107], v[106:107], v[124:125]
	v_pk_mul_f32 v[112:113], v[102:103], v[128:129]
	v_pk_mul_f32 v[102:103], v[100:101], v[126:127]
	v_pk_mul_f32 v[104:105], v[104:105], v[122:123]
	s_nop 0
	v_cvt_pk_bf16_f32 v100, v104, v105
	v_cvt_pk_bf16_f32 v101, v106, v107
	v_cvt_pk_bf16_f32 v102, v102, v103
	v_cvt_pk_bf16_f32 v103, v112, v113
	global_store_dwordx4 v[132:133], v[100:103], off offset:3072
	s_nop 1
	s_nop 0
	v_lshl_add_u64 v[112:113], s[40:41], 0, v[40:41]
	s_add_u32 s40, s6, s44
	s_addc_u32 s41, s7, s45
	s_add_u32 s12, s6, s12
	s_addc_u32 s13, s7, s13
	v_mov_b32_e32 v100, v166
	v_mov_b32_e32 v101, v167
	v_mov_b32_e32 v102, v168
	v_mov_b32_e32 v103, v169
	v_mov_b32_e32 v104, v170
	v_mov_b32_e32 v105, v171
	v_mov_b32_e32 v106, v172
	v_mov_b32_e32 v107, v173
	v_pk_mul_f32 v[64:65], v[64:65], v[102:103]
	v_pk_mul_f32 v[62:63], v[62:63], v[100:101]
	v_pk_mul_f32 v[72:73], v[72:73], v[106:107]
	v_pk_mul_f32 v[70:71], v[70:71], v[104:105]
	v_cvt_pk_bf16_f32 v62, v62, v63
	v_cvt_pk_bf16_f32 v63, v64, v65
	v_and_b32_e32 v100, 0xffff0000, v36
	v_cvt_pk_bf16_f32 v64, v70, v71
	v_cvt_pk_bf16_f32 v65, v72, v73
	global_store_dwordx4 v[112:113], v[62:65], off
	s_nop 1
	s_nop 0
	v_pk_mul_f32 v[36:37], v[60:61], v[130:131] op_sel_hi:[1,0]
	v_and_b32_e32 v101, 0xffff0000, v20
	v_lshlrev_b32_e32 v107, 16, v2
	v_and_b32_e32 v61, 0xffff0000, v11
	v_mov_b32_e32 v106, v98
	v_and_b32_e32 v60, 0xffff0000, v31
	v_mov_b32_e32 v62, v174
	v_mov_b32_e32 v63, v175
	v_mov_b32_e32 v64, v176
	v_mov_b32_e32 v65, v177
	v_mov_b32_e32 v70, v178
	v_mov_b32_e32 v71, v179
	v_mov_b32_e32 v72, v180
	v_mov_b32_e32 v73, v181
	v_pk_mul_f32 v[64:65], v[68:69], v[64:65]
	v_pk_mul_f32 v[56:57], v[56:57], v[62:63]
	v_pk_mul_f32 v[68:69], v[80:81], v[72:73]
	v_pk_mul_f32 v[70:71], v[76:77], v[70:71]
	v_cvt_pk_bf16_f32 v62, v56, v57
	v_cvt_pk_bf16_f32 v63, v64, v65
	v_and_b32_e32 v80, 0xffff0000, v32
	v_cvt_pk_bf16_f32 v64, v70, v71
	v_cvt_pk_bf16_f32 v65, v68, v69
	global_store_dwordx4 v[112:113], v[62:65], off offset:1024
	s_nop 1
	v_lshlrev_b32_e32 v64, 16, v32
	v_lshlrev_b32_e32 v68, 16, v33
	v_pk_mul_f32 v[32:33], v[58:59], v[130:131] op_sel_hi:[1,0]
	v_and_b32_e32 v63, 0xffff0000, v9
	v_lshlrev_b32_e32 v57, 16, v10
	v_lshlrev_b32_e32 v65, 16, v16
	v_lshlrev_b32_e32 v59, 16, v11
	v_pk_mov_b32 v[10:11], v[52:53], v[26:27] op_sel:[1,0]
	v_and_b32_e32 v81, 0xffff0000, v16
	v_lshlrev_b32_e32 v69, 16, v17
	v_pk_mul_f32 v[16:17], v[106:107], v[106:107]
	v_pk_mul_f32 v[10:11], v[130:131], v[10:11] op_sel_hi:[0,1]
	v_mov_b32_e32 v23, v17
	v_and_b32_e32 v62, 0xffff0000, v29
	v_lshlrev_b32_e32 v56, 16, v30
	v_lshlrev_b32_e32 v70, 16, v34
	v_and_b32_e32 v76, 0xffff0000, v34
	v_lshlrev_b32_e32 v72, 16, v35
	v_lshlrev_b32_e32 v58, 16, v31
	v_and_b32_e32 v30, 0xffff0000, v4
	v_and_b32_e32 v34, 0xffff0000, v5
	v_lshlrev_b32_e32 v71, 16, v18
	v_and_b32_e32 v77, 0xffff0000, v18
	v_lshlrev_b32_e32 v73, 16, v19
	v_and_b32_e32 v31, 0xffff0000, v0
	v_and_b32_e32 v35, 0xffff0000, v1
	v_mov_b32_e32 v102, v182
	v_mov_b32_e32 v103, v183
	v_mov_b32_e32 v104, v184
	v_mov_b32_e32 v105, v185
	v_mov_b32_e32 v122, v186
	v_mov_b32_e32 v123, v187
	v_mov_b32_e32 v124, v188
	v_mov_b32_e32 v125, v189
	v_pk_mul_f32 v[54:55], v[36:37], v[104:105]
	v_pk_mul_f32 v[38:39], v[38:39], v[122:123]
	v_pk_mul_f32 v[32:33], v[32:33], v[102:103]
	v_pk_mul_f32 v[42:43], v[42:43], v[124:125]
	v_cvt_pk_bf16_f32 v36, v32, v33
	v_cvt_pk_bf16_f32 v37, v54, v55
	v_cvt_pk_bf16_f32 v38, v38, v39
	v_lshlrev_b32_e32 v55, 16, v9
	v_cvt_pk_bf16_f32 v39, v42, v43
	global_store_dwordx4 v[112:113], v[36:39], off offset:2048
	s_nop 1
	v_lshlrev_b32_e32 v43, 16, v8
	v_pk_mul_f32 v[8:9], v[100:101], v[100:101]
	v_lshlrev_b32_e32 v33, 16, v6
	v_pk_fma_f32 v[8:9], v[84:85], v[84:85], v[8:9]
	v_mov_b32_e32 v32, v14
	v_pk_fma_f32 v[8:9], v[86:87], v[86:87], v[8:9]
	v_and_b32_e32 v36, 0xffff0000, v7
	v_pk_fma_f32 v[8:9], v[92:93], v[92:93], v[8:9]
	v_and_b32_e32 v102, 0xffff0000, v3
	v_pk_fma_f32 v[8:9], v[88:89], v[88:89], v[8:9]
	v_pk_mul_f32 v[20:21], v[32:33], v[32:33]
	v_pk_fma_f32 v[8:9], v[94:95], v[94:95], v[8:9]
	v_lshlrev_b32_e32 v39, 16, v7
	v_pk_fma_f32 v[8:9], v[90:91], v[90:91], v[8:9]
	v_mov_b32_e32 v38, v36
	v_pk_fma_f32 v[8:9], v[96:97], v[96:97], v[8:9]
	v_lshlrev_b32_e32 v105, 16, v3
	v_pk_fma_f32 v[52:53], v[64:65], v[64:65], v[8:9]
	v_pk_mul_f32 v[8:9], v[46:47], v[130:131] op_sel_hi:[1,0]
	v_mov_b32_e32 v104, v102
	v_mov_b32_e32 v22, v21
	v_mov_b32_e32 v21, v16
	v_pk_mul_f32 v[16:17], v[50:51], v[130:131] op_sel_hi:[1,0]
	v_lshlrev_b32_e32 v42, 16, v28
	v_lshlrev_b32_e32 v54, 16, v29
	v_lshlrev_b32_e32 v28, 16, v4
	v_lshlrev_b32_e32 v4, 16, v5
	v_lshlrev_b32_e32 v29, 16, v0
	v_lshlrev_b32_e32 v5, 16, v1
	v_pk_mul_f32 v[0:1], v[38:39], v[38:39]
	v_pk_mul_f32 v[18:19], v[104:105], v[104:105]
	v_mov_b32_e32 v26, v1
	v_mov_b32_e32 v27, v19
	v_mov_b32_e32 v1, v18
	v_mov_b32_e32 v103, v41
	v_mov_b32_e32 v87, v92
	v_mov_b32_e32 v37, v41
	v_mov_b32_e32 v122, v200
	v_mov_b32_e32 v123, v201
	v_mov_b32_e32 v124, v202
	v_mov_b32_e32 v125, v203
	v_mov_b32_e32 v126, v190
	v_mov_b32_e32 v127, v191
	v_mov_b32_e32 v128, v192
	v_mov_b32_e32 v129, v193
	v_pk_mul_f32 v[10:11], v[10:11], v[122:123]
	v_pk_mul_f32 v[8:9], v[8:9], v[126:127]
	v_pk_mul_f32 v[16:17], v[16:17], v[128:129]
	v_pk_mul_f32 v[12:13], v[12:13], v[124:125]
	v_cvt_pk_bf16_f32 v8, v8, v9
	v_cvt_pk_bf16_f32 v9, v16, v17
	v_cvt_pk_bf16_f32 v10, v10, v11
	s_nop 0
	v_cvt_pk_bf16_f32 v11, v12, v13
	global_store_dwordx4 v[112:113], v[8:11], off offset:3072
	s_nop 1
	s_nop 0
	v_pk_fma_f32 v[12:13], v[80:81], v[80:81], v[52:53]
	s_nop 0
	v_pk_fma_f32 v[12:13], v[68:69], v[68:69], v[12:13]
	s_nop 0
	v_pk_fma_f32 v[12:13], v[82:83], v[82:83], v[12:13]
	s_nop 0
	v_pk_fma_f32 v[12:13], v[70:71], v[70:71], v[12:13]
	s_nop 0
	v_pk_fma_f32 v[12:13], v[76:77], v[76:77], v[12:13]
	s_nop 0
	v_pk_fma_f32 v[12:13], v[72:73], v[72:73], v[12:13]
	s_nop 0
	v_pk_fma_f32 v[12:13], v[78:79], v[78:79], v[12:13]
	s_nop 0
	v_pk_fma_f32 v[12:13], v[42:43], v[42:43], v[12:13]
	s_nop 0
	v_pk_fma_f32 v[12:13], v[74:75], v[74:75], v[12:13]
	s_nop 0
	v_pk_fma_f32 v[12:13], v[54:55], v[54:55], v[12:13]
	s_nop 0
	v_pk_fma_f32 v[12:13], v[62:63], v[62:63], v[12:13]
	s_nop 0
	v_pk_fma_f32 v[12:13], v[56:57], v[56:57], v[12:13]
	s_nop 0
	v_pk_fma_f32 v[12:13], v[66:67], v[66:67], v[12:13]
	s_nop 0
	v_pk_fma_f32 v[12:13], v[58:59], v[58:59], v[12:13]
	s_nop 0
	v_pk_fma_f32 v[12:13], v[60:61], v[60:61], v[12:13]
	s_nop 0
	v_pk_fma_f32 v[12:13], v[28:29], v[28:29], v[12:13]
	s_nop 0
	v_pk_fma_f32 v[12:13], v[30:31], v[30:31], v[12:13]
	s_nop 0
	v_pk_fma_f32 v[12:13], v[4:5], v[4:5], v[12:13]
	s_nop 0
	v_pk_fma_f32 v[12:13], v[34:35], v[34:35], v[12:13]
	s_nop 0
	v_pk_add_f32 v[12:13], v[22:23], v[12:13]
	v_mov_b32_e32 v22, v85
	v_pk_add_f32 v[12:13], v[20:21], v[12:13]
	v_mov_b32_e32 v23, v101
	v_pk_add_f32 v[12:13], v[26:27], v[12:13]
	v_mov_b32_e32 v26, v89
	v_pk_add_f32 v[0:1], v[0:1], v[12:13]
	ds_bpermute_b32 v13, v116, v1
	ds_bpermute_b32 v12, v116, v0
	v_mov_b32_e32 v27, v95
	v_lshl_add_u64 v[20:21], s[40:41], 0, v[40:41]
	v_mov_b32_e32 v85, v100
	v_mov_b32_e32 v89, v94
	s_waitcnt lgkmcnt(0)
	v_pk_add_f32 v[0:1], v[0:1], v[12:13]
	ds_bpermute_b32 v13, v118, v1
	ds_bpermute_b32 v12, v118, v0
	s_waitcnt lgkmcnt(0)
	v_pk_add_f32 v[0:1], v[0:1], v[12:13]
	ds_bpermute_b32 v13, v119, v1
	ds_bpermute_b32 v12, v119, v0
	s_waitcnt lgkmcnt(0)
	v_pk_add_f32 v[0:1], v[0:1], v[12:13]
	ds_bpermute_b32 v13, v120, v1
	ds_bpermute_b32 v12, v120, v0
	s_waitcnt lgkmcnt(0)
	v_pk_add_f32 v[0:1], v[0:1], v[12:13]
	ds_bpermute_b32 v13, v121, v1
	ds_bpermute_b32 v12, v121, v0
	s_waitcnt lgkmcnt(0)
	v_pk_add_f32 v[0:1], v[0:1], v[12:13]
	ds_bpermute_b32 v13, v117, v1
	ds_bpermute_b32 v12, v117, v0
	s_waitcnt lgkmcnt(0)
	v_pk_add_f32 v[0:1], v[0:1], v[12:13]
	s_nop 0
	v_pk_fma_f32 v[12:13], v[0:1], s[48:49], v[108:109] op_sel_hi:[1,0,0]
	v_mov_b32_e32 v1, v97
	v_mul_f32_e32 v0, 0x4b800000, v13
	v_cmp_gt_f32_e32 vcc, s3, v13
	s_nop 1
	v_cndmask_b32_e32 v0, v13, v0, vcc
	v_rsq_f32_e32 v2, v0
	v_mov_b32_e32 v0, v91
	v_mov_b32_e32 v91, v96
	v_mul_f32_e32 v6, 0x45800000, v2
	v_cndmask_b32_e32 v2, v2, v6, vcc
	v_pk_mul_f32 v[26:27], v[26:27], v[2:3] op_sel_hi:[1,0]
	v_pk_mul_f32 v[0:1], v[0:1], v[2:3] op_sel_hi:[1,0]
	v_pk_mul_f32 v[22:23], v[22:23], v[2:3] op_sel_hi:[1,0]
	v_pk_mul_f32 v[24:25], v[24:25], v[2:3] op_sel_hi:[1,0]
	v_mov_b32_e32 v8, v170
	v_mov_b32_e32 v9, v171
	v_mov_b32_e32 v10, v172
	v_mov_b32_e32 v11, v173
	v_mov_b32_e32 v16, v166
	v_mov_b32_e32 v17, v167
	v_mov_b32_e32 v18, v168
	v_mov_b32_e32 v19, v169
	v_pk_mul_f32 v[0:1], v[0:1], v[10:11]
	v_pk_mul_f32 v[10:11], v[26:27], v[8:9]
	v_pk_mul_f32 v[18:19], v[24:25], v[18:19]
	v_pk_mul_f32 v[16:17], v[22:23], v[16:17]
	v_mov_b32_e32 v22, v69
	v_cvt_pk_bf16_f32 v8, v16, v17
	v_cvt_pk_bf16_f32 v9, v18, v19
	v_cvt_pk_bf16_f32 v10, v10, v11
	v_cvt_pk_bf16_f32 v11, v0, v1
	global_store_dwordx4 v[20:21], v[8:11], off
	s_nop 1
	s_nop 0
	v_mov_b32_e32 v23, v83
	v_mov_b32_e32 v0, v65
	v_mov_b32_e32 v1, v81
	v_mov_b32_e32 v24, v71
	v_mov_b32_e32 v25, v77
	v_mov_b32_e32 v26, v73
	v_mov_b32_e32 v27, v79
	v_pk_mul_f32 v[22:23], v[22:23], v[2:3] op_sel_hi:[1,0]
	v_pk_mul_f32 v[0:1], v[0:1], v[2:3] op_sel_hi:[1,0]
	v_pk_mul_f32 v[24:25], v[24:25], v[2:3] op_sel_hi:[1,0]
	v_pk_mul_f32 v[26:27], v[26:27], v[2:3] op_sel_hi:[1,0]
	v_cmp_gt_f32_e32 vcc, s3, v12
	v_mov_b32_e32 v65, v80
	v_mov_b32_e32 v69, v82
	v_mov_b32_e32 v71, v76
	v_mov_b32_e32 v73, v78
	s_lshl_b32 s3, s26, 5
	s_add_i32 s52, s24, s3
	v_mov_b32_e32 v8, v174
	v_mov_b32_e32 v9, v175
	v_mov_b32_e32 v10, v176
	v_mov_b32_e32 v11, v177
	v_mov_b32_e32 v16, v178
	v_mov_b32_e32 v17, v179
	v_mov_b32_e32 v18, v180
	v_mov_b32_e32 v19, v181
	v_pk_mul_f32 v[10:11], v[22:23], v[10:11]
	v_pk_mul_f32 v[0:1], v[0:1], v[8:9]
	v_pk_mul_f32 v[18:19], v[26:27], v[18:19]
	v_pk_mul_f32 v[16:17], v[24:25], v[16:17]
	v_cvt_pk_bf16_f32 v8, v0, v1
	v_cvt_pk_bf16_f32 v9, v10, v11
	v_mov_b32_e32 v22, v55
	v_cvt_pk_bf16_f32 v10, v16, v17
	v_cvt_pk_bf16_f32 v11, v18, v19
	global_store_dwordx4 v[20:21], v[8:11], off offset:1024
	s_nop 1
	s_nop 0
	v_mov_b32_e32 v23, v63
	v_mov_b32_e32 v0, v43
	v_mov_b32_e32 v1, v75
	v_mov_b32_e32 v24, v57
	v_mov_b32_e32 v25, v67
	v_mov_b32_e32 v26, v59
	v_mov_b32_e32 v27, v61
	v_pk_mul_f32 v[22:23], v[22:23], v[2:3] op_sel_hi:[1,0]
	v_pk_mul_f32 v[0:1], v[0:1], v[2:3] op_sel_hi:[1,0]
	v_pk_mul_f32 v[24:25], v[24:25], v[2:3] op_sel_hi:[1,0]
	v_pk_mul_f32 v[26:27], v[26:27], v[2:3] op_sel_hi:[1,0]
	v_mov_b32_e32 v43, v74
	v_mov_b32_e32 v55, v62
	v_mov_b32_e32 v57, v66
	v_mov_b32_e32 v59, v60
	v_mov_b32_e32 v8, v182
	v_mov_b32_e32 v9, v183
	v_mov_b32_e32 v10, v184
	v_mov_b32_e32 v11, v185
	v_mov_b32_e32 v16, v186
	v_mov_b32_e32 v17, v187
	v_mov_b32_e32 v18, v188
	v_mov_b32_e32 v19, v189
	v_pk_mul_f32 v[10:11], v[22:23], v[10:11]
	v_pk_mul_f32 v[0:1], v[0:1], v[8:9]
	v_pk_mul_f32 v[18:19], v[26:27], v[18:19]
	v_pk_mul_f32 v[16:17], v[24:25], v[16:17]
	v_cvt_pk_bf16_f32 v8, v0, v1
	v_cvt_pk_bf16_f32 v9, v10, v11
	v_mov_b32_e32 v0, v29
	v_cvt_pk_bf16_f32 v10, v16, v17
	v_cvt_pk_bf16_f32 v11, v18, v19
	global_store_dwordx4 v[20:21], v[8:11], off offset:2048
	s_nop 1
	s_nop 0
	v_mov_b32_e32 v1, v31
	v_mov_b32_e32 v22, v5
	v_mov_b32_e32 v23, v35
	v_pk_mov_b32 v[24:25], v[106:107], v[98:99] op_sel:[1,0]
	v_pk_mov_b32 v[26:27], v[104:105], v[102:103] op_sel:[1,0]
	v_pk_mul_f32 v[0:1], v[0:1], v[2:3] op_sel_hi:[1,0]
	v_pk_mul_f32 v[22:23], v[22:23], v[2:3] op_sel_hi:[1,0]
	v_pk_mul_f32 v[24:25], v[2:3], v[24:25] op_sel_hi:[0,1]
	v_pk_mul_f32 v[2:3], v[2:3], v[26:27] op_sel_hi:[0,1]
	v_mul_f32_e32 v5, 0x4b800000, v12
	v_cndmask_b32_e32 v5, v12, v5, vcc
	v_rsq_f32_e32 v5, v5
	v_mov_b32_e32 v29, v30
	v_mul_f32_e32 v6, 0x45800000, v5
	v_cndmask_b32_e32 v6, v5, v6, vcc
	v_pk_mul_f32 v[12:13], v[84:85], v[6:7] op_sel_hi:[1,0]
	v_mov_b32_e32 v5, v34
	v_pk_mul_f32 v[4:5], v[4:5], v[6:7] op_sel_hi:[1,0]
	v_mov_b32_e32 v8, v190
	v_mov_b32_e32 v9, v191
	v_mov_b32_e32 v10, v192
	v_mov_b32_e32 v11, v193
	v_mov_b32_e32 v16, v200
	v_mov_b32_e32 v17, v201
	v_mov_b32_e32 v18, v202
	v_mov_b32_e32 v19, v203
	v_pk_mul_f32 v[0:1], v[0:1], v[8:9]
	v_pk_mul_f32 v[8:9], v[2:3], v[18:19]
	v_pk_mul_f32 v[2:3], v[24:25], v[16:17]
	v_pk_mul_f32 v[10:11], v[22:23], v[10:11]
	v_cvt_pk_bf16_f32 v0, v0, v1
	v_pk_mul_f32 v[18:19], v[86:87], v[6:7] op_sel_hi:[1,0]
	v_cvt_pk_bf16_f32 v1, v10, v11
	v_cvt_pk_bf16_f32 v2, v2, v3
	v_cvt_pk_bf16_f32 v3, v8, v9
	global_store_dwordx4 v[20:21], v[0:3], off offset:3072
	s_nop 1
	s_nop 0
	v_lshl_add_u64 v[16:17], s[12:13], 0, v[40:41]
	v_pk_mul_f32 v[20:21], v[88:89], v[6:7] op_sel_hi:[1,0]
	v_pk_mul_f32 v[22:23], v[90:91], v[6:7] op_sel_hi:[1,0]
	v_mov_b32_e32 v0, v166
	v_mov_b32_e32 v1, v167
	v_mov_b32_e32 v2, v168
	v_mov_b32_e32 v3, v169
	v_mov_b32_e32 v8, v170
	v_mov_b32_e32 v9, v171
	v_mov_b32_e32 v10, v172
	v_mov_b32_e32 v11, v173
	v_pk_mul_f32 v[2:3], v[18:19], v[2:3]
	v_pk_mul_f32 v[0:1], v[12:13], v[0:1]
	v_pk_mul_f32 v[10:11], v[22:23], v[10:11]
	v_pk_mul_f32 v[8:9], v[20:21], v[8:9]
	v_cvt_pk_bf16_f32 v0, v0, v1
	v_cvt_pk_bf16_f32 v1, v2, v3
	v_pk_mul_f32 v[12:13], v[64:65], v[6:7] op_sel_hi:[1,0]
	v_cvt_pk_bf16_f32 v2, v8, v9
	v_cvt_pk_bf16_f32 v3, v10, v11
	global_store_dwordx4 v[16:17], v[0:3], off
	s_nop 1
	s_nop 0
	v_pk_mul_f32 v[18:19], v[68:69], v[6:7] op_sel_hi:[1,0]
	v_pk_mul_f32 v[20:21], v[70:71], v[6:7] op_sel_hi:[1,0]
	v_pk_mul_f32 v[22:23], v[72:73], v[6:7] op_sel_hi:[1,0]
	v_mov_b32_e32 v0, v174
	v_mov_b32_e32 v1, v175
	v_mov_b32_e32 v2, v176
	v_mov_b32_e32 v3, v177
	v_mov_b32_e32 v8, v178
	v_mov_b32_e32 v9, v179
	v_mov_b32_e32 v10, v180
	v_mov_b32_e32 v11, v181
	v_pk_mul_f32 v[2:3], v[18:19], v[2:3]
	v_pk_mul_f32 v[0:1], v[12:13], v[0:1]
	v_pk_mul_f32 v[10:11], v[22:23], v[10:11]
	v_pk_mul_f32 v[8:9], v[20:21], v[8:9]
	v_cvt_pk_bf16_f32 v0, v0, v1
	v_cvt_pk_bf16_f32 v1, v2, v3
	v_pk_mul_f32 v[12:13], v[42:43], v[6:7] op_sel_hi:[1,0]
	v_cvt_pk_bf16_f32 v2, v8, v9
	v_cvt_pk_bf16_f32 v3, v10, v11
	global_store_dwordx4 v[16:17], v[0:3], off offset:1024
	s_nop 1
	s_nop 0
	v_pk_mul_f32 v[18:19], v[54:55], v[6:7] op_sel_hi:[1,0]
	v_pk_mul_f32 v[20:21], v[56:57], v[6:7] op_sel_hi:[1,0]
	v_pk_mul_f32 v[22:23], v[58:59], v[6:7] op_sel_hi:[1,0]
	v_mov_b32_e32 v0, v182
	v_mov_b32_e32 v1, v183
	v_mov_b32_e32 v2, v184
	v_mov_b32_e32 v3, v185
	v_mov_b32_e32 v8, v186
	v_mov_b32_e32 v9, v187
	v_mov_b32_e32 v10, v188
	v_mov_b32_e32 v11, v189
	v_pk_mul_f32 v[2:3], v[18:19], v[2:3]
	v_pk_mul_f32 v[0:1], v[12:13], v[0:1]
	v_pk_mul_f32 v[10:11], v[22:23], v[10:11]
	v_pk_mul_f32 v[8:9], v[20:21], v[8:9]
	v_cvt_pk_bf16_f32 v0, v0, v1
	v_cvt_pk_bf16_f32 v1, v2, v3
	v_pk_mov_b32 v[12:13], v[32:33], v[14:15] op_sel:[1,0]
	v_cvt_pk_bf16_f32 v2, v8, v9
	v_cvt_pk_bf16_f32 v3, v10, v11
	global_store_dwordx4 v[16:17], v[0:3], off offset:2048
	s_nop 1
	s_nop 0
	v_pk_mov_b32 v[14:15], v[38:39], v[36:37] op_sel:[1,0]
	v_pk_mul_f32 v[18:19], v[28:29], v[6:7] op_sel_hi:[1,0]
	v_pk_mul_f32 v[12:13], v[6:7], v[12:13] op_sel_hi:[0,1]
	v_pk_mul_f32 v[6:7], v[6:7], v[14:15] op_sel_hi:[0,1]
	v_mov_b32_e32 v0, v190
	v_mov_b32_e32 v1, v191
	v_mov_b32_e32 v2, v192
	v_mov_b32_e32 v3, v193
	v_mov_b32_e32 v8, v200
	v_mov_b32_e32 v9, v201
	v_mov_b32_e32 v10, v202
	v_mov_b32_e32 v11, v203
	v_pk_mul_f32 v[2:3], v[4:5], v[2:3]
	v_pk_mul_f32 v[0:1], v[18:19], v[0:1]
	v_pk_mul_f32 v[4:5], v[6:7], v[10:11]
	v_pk_mul_f32 v[6:7], v[12:13], v[8:9]
	v_cvt_pk_bf16_f32 v0, v0, v1
	v_cvt_pk_bf16_f32 v1, v2, v3
	s_nop 0
	v_cvt_pk_bf16_f32 v2, v6, v7
	v_cvt_pk_bf16_f32 v3, v4, v5
	global_store_dwordx4 v[16:17], v[0:3], off offset:3072
	s_nop 1

.LBB0_1026:
	s_or_b64 exec, exec, s[6:7]
	s_waitcnt lgkmcnt(0)
	v_mov_b32_e32 v0, v164
	s_barrier
	s_add_u32 s6, s34, 0x2aa00000
	s_mov_b32 s8, 22
	s_addc_u32 s7, s35, 0
	s_ashr_i32 s9, s8, 31
	s_lshl_b64 s[8:9], s[8:9], 3
	s_add_u32 s8, s0, s8
	s_addc_u32 s9, s1, s9
	s_load_dwordx2 s[12:13], s[8:9], 0x0
	v_and_b32_e32 v0, 63, v0
	s_add_u32 s10, s34, 0x9800000
	s_addc_u32 s11, s35, 0
	s_and_b64 vcc, exec, s[4:5]
	v_lshlrev_b32_e32 v40, 4, v0
	v_lshlrev_b32_e32 v48, 5, v0
	s_mov_b32 s48, s24
	s_cbranch_vccnz .LBB0_1028
	v_mov_b32_e32 v41, 0
	s_ashr_i32 s25, s24, 31
	v_lshl_add_u64 v[0:1], s[6:7], 0, v[40:41]
	s_lshl_b64 s[48:49], s[24:25], 12
	v_lshl_add_u64 v[2:3], v[0:1], 0, s[48:49]
	s_add_i32 s8, s24, s18
	flat_load_dwordx4 v[4:7], v[2:3] offset:1024
	flat_load_dwordx4 v[28:31], v[2:3] offset:2048
	flat_load_dwordx4 v[24:27], v[2:3] offset:3072
	flat_load_dwordx4 v[32:35], v[2:3]
	s_ashr_i32 s9, s8, 31
	s_lshl_b64 s[44:45], s[8:9], 12
	v_lshl_add_u64 v[2:3], v[0:1], 0, s[44:45]
	flat_load_dwordx4 v[36:39], v[2:3]
	flat_load_dwordx4 v[44:47], v[2:3] offset:1024
	flat_load_dwordx4 v[110:113], v[2:3] offset:2048
	flat_load_dwordx4 v[12:15], v[2:3] offset:3072
	v_readlane_b32 s14, v226, 1
	v_readlane_b32 s15, v226, 2
	s_mov_b32 s28, s14
	s_ashr_i32 s29, s14, 31
	s_add_i32 s14, s8, s18
	s_mov_b32 s8, s28
	s_ashr_i32 s15, s14, 31
	v_writelane_b32 v226, s8, 1
	s_lshl_b64 s[14:15], s[14:15], 12
	v_lshl_add_u64 v[42:43], v[0:1], 0, s[14:15]
	v_writelane_b32 v226, s9, 2
	s_lshl_b64 s[8:9], s[28:29], 12
	v_lshl_add_u64 v[108:109], v[0:1], 0, s[8:9]
	flat_load_dwordx4 v[20:23], v[42:43]
	flat_load_dwordx4 v[16:19], v[42:43] offset:1024
	flat_load_dwordx4 v[8:11], v[42:43] offset:2048
	flat_load_dwordx4 v[0:3], v[42:43] offset:3072
	s_waitcnt lgkmcnt(0)
	v_add_u32_e32 v204, 0x1000, v48
	global_load_dwordx4 v[166:169], v48, s[12:13]
	global_load_dwordx4 v[170:173], v48, s[12:13] offset:16
	global_load_dwordx4 v[174:177], v48, s[12:13] offset:2048
	global_load_dwordx4 v[178:181], v48, s[12:13] offset:2064
	global_load_dwordx4 v[182:185], v204, s[12:13]
	global_load_dwordx4 v[186:189], v204, s[12:13] offset:16
	global_load_dwordx4 v[190:193], v204, s[12:13] offset:2048
	global_load_dwordx4 v[200:203], v204, s[12:13] offset:2064
	s_mov_b32 s40, 0x358637bd
	s_mov_b32 s46, 0x3a000000
	s_mov_b32 s3, 0x800000
	v_or_b32_e32 v49, 0x1800, v48
	v_mov_b32_e32 v105, v41
	s_waitcnt vmcnt(0)
	v_mov_b32_e32 v120, v170
	v_mov_b32_e32 v121, v171
	v_mov_b32_e32 v122, v172
	v_mov_b32_e32 v123, v173
	v_mov_b32_e32 v124, v166
	v_mov_b32_e32 v125, v167
	v_mov_b32_e32 v126, v168
	v_mov_b32_e32 v127, v169
	v_lshlrev_b32_e32 v69, 16, v4
	v_and_b32_e32 v55, 0xffff0000, v29
	v_lshlrev_b32_e32 v59, 16, v28
	v_and_b32_e32 v71, 0xffff0000, v32
	v_and_b32_e32 v70, 0xffff0000, v36
	v_lshlrev_b32_e32 v63, 16, v32
	v_and_b32_e32 v67, 0xffff0000, v28
	v_lshlrev_b32_e32 v61, 16, v29
	v_lshlrev_b32_e32 v62, 16, v36
	v_pk_mul_f32 v[28:29], v[70:71], v[70:71]
	v_lshlrev_b32_e32 v65, 16, v33
	v_and_b32_e32 v77, 0xffff0000, v33
	v_lshlrev_b32_e32 v64, 16, v37
	v_pk_fma_f32 v[32:33], v[62:63], v[62:63], v[28:29]
	v_and_b32_e32 v76, 0xffff0000, v37
	v_pk_fma_f32 v[32:33], v[64:65], v[64:65], v[32:33]
	v_lshlrev_b32_e32 v73, 16, v34
	v_lshlrev_b32_e32 v72, 16, v38
	v_pk_fma_f32 v[32:33], v[76:77], v[76:77], v[32:33]
	v_and_b32_e32 v85, 0xffff0000, v34
	v_and_b32_e32 v84, 0xffff0000, v38
	v_pk_fma_f32 v[32:33], v[72:73], v[72:73], v[32:33]
	v_lshlrev_b32_e32 v83, 16, v35
	v_lshlrev_b32_e32 v82, 16, v39
	v_pk_fma_f32 v[32:33], v[84:85], v[84:85], v[32:33]
	v_and_b32_e32 v95, 0xffff0000, v35
	v_and_b32_e32 v94, 0xffff0000, v39
	v_pk_fma_f32 v[32:33], v[82:83], v[82:83], v[32:33]
	v_lshlrev_b32_e32 v68, 16, v44
	v_pk_fma_f32 v[32:33], v[94:95], v[94:95], v[32:33]
	v_and_b32_e32 v57, 0xffff0000, v4
	v_and_b32_e32 v56, 0xffff0000, v44
	v_pk_fma_f32 v[32:33], v[68:69], v[68:69], v[32:33]
	v_lshlrev_b32_e32 v81, 16, v5
	v_lshlrev_b32_e32 v80, 16, v45
	v_pk_fma_f32 v[32:33], v[56:57], v[56:57], v[32:33]
	v_and_b32_e32 v91, 0xffff0000, v5
	v_and_b32_e32 v90, 0xffff0000, v45
	v_pk_fma_f32 v[32:33], v[80:81], v[80:81], v[32:33]
	v_lshlrev_b32_e32 v87, 16, v6
	v_lshlrev_b32_e32 v86, 16, v46
	v_pk_fma_f32 v[32:33], v[90:91], v[90:91], v[32:33]
	v_and_b32_e32 v93, 0xffff0000, v6
	v_and_b32_e32 v92, 0xffff0000, v46
	v_pk_fma_f32 v[32:33], v[86:87], v[86:87], v[32:33]
	v_lshlrev_b32_e32 v89, 16, v7
	v_lshlrev_b32_e32 v88, 16, v47
	v_pk_fma_f32 v[32:33], v[92:93], v[92:93], v[32:33]
	v_and_b32_e32 v97, 0xffff0000, v7
	v_and_b32_e32 v96, 0xffff0000, v47
	v_pk_fma_f32 v[32:33], v[88:89], v[88:89], v[32:33]
	v_lshlrev_b32_e32 v58, 16, v110
	v_pk_fma_f32 v[32:33], v[96:97], v[96:97], v[32:33]
	v_and_b32_e32 v66, 0xffff0000, v110
	v_pk_fma_f32 v[32:33], v[58:59], v[58:59], v[32:33]
	v_lshlrev_b32_e32 v60, 16, v111
	v_pk_fma_f32 v[32:33], v[66:67], v[66:67], v[32:33]
	v_lshlrev_b32_e32 v43, 16, v30
	v_and_b32_e32 v79, 0xffff0000, v30
	v_lshlrev_b32_e32 v75, 16, v31
	v_and_b32_e32 v54, 0xffff0000, v111
	v_and_b32_e32 v99, 0xffff0000, v31
	v_pk_fma_f32 v[30:31], v[60:61], v[60:61], v[32:33]
	v_lshlrev_b32_e32 v42, 16, v112
	v_pk_fma_f32 v[30:31], v[54:55], v[54:55], v[30:31]
	v_and_b32_e32 v78, 0xffff0000, v112
	v_pk_fma_f32 v[30:31], v[42:43], v[42:43], v[30:31]
	v_lshlrev_b32_e32 v74, 16, v113
	v_pk_fma_f32 v[30:31], v[78:79], v[78:79], v[30:31]
	v_and_b32_e32 v100, 0xffff0000, v26
	v_and_b32_e32 v98, 0xffff0000, v113
	v_pk_fma_f32 v[30:31], v[74:75], v[74:75], v[30:31]
	v_lshlrev_b32_e32 v103, 16, v26
	v_mov_b32_e32 v102, v100
	v_pk_fma_f32 v[30:31], v[98:99], v[98:99], v[30:31]
	v_lshlrev_b32_e32 v45, 16, v24
	v_lshlrev_b32_e32 v44, 16, v12
	v_and_b32_e32 v26, 0xffff0000, v14
	v_pk_mul_f32 v[6:7], v[102:103], v[102:103]
	v_and_b32_e32 v47, 0xffff0000, v24
	v_and_b32_e32 v46, 0xffff0000, v12
	v_lshlrev_b32_e32 v50, 16, v13
	v_and_b32_e32 v24, 0xffff0000, v13
	v_pk_fma_f32 v[12:13], v[44:45], v[44:45], v[30:31]
	v_lshlrev_b32_e32 v53, 16, v14
	v_mov_b32_e32 v52, v26
	v_lshlrev_b32_e32 v51, 16, v25
	v_pk_fma_f32 v[12:13], v[46:47], v[46:47], v[12:13]
	v_mov_b32_e32 v31, v7
	v_and_b32_e32 v7, 64, v196
	v_and_b32_e32 v104, 0xffff0000, v27
	v_pk_mul_f32 v[28:29], v[52:53], v[52:53]
	v_and_b32_e32 v25, 0xffff0000, v25
	v_pk_fma_f32 v[12:13], v[50:51], v[50:51], v[12:13]
	v_and_b32_e32 v110, 0xffff0000, v15
	v_add_u32_e32 v14, 64, v7
	v_xor_b32_e32 v7, 1, v196
	v_lshlrev_b32_e32 v107, 16, v27
	v_mov_b32_e32 v106, v104
	v_pk_fma_f32 v[12:13], v[24:25], v[24:25], v[12:13]
	v_mov_b32_e32 v30, v29
	v_lshlrev_b32_e32 v113, 16, v15
	v_mov_b32_e32 v112, v110
	v_cmp_lt_i32_e32 vcc, v7, v14
	v_pk_mul_f32 v[4:5], v[106:107], v[106:107]
	v_pk_add_f32 v[12:13], v[30:31], v[12:13]
	v_pk_mul_f32 v[30:31], v[112:113], v[112:113]
	v_cndmask_b32_e32 v7, v196, v7, vcc
	v_mov_b32_e32 v29, v6
	v_lshlrev_b32_e32 v114, 2, v7
	v_pk_add_f32 v[6:7], v[28:29], v[12:13]
	v_mov_b32_e32 v12, v31
	v_mov_b32_e32 v13, v5
	v_pk_add_f32 v[6:7], v[12:13], v[6:7]
	v_mov_b32_e32 v31, v4
	v_pk_add_f32 v[4:5], v[30:31], v[6:7]
	ds_bpermute_b32 v7, v114, v5
	ds_bpermute_b32 v6, v114, v4
	v_xor_b32_e32 v12, 2, v196
	v_cmp_lt_i32_e32 vcc, v12, v14
	v_mov_b32_e32 v130, v63
	v_mov_b32_e32 v131, v71
	v_cndmask_b32_e32 v12, v196, v12, vcc
	v_lshlrev_b32_e32 v116, 2, v12
	s_waitcnt lgkmcnt(0)
	v_pk_add_f32 v[4:5], v[4:5], v[6:7]
	ds_bpermute_b32 v7, v116, v5
	ds_bpermute_b32 v6, v116, v4
	v_xor_b32_e32 v12, 4, v196
	v_cmp_lt_i32_e32 vcc, v12, v14
	v_mov_b32_e32 v132, v65
	v_mov_b32_e32 v133, v77
	v_cndmask_b32_e32 v12, v196, v12, vcc
	v_lshlrev_b32_e32 v117, 2, v12
	s_waitcnt lgkmcnt(0)
	v_pk_add_f32 v[4:5], v[4:5], v[6:7]
	ds_bpermute_b32 v7, v117, v5
	ds_bpermute_b32 v6, v117, v4
	v_xor_b32_e32 v12, 8, v196
	v_cmp_lt_i32_e32 vcc, v12, v14
	v_mov_b32_e32 v134, v87
	v_mov_b32_e32 v135, v93
	v_cndmask_b32_e32 v12, v196, v12, vcc
	v_lshlrev_b32_e32 v118, 2, v12
	s_waitcnt lgkmcnt(0)
	v_pk_add_f32 v[4:5], v[4:5], v[6:7]
	ds_bpermute_b32 v7, v118, v5
	ds_bpermute_b32 v6, v118, v4
	v_xor_b32_e32 v12, 16, v196
	v_cmp_lt_i32_e32 vcc, v12, v14
	v_mov_b32_e32 v136, v89
	v_mov_b32_e32 v137, v97
	v_cndmask_b32_e32 v12, v196, v12, vcc
	v_lshlrev_b32_e32 v119, 2, v12
	s_waitcnt lgkmcnt(0)
	v_pk_add_f32 v[4:5], v[4:5], v[6:7]
	ds_bpermute_b32 v7, v119, v5
	ds_bpermute_b32 v6, v119, v4
	v_xor_b32_e32 v12, 32, v196
	v_cmp_lt_i32_e32 vcc, v12, v14
	v_and_b32_e32 v101, s0, v27
	v_pk_mov_b32 v[100:101], v[102:103], v[100:101] op_sel:[1,0]
	v_cndmask_b32_e32 v12, v196, v12, vcc
	v_lshlrev_b32_e32 v115, 2, v12
	s_waitcnt lgkmcnt(0)
	v_pk_add_f32 v[12:13], v[4:5], v[6:7]
	ds_bpermute_b32 v129, v115, v13
	ds_bpermute_b32 v128, v115, v12
	flat_load_dwordx4 v[36:39], v[108:109]
	flat_load_dwordx4 v[32:35], v[108:109] offset:1024
	flat_load_dwordx4 v[28:31], v[108:109] offset:2048
	flat_load_dwordx4 v[4:7], v[108:109] offset:3072
	v_mov_b64_e32 v[108:109], s[40:41]
	s_add_u32 s40, s10, s48
	s_addc_u32 s41, s11, s49
	s_waitcnt lgkmcnt(0)
	v_pk_add_f32 v[12:13], v[12:13], v[128:129]
	v_lshl_add_u64 v[128:129], s[40:41], 0, v[40:41]
	v_pk_fma_f32 v[12:13], v[12:13], s[46:47], v[108:109] op_sel_hi:[1,0,0]
	v_pk_mov_b32 v[102:103], v[106:107], v[104:105] op_sel:[1,0]
	v_mul_f32_e32 v14, 0x4b800000, v13
	v_cmp_gt_f32_e32 vcc, s3, v13
	s_add_u32 s40, s10, s44
	v_mov_b32_e32 v63, v70
	v_cndmask_b32_e32 v13, v13, v14, vcc
	v_rsq_f32_e32 v13, v13
	v_mov_b32_e32 v65, v76
	s_addc_u32 s41, s11, s45
	v_mov_b32_e32 v87, v92
	v_mul_f32_e32 v14, 0x45800000, v13
	v_cndmask_b32_e32 v14, v13, v14, vcc
	v_pk_mul_f32 v[130:131], v[130:131], v[14:15] op_sel_hi:[1,0]
	v_pk_mul_f32 v[132:133], v[132:133], v[14:15] op_sel_hi:[1,0]
	v_pk_mul_f32 v[124:125], v[124:125], v[130:131]
	v_pk_mul_f32 v[126:127], v[126:127], v[132:133]
	v_mov_b32_e32 v130, v73
	v_mov_b32_e32 v131, v85
	v_mov_b32_e32 v132, v83
	v_mov_b32_e32 v133, v95
	v_pk_mul_f32 v[130:131], v[130:131], v[14:15] op_sel_hi:[1,0]
	v_pk_mul_f32 v[132:133], v[132:133], v[14:15] op_sel_hi:[1,0]
	v_pk_mul_f32 v[134:135], v[134:135], v[14:15] op_sel_hi:[1,0]
	v_pk_mul_f32 v[132:133], v[122:123], v[132:133]
	v_pk_mul_f32 v[122:123], v[120:121], v[130:131]
	v_cvt_pk_bf16_f32 v120, v124, v125
	v_cvt_pk_bf16_f32 v121, v126, v127
	v_mov_b32_e32 v130, v69
	v_cvt_pk_bf16_f32 v122, v122, v123
	v_cvt_pk_bf16_f32 v123, v132, v133
	global_store_dwordx4 v[128:129], v[120:123], off
	s_nop 1
	s_nop 0
	v_mov_b32_e32 v131, v57
	v_mov_b32_e32 v132, v81
	v_mov_b32_e32 v133, v91
	v_pk_mul_f32 v[130:131], v[130:131], v[14:15] op_sel_hi:[1,0]
	v_pk_mul_f32 v[132:133], v[132:133], v[14:15] op_sel_hi:[1,0]
	v_pk_mul_f32 v[136:137], v[136:137], v[14:15] op_sel_hi:[1,0]
	v_or_b32_e32 v13, 0x1000, v48
	v_pk_mul_f32 v[100:101], v[14:15], v[100:101] op_sel_hi:[0,1]
	v_pk_mul_f32 v[102:103], v[14:15], v[102:103] op_sel_hi:[0,1]
	v_cmp_gt_f32_e32 vcc, s3, v12
	v_mov_b32_e32 v73, v84
	v_mov_b32_e32 v83, v94
	v_mov_b32_e32 v69, v56
	v_mov_b32_e32 v81, v90
	v_mov_b32_e32 v89, v96
	v_and_b32_e32 v97, 0xffff0000, v20
	v_lshlrev_b32_e32 v85, 16, v21
	v_and_b32_e32 v91, 0xffff0000, v21
	v_and_b32_e32 v93, 0xffff0000, v22
	v_and_b32_e32 v27, s0, v15
	v_and_b32_e32 v95, 0xffff0000, v23
	v_mov_b32_e32 v111, v41
	s_add_u32 s14, s10, s14
	s_addc_u32 s15, s11, s15
	s_add_u32 s8, s10, s8
	s_addc_u32 s9, s11, s9
	s_waitcnt vmcnt(1)
	v_mov_b32_e32 v120, v174
	v_mov_b32_e32 v121, v175
	v_mov_b32_e32 v122, v176
	v_mov_b32_e32 v123, v177
	v_mov_b32_e32 v124, v178
	v_mov_b32_e32 v125, v179
	v_mov_b32_e32 v126, v180
	v_mov_b32_e32 v127, v181
	v_and_b32_e32 v96, 0xffff0000, v36
	v_lshlrev_b32_e32 v84, 16, v37
	v_and_b32_e32 v90, 0xffff0000, v37
	v_and_b32_e32 v92, 0xffff0000, v38
	v_and_b32_e32 v94, 0xffff0000, v39
	v_pk_mul_f32 v[122:123], v[122:123], v[132:133]
	v_pk_mul_f32 v[120:121], v[120:121], v[130:131]
	v_pk_mul_f32 v[126:127], v[126:127], v[136:137]
	v_pk_mul_f32 v[124:125], v[124:125], v[134:135]
	v_cvt_pk_bf16_f32 v120, v120, v121
	v_cvt_pk_bf16_f32 v121, v122, v123
	v_mov_b32_e32 v130, v59
	v_cvt_pk_bf16_f32 v122, v124, v125
	v_cvt_pk_bf16_f32 v123, v126, v127
	global_store_dwordx4 v[128:129], v[120:123], off offset:1024
	s_nop 1
	s_nop 0
	v_mov_b32_e32 v131, v67
	v_mov_b32_e32 v132, v61
	v_mov_b32_e32 v133, v55
	v_mov_b32_e32 v134, v43
	v_mov_b32_e32 v135, v79
	v_mov_b32_e32 v136, v75
	v_mov_b32_e32 v137, v99
	v_pk_mul_f32 v[130:131], v[130:131], v[14:15] op_sel_hi:[1,0]
	v_pk_mul_f32 v[132:133], v[132:133], v[14:15] op_sel_hi:[1,0]
	v_pk_mul_f32 v[134:135], v[134:135], v[14:15] op_sel_hi:[1,0]
	v_pk_mul_f32 v[136:137], v[136:137], v[14:15] op_sel_hi:[1,0]
	v_mov_b32_e32 v59, v66
	v_mov_b32_e32 v61, v54
	v_mov_b32_e32 v43, v78
	v_mov_b32_e32 v75, v98
	v_and_b32_e32 v98, 0xffff0000, v2
	v_and_b32_e32 v66, 0xffff0000, v30
	v_and_b32_e32 v67, 0xffff0000, v10
	v_and_b32_e32 v79, 0xffff0000, v19
	v_and_b32_e32 v78, 0xffff0000, v35
	v_and_b32_e32 v99, s0, v3
	v_mov_b32_e32 v120, v182
	v_mov_b32_e32 v121, v183
	v_mov_b32_e32 v122, v184
	v_mov_b32_e32 v123, v185
	v_mov_b32_e32 v124, v186
	v_mov_b32_e32 v125, v187
	v_mov_b32_e32 v126, v188
	v_mov_b32_e32 v127, v189
	v_pk_mul_f32 v[122:123], v[132:133], v[122:123]
	v_pk_mul_f32 v[120:121], v[130:131], v[120:121]
	v_pk_mul_f32 v[126:127], v[136:137], v[126:127]
	v_pk_mul_f32 v[124:125], v[134:135], v[124:125]
	v_cvt_pk_bf16_f32 v120, v120, v121
	v_cvt_pk_bf16_f32 v121, v122, v123
	v_mov_b32_e32 v130, v45
	v_cvt_pk_bf16_f32 v122, v124, v125
	v_cvt_pk_bf16_f32 v123, v126, v127
	global_store_dwordx4 v[128:129], v[120:123], off offset:2048
	s_nop 1
	s_nop 0
	v_mov_b32_e32 v131, v47
	v_mov_b32_e32 v132, v51
	v_mov_b32_e32 v133, v25
	v_pk_mul_f32 v[104:105], v[130:131], v[14:15] op_sel_hi:[1,0]
	v_pk_mul_f32 v[106:107], v[132:133], v[14:15] op_sel_hi:[1,0]
	v_mul_f32_e32 v14, 0x4b800000, v12
	v_cndmask_b32_e32 v12, v12, v14, vcc
	v_rsq_f32_e32 v12, v12
	v_lshlrev_b32_e32 v15, 16, v0
	v_mov_b32_e32 v45, v46
	v_mov_b32_e32 v51, v24
	v_mul_f32_e32 v14, 0x45800000, v12
	v_mov_b32_e32 v120, v190
	v_mov_b32_e32 v121, v191
	v_mov_b32_e32 v122, v192
	v_mov_b32_e32 v123, v193
	v_mov_b32_e32 v124, v200
	v_mov_b32_e32 v125, v201
	v_mov_b32_e32 v126, v202
	v_mov_b32_e32 v127, v203
	v_pk_mul_f32 v[104:105], v[104:105], v[120:121]
	v_pk_mul_f32 v[120:121], v[102:103], v[126:127]
	v_pk_mul_f32 v[102:103], v[100:101], v[124:125]
	v_pk_mul_f32 v[106:107], v[106:107], v[122:123]
	v_cvt_pk_bf16_f32 v100, v104, v105
	v_lshlrev_b32_e32 v105, 16, v2
	v_cvt_pk_bf16_f32 v101, v106, v107
	v_cvt_pk_bf16_f32 v102, v102, v103
	v_cvt_pk_bf16_f32 v103, v120, v121
	global_store_dwordx4 v[128:129], v[100:103], off offset:3072
	s_nop 1
	s_nop 0
	v_cndmask_b32_e32 v128, v12, v14, vcc
	v_pk_mul_f32 v[62:63], v[62:63], v[128:129] op_sel_hi:[1,0]
	v_pk_mul_f32 v[64:65], v[64:65], v[128:129] op_sel_hi:[1,0]
	v_lshl_add_u64 v[106:107], s[40:41], 0, v[40:41]
	v_pk_mul_f32 v[70:71], v[72:73], v[128:129] op_sel_hi:[1,0]
	v_pk_mul_f32 v[72:73], v[82:83], v[128:129] op_sel_hi:[1,0]
	v_pk_mul_f32 v[56:57], v[68:69], v[128:129] op_sel_hi:[1,0]
	v_pk_mul_f32 v[68:69], v[80:81], v[128:129] op_sel_hi:[1,0]
	v_pk_mul_f32 v[76:77], v[86:87], v[128:129] op_sel_hi:[1,0]
	v_pk_mul_f32 v[80:81], v[88:89], v[128:129] op_sel_hi:[1,0]
	v_lshlrev_b32_e32 v82, 16, v36
	v_pk_mul_f32 v[36:37], v[60:61], v[128:129] op_sel_hi:[1,0]
	v_pk_mul_f32 v[42:43], v[42:43], v[128:129] op_sel_hi:[1,0]
	v_pk_mul_f32 v[54:55], v[74:75], v[128:129] op_sel_hi:[1,0]
	v_lshlrev_b32_e32 v83, 16, v20
	v_and_b32_e32 v75, 0xffff0000, v8
	v_lshlrev_b32_e32 v86, 16, v38
	v_lshlrev_b32_e32 v87, 16, v22
	v_lshlrev_b32_e32 v88, 16, v39
	v_lshlrev_b32_e32 v89, 16, v23
	v_and_b32_e32 v12, 0xffff0000, v6
	v_lshlrev_b32_e32 v38, 16, v30
	v_and_b32_e32 v74, 0xffff0000, v28
	v_lshlrev_b32_e32 v14, 16, v4
	v_and_b32_e32 v30, 0xffff0000, v4
	v_lshlrev_b32_e32 v4, 16, v5
	v_lshlrev_b32_e32 v39, 16, v10
	v_mov_b32_e32 v104, v98
	v_mov_b32_e32 v100, v166
	v_mov_b32_e32 v101, v167
	v_mov_b32_e32 v102, v168
	v_mov_b32_e32 v103, v169
	v_mov_b32_e32 v120, v170
	v_mov_b32_e32 v121, v171
	v_mov_b32_e32 v122, v172
	v_mov_b32_e32 v123, v173
	v_pk_mul_f32 v[64:65], v[64:65], v[102:103]
	v_pk_mul_f32 v[62:63], v[62:63], v[100:101]
	v_pk_mul_f32 v[72:73], v[72:73], v[122:123]
	v_pk_mul_f32 v[70:71], v[70:71], v[120:121]
	v_cvt_pk_bf16_f32 v62, v62, v63
	v_cvt_pk_bf16_f32 v63, v64, v65
	s_nop 0
	v_cvt_pk_bf16_f32 v64, v70, v71
	v_cvt_pk_bf16_f32 v65, v72, v73
	global_store_dwordx4 v[106:107], v[62:65], off
	s_nop 1
	s_nop 0
	v_mov_b32_e32 v62, v174
	v_mov_b32_e32 v63, v175
	v_mov_b32_e32 v64, v176
	v_mov_b32_e32 v65, v177
	v_mov_b32_e32 v70, v178
	v_mov_b32_e32 v71, v179
	v_mov_b32_e32 v72, v180
	v_mov_b32_e32 v73, v181
	v_pk_mul_f32 v[64:65], v[68:69], v[64:65]
	v_pk_mul_f32 v[56:57], v[56:57], v[62:63]
	v_pk_mul_f32 v[68:69], v[80:81], v[72:73]
	v_pk_mul_f32 v[70:71], v[76:77], v[70:71]
	v_cvt_pk_bf16_f32 v62, v56, v57
	v_cvt_pk_bf16_f32 v63, v64, v65
	v_and_b32_e32 v76, 0xffff0000, v32
	v_cvt_pk_bf16_f32 v64, v70, v71
	v_cvt_pk_bf16_f32 v65, v68, v69
	global_store_dwordx4 v[106:107], v[62:65], off offset:1024
	s_nop 1
	v_lshlrev_b32_e32 v62, 16, v32
	v_lshlrev_b32_e32 v64, 16, v33
	v_and_b32_e32 v80, 0xffff0000, v33
	v_pk_mul_f32 v[32:33], v[58:59], v[128:129] op_sel_hi:[1,0]
	v_and_b32_e32 v57, 0xffff0000, v9
	v_lshlrev_b32_e32 v68, 16, v34
	v_and_b32_e32 v72, 0xffff0000, v34
	v_and_b32_e32 v34, 0xffff0000, v7
	v_and_b32_e32 v56, 0xffff0000, v29
	v_lshlrev_b32_e32 v63, 16, v16
	v_and_b32_e32 v77, 0xffff0000, v16
	v_lshlrev_b32_e32 v65, 16, v17
	v_and_b32_e32 v81, 0xffff0000, v17
	v_lshlrev_b32_e32 v69, 16, v18
	v_and_b32_e32 v73, 0xffff0000, v18
	v_lshlrev_b32_e32 v71, 16, v19
	v_pk_mov_b32 v[16:17], v[112:113], v[110:111] op_sel:[1,0]
	v_pk_mul_f32 v[18:19], v[104:105], v[104:105]
	v_pk_mul_f32 v[16:17], v[128:129], v[16:17] op_sel_hi:[0,1]
	v_mov_b32_e32 v23, v19
	v_lshlrev_b32_e32 v70, 16, v35
	v_mov_b32_e32 v35, v41
	v_mov_b32_e32 v100, v182
	v_mov_b32_e32 v101, v183
	v_mov_b32_e32 v102, v184
	v_mov_b32_e32 v103, v185
	v_mov_b32_e32 v120, v186
	v_mov_b32_e32 v121, v187
	v_mov_b32_e32 v122, v188
	v_mov_b32_e32 v123, v189
	v_pk_mul_f32 v[36:37], v[36:37], v[102:103]
	v_pk_mul_f32 v[32:33], v[32:33], v[100:101]
	v_pk_mul_f32 v[54:55], v[54:55], v[122:123]
	v_pk_mul_f32 v[42:43], v[42:43], v[120:121]
	v_cvt_pk_bf16_f32 v58, v32, v33
	v_cvt_pk_bf16_f32 v59, v36, v37
	v_and_b32_e32 v100, 0xffff0000, v3
	v_cvt_pk_bf16_f32 v60, v42, v43
	v_cvt_pk_bf16_f32 v61, v54, v55
	global_store_dwordx4 v[106:107], v[58:61], off offset:2048
	s_nop 1
	v_lshlrev_b32_e32 v43, 16, v8
	v_lshlrev_b32_e32 v55, 16, v9
	v_pk_mul_f32 v[8:9], v[96:97], v[96:97]
	v_lshlrev_b32_e32 v37, 16, v7
	v_pk_fma_f32 v[8:9], v[82:83], v[82:83], v[8:9]
	v_mov_b32_e32 v36, v34
	v_pk_fma_f32 v[8:9], v[84:85], v[84:85], v[8:9]
	v_lshlrev_b32_e32 v103, 16, v3
	v_pk_fma_f32 v[8:9], v[90:91], v[90:91], v[8:9]
	v_mov_b32_e32 v102, v100
	v_pk_fma_f32 v[8:9], v[86:87], v[86:87], v[8:9]
	v_lshlrev_b32_e32 v42, 16, v28
	v_pk_fma_f32 v[8:9], v[92:93], v[92:93], v[8:9]
	v_lshlrev_b32_e32 v54, 16, v29
	v_pk_fma_f32 v[8:9], v[88:89], v[88:89], v[8:9]
	v_lshlrev_b32_e32 v29, 16, v6
	v_lshlrev_b32_e32 v58, 16, v31
	v_and_b32_e32 v60, 0xffff0000, v31
	v_and_b32_e32 v32, 0xffff0000, v5
	v_mov_b32_e32 v28, v12
	v_lshlrev_b32_e32 v59, 16, v11
	v_and_b32_e32 v61, 0xffff0000, v11
	v_and_b32_e32 v31, 0xffff0000, v0
	v_lshlrev_b32_e32 v5, 16, v1
	v_and_b32_e32 v33, 0xffff0000, v1
	v_pk_mul_f32 v[0:1], v[36:37], v[36:37]
	v_pk_mov_b32 v[10:11], v[52:53], v[26:27] op_sel:[1,0]
	v_pk_mul_f32 v[52:53], v[102:103], v[102:103]
	v_pk_fma_f32 v[8:9], v[94:95], v[94:95], v[8:9]
	v_pk_mul_f32 v[20:21], v[28:29], v[28:29]
	v_mov_b32_e32 v26, v1
	v_mov_b32_e32 v27, v53
	v_mov_b32_e32 v1, v52
	v_pk_fma_f32 v[52:53], v[62:63], v[62:63], v[8:9]
	v_pk_mul_f32 v[8:9], v[44:45], v[128:129] op_sel_hi:[1,0]
	v_pk_mul_f32 v[10:11], v[128:129], v[10:11] op_sel_hi:[0,1]
	v_mov_b32_e32 v22, v21
	v_mov_b32_e32 v21, v18
	v_pk_mul_f32 v[18:19], v[50:51], v[128:129] op_sel_hi:[1,0]
	v_pk_fma_f32 v[24:25], v[76:77], v[76:77], v[52:53]
	v_mov_b32_e32 v44, v87
	v_pk_fma_f32 v[24:25], v[64:65], v[64:65], v[24:25]
	v_mov_b32_e32 v45, v93
	v_pk_fma_f32 v[24:25], v[80:81], v[80:81], v[24:25]
	v_mov_b32_e32 v101, v41
	v_pk_fma_f32 v[24:25], v[68:69], v[68:69], v[24:25]
	v_mov_b32_e32 v87, v92
	v_pk_fma_f32 v[24:25], v[72:73], v[72:73], v[24:25]
	v_mov_b32_e32 v120, v200
	v_mov_b32_e32 v121, v201
	v_mov_b32_e32 v122, v202
	v_mov_b32_e32 v123, v203
	v_mov_b32_e32 v124, v190
	v_mov_b32_e32 v125, v191
	v_mov_b32_e32 v126, v192
	v_mov_b32_e32 v127, v193
	v_pk_mul_f32 v[10:11], v[10:11], v[120:121]
	v_pk_mul_f32 v[8:9], v[8:9], v[124:125]
	v_pk_mul_f32 v[18:19], v[18:19], v[126:127]
	v_pk_mul_f32 v[16:17], v[16:17], v[122:123]
	v_cvt_pk_bf16_f32 v8, v8, v9
	v_cvt_pk_bf16_f32 v9, v18, v19
	v_cvt_pk_bf16_f32 v10, v10, v11
	v_pk_fma_f32 v[24:25], v[70:71], v[70:71], v[24:25]
	v_cvt_pk_bf16_f32 v11, v16, v17
	global_store_dwordx4 v[106:107], v[8:11], off offset:3072
	s_nop 1
	s_nop 0
	v_pk_fma_f32 v[24:25], v[78:79], v[78:79], v[24:25]
	s_nop 0
	v_pk_fma_f32 v[24:25], v[42:43], v[42:43], v[24:25]
	s_nop 0
	v_pk_fma_f32 v[24:25], v[74:75], v[74:75], v[24:25]
	s_nop 0
	v_pk_fma_f32 v[24:25], v[54:55], v[54:55], v[24:25]
	s_nop 0
	v_pk_fma_f32 v[24:25], v[56:57], v[56:57], v[24:25]
	s_nop 0
	v_pk_fma_f32 v[24:25], v[38:39], v[38:39], v[24:25]
	s_nop 0
	v_pk_fma_f32 v[24:25], v[66:67], v[66:67], v[24:25]
	s_nop 0
	v_pk_fma_f32 v[24:25], v[58:59], v[58:59], v[24:25]
	s_nop 0
	v_pk_fma_f32 v[24:25], v[60:61], v[60:61], v[24:25]
	s_nop 0
	v_pk_fma_f32 v[24:25], v[14:15], v[14:15], v[24:25]
	s_nop 0
	v_pk_fma_f32 v[24:25], v[30:31], v[30:31], v[24:25]
	s_nop 0
	v_pk_fma_f32 v[24:25], v[4:5], v[4:5], v[24:25]
	s_nop 0
	v_pk_fma_f32 v[24:25], v[32:33], v[32:33], v[24:25]
	s_nop 0
	v_pk_add_f32 v[22:23], v[22:23], v[24:25]
	v_mov_b32_e32 v24, v83
	v_pk_add_f32 v[20:21], v[20:21], v[22:23]
	v_mov_b32_e32 v25, v97
	v_pk_add_f32 v[20:21], v[26:27], v[20:21]
	v_mov_b32_e32 v26, v85
	v_pk_add_f32 v[0:1], v[0:1], v[20:21]
	ds_bpermute_b32 v21, v114, v1
	ds_bpermute_b32 v20, v114, v0
	v_mov_b32_e32 v27, v91
	v_lshl_add_u64 v[22:23], s[14:15], 0, v[40:41]
	v_mov_b32_e32 v83, v96
	v_mov_b32_e32 v85, v90
	s_waitcnt lgkmcnt(0)
	v_pk_add_f32 v[0:1], v[0:1], v[20:21]
	ds_bpermute_b32 v21, v116, v1
	ds_bpermute_b32 v20, v116, v0
	s_waitcnt lgkmcnt(0)
	v_pk_add_f32 v[0:1], v[0:1], v[20:21]
	ds_bpermute_b32 v21, v117, v1
	ds_bpermute_b32 v20, v117, v0
	s_waitcnt lgkmcnt(0)
	v_pk_add_f32 v[0:1], v[0:1], v[20:21]
	ds_bpermute_b32 v21, v118, v1
	ds_bpermute_b32 v20, v118, v0
	s_waitcnt lgkmcnt(0)
	v_pk_add_f32 v[0:1], v[0:1], v[20:21]
	ds_bpermute_b32 v21, v119, v1
	ds_bpermute_b32 v20, v119, v0
	s_waitcnt lgkmcnt(0)
	v_pk_add_f32 v[0:1], v[0:1], v[20:21]
	ds_bpermute_b32 v21, v115, v1
	ds_bpermute_b32 v20, v115, v0
	s_waitcnt lgkmcnt(0)
	v_pk_add_f32 v[0:1], v[0:1], v[20:21]
	s_nop 0
	v_pk_fma_f32 v[20:21], v[0:1], s[46:47], v[108:109] op_sel_hi:[1,0,0]
	v_mov_b32_e32 v1, v95
	v_mul_f32_e32 v0, 0x4b800000, v21
	v_cmp_gt_f32_e32 vcc, s3, v21
	s_nop 1
	v_cndmask_b32_e32 v0, v21, v0, vcc
	v_rsq_f32_e32 v2, v0
	v_mov_b32_e32 v0, v89
	v_mov_b32_e32 v89, v94
	v_mul_f32_e32 v6, 0x45800000, v2
	v_cndmask_b32_e32 v2, v2, v6, vcc
	v_pk_mul_f32 v[44:45], v[44:45], v[2:3] op_sel_hi:[1,0]
	v_pk_mul_f32 v[0:1], v[0:1], v[2:3] op_sel_hi:[1,0]
	v_pk_mul_f32 v[24:25], v[24:25], v[2:3] op_sel_hi:[1,0]
	v_pk_mul_f32 v[26:27], v[26:27], v[2:3] op_sel_hi:[1,0]
	v_mov_b32_e32 v8, v170
	v_mov_b32_e32 v9, v171
	v_mov_b32_e32 v10, v172
	v_mov_b32_e32 v11, v173
	v_mov_b32_e32 v16, v166
	v_mov_b32_e32 v17, v167
	v_mov_b32_e32 v18, v168
	v_mov_b32_e32 v19, v169
	v_pk_mul_f32 v[0:1], v[0:1], v[10:11]
	v_pk_mul_f32 v[10:11], v[44:45], v[8:9]
	v_pk_mul_f32 v[18:19], v[26:27], v[18:19]
	v_pk_mul_f32 v[16:17], v[24:25], v[16:17]
	v_mov_b32_e32 v24, v65
	v_cvt_pk_bf16_f32 v8, v16, v17
	v_cvt_pk_bf16_f32 v9, v18, v19
	v_cvt_pk_bf16_f32 v10, v10, v11
	v_cvt_pk_bf16_f32 v11, v0, v1
	global_store_dwordx4 v[22:23], v[8:11], off
	s_nop 1
	s_nop 0
	v_mov_b32_e32 v25, v81
	v_mov_b32_e32 v0, v63
	v_mov_b32_e32 v1, v77
	v_mov_b32_e32 v26, v69
	v_mov_b32_e32 v27, v73
	v_mov_b32_e32 v44, v71
	v_mov_b32_e32 v45, v79
	v_pk_mul_f32 v[24:25], v[24:25], v[2:3] op_sel_hi:[1,0]
	v_pk_mul_f32 v[0:1], v[0:1], v[2:3] op_sel_hi:[1,0]
	v_pk_mul_f32 v[26:27], v[26:27], v[2:3] op_sel_hi:[1,0]
	v_pk_mul_f32 v[44:45], v[44:45], v[2:3] op_sel_hi:[1,0]
	v_cmp_gt_f32_e32 vcc, s3, v20
	v_mov_b32_e32 v63, v76
	v_mov_b32_e32 v65, v80
	v_mov_b32_e32 v69, v72
	v_mov_b32_e32 v71, v78
	s_lshl_b32 s3, s26, 5
	s_add_i32 s48, s24, s3
	v_mov_b32_e32 v8, v174
	v_mov_b32_e32 v9, v175
	v_mov_b32_e32 v10, v176
	v_mov_b32_e32 v11, v177
	v_mov_b32_e32 v16, v178
	v_mov_b32_e32 v17, v179
	v_mov_b32_e32 v18, v180
	v_mov_b32_e32 v19, v181
	v_pk_mul_f32 v[10:11], v[24:25], v[10:11]
	v_pk_mul_f32 v[0:1], v[0:1], v[8:9]
	v_pk_mul_f32 v[18:19], v[44:45], v[18:19]
	v_pk_mul_f32 v[16:17], v[26:27], v[16:17]
	v_cvt_pk_bf16_f32 v8, v0, v1
	v_cvt_pk_bf16_f32 v9, v10, v11
	v_mov_b32_e32 v24, v55
	v_cvt_pk_bf16_f32 v10, v16, v17
	v_cvt_pk_bf16_f32 v11, v18, v19
	global_store_dwordx4 v[22:23], v[8:11], off offset:1024
	s_nop 1
	s_nop 0
	v_mov_b32_e32 v25, v57
	v_mov_b32_e32 v0, v43
	v_mov_b32_e32 v1, v75
	v_mov_b32_e32 v26, v39
	v_mov_b32_e32 v27, v67
	v_mov_b32_e32 v44, v59
	v_mov_b32_e32 v45, v61
	v_pk_mul_f32 v[24:25], v[24:25], v[2:3] op_sel_hi:[1,0]
	v_pk_mul_f32 v[0:1], v[0:1], v[2:3] op_sel_hi:[1,0]
	v_pk_mul_f32 v[26:27], v[26:27], v[2:3] op_sel_hi:[1,0]
	v_pk_mul_f32 v[44:45], v[44:45], v[2:3] op_sel_hi:[1,0]
	v_mov_b32_e32 v43, v74
	v_mov_b32_e32 v55, v56
	v_mov_b32_e32 v39, v66
	v_mov_b32_e32 v59, v60
	v_mov_b32_e32 v8, v182
	v_mov_b32_e32 v9, v183
	v_mov_b32_e32 v10, v184
	v_mov_b32_e32 v11, v185
	v_mov_b32_e32 v16, v186
	v_mov_b32_e32 v17, v187
	v_mov_b32_e32 v18, v188
	v_mov_b32_e32 v19, v189
	v_pk_mul_f32 v[10:11], v[24:25], v[10:11]
	v_pk_mul_f32 v[0:1], v[0:1], v[8:9]
	v_pk_mul_f32 v[18:19], v[44:45], v[18:19]
	v_pk_mul_f32 v[16:17], v[26:27], v[16:17]
	v_cvt_pk_bf16_f32 v8, v0, v1
	v_cvt_pk_bf16_f32 v9, v10, v11
	v_mov_b32_e32 v0, v15
	v_cvt_pk_bf16_f32 v10, v16, v17
	v_cvt_pk_bf16_f32 v11, v18, v19
	global_store_dwordx4 v[22:23], v[8:11], off offset:2048
	s_nop 1
	s_nop 0
	v_mov_b32_e32 v1, v31
	v_mov_b32_e32 v24, v5
	v_mov_b32_e32 v25, v33
	v_pk_mov_b32 v[26:27], v[104:105], v[98:99] op_sel:[1,0]
	v_pk_mov_b32 v[44:45], v[102:103], v[100:101] op_sel:[1,0]
	v_pk_mul_f32 v[0:1], v[0:1], v[2:3] op_sel_hi:[1,0]
	v_pk_mul_f32 v[24:25], v[24:25], v[2:3] op_sel_hi:[1,0]
	v_pk_mul_f32 v[26:27], v[2:3], v[26:27] op_sel_hi:[0,1]
	v_pk_mul_f32 v[2:3], v[2:3], v[44:45] op_sel_hi:[0,1]
	v_mul_f32_e32 v5, 0x4b800000, v20
	v_cndmask_b32_e32 v5, v20, v5, vcc
	v_rsq_f32_e32 v5, v5
	v_mov_b32_e32 v15, v30
	v_mul_f32_e32 v6, 0x45800000, v5
	v_cndmask_b32_e32 v6, v5, v6, vcc
	v_pk_mul_f32 v[20:21], v[84:85], v[6:7] op_sel_hi:[1,0]
	v_mov_b32_e32 v5, v32
	v_pk_mul_f32 v[14:15], v[14:15], v[6:7] op_sel_hi:[1,0]
	v_pk_mul_f32 v[4:5], v[4:5], v[6:7] op_sel_hi:[1,0]
	v_mov_b32_e32 v8, v190
	v_mov_b32_e32 v9, v191
	v_mov_b32_e32 v10, v192
	v_mov_b32_e32 v11, v193
	v_mov_b32_e32 v16, v200
	v_mov_b32_e32 v17, v201
	v_mov_b32_e32 v18, v202
	v_mov_b32_e32 v19, v203
	v_pk_mul_f32 v[0:1], v[0:1], v[8:9]
	v_pk_mul_f32 v[8:9], v[2:3], v[18:19]
	v_pk_mul_f32 v[2:3], v[26:27], v[16:17]
	v_pk_mul_f32 v[10:11], v[24:25], v[10:11]
	v_cvt_pk_bf16_f32 v0, v0, v1
	v_pk_mul_f32 v[18:19], v[82:83], v[6:7] op_sel_hi:[1,0]
	v_cvt_pk_bf16_f32 v1, v10, v11
	v_cvt_pk_bf16_f32 v2, v2, v3
	v_cvt_pk_bf16_f32 v3, v8, v9
	global_store_dwordx4 v[22:23], v[0:3], off offset:3072
	s_nop 1
	s_nop 0
	v_lshl_add_u64 v[16:17], s[8:9], 0, v[40:41]
	v_pk_mul_f32 v[22:23], v[86:87], v[6:7] op_sel_hi:[1,0]
	v_pk_mul_f32 v[24:25], v[88:89], v[6:7] op_sel_hi:[1,0]
	v_mov_b32_e32 v0, v166
	v_mov_b32_e32 v1, v167
	v_mov_b32_e32 v2, v168
	v_mov_b32_e32 v3, v169
	v_mov_b32_e32 v8, v170
	v_mov_b32_e32 v9, v171
	v_mov_b32_e32 v10, v172
	v_mov_b32_e32 v11, v173
	v_pk_mul_f32 v[2:3], v[20:21], v[2:3]
	v_pk_mul_f32 v[0:1], v[18:19], v[0:1]
	v_pk_mul_f32 v[10:11], v[24:25], v[10:11]
	v_pk_mul_f32 v[8:9], v[22:23], v[8:9]
	v_cvt_pk_bf16_f32 v0, v0, v1
	v_cvt_pk_bf16_f32 v1, v2, v3
	v_pk_mul_f32 v[18:19], v[62:63], v[6:7] op_sel_hi:[1,0]
	v_cvt_pk_bf16_f32 v2, v8, v9
	v_cvt_pk_bf16_f32 v3, v10, v11
	global_store_dwordx4 v[16:17], v[0:3], off
	s_nop 1
	s_nop 0
	v_pk_mul_f32 v[20:21], v[64:65], v[6:7] op_sel_hi:[1,0]
	v_pk_mul_f32 v[22:23], v[68:69], v[6:7] op_sel_hi:[1,0]
	v_pk_mul_f32 v[24:25], v[70:71], v[6:7] op_sel_hi:[1,0]
	v_mov_b32_e32 v0, v174
	v_mov_b32_e32 v1, v175
	v_mov_b32_e32 v2, v176
	v_mov_b32_e32 v3, v177
	v_mov_b32_e32 v8, v178
	v_mov_b32_e32 v9, v179
	v_mov_b32_e32 v10, v180
	v_mov_b32_e32 v11, v181
	v_pk_mul_f32 v[2:3], v[20:21], v[2:3]
	v_pk_mul_f32 v[0:1], v[18:19], v[0:1]
	v_pk_mul_f32 v[10:11], v[24:25], v[10:11]
	v_pk_mul_f32 v[8:9], v[22:23], v[8:9]
	v_cvt_pk_bf16_f32 v0, v0, v1
	v_cvt_pk_bf16_f32 v1, v2, v3
	v_pk_mul_f32 v[18:19], v[42:43], v[6:7] op_sel_hi:[1,0]
	v_cvt_pk_bf16_f32 v2, v8, v9
	v_cvt_pk_bf16_f32 v3, v10, v11
	global_store_dwordx4 v[16:17], v[0:3], off offset:1024
	s_nop 1
	s_nop 0
	v_pk_mul_f32 v[20:21], v[54:55], v[6:7] op_sel_hi:[1,0]
	v_pk_mul_f32 v[22:23], v[38:39], v[6:7] op_sel_hi:[1,0]
	v_pk_mul_f32 v[24:25], v[58:59], v[6:7] op_sel_hi:[1,0]
	v_and_b32_e32 v13, s0, v7
	v_pk_mov_b32 v[12:13], v[28:29], v[12:13] op_sel:[1,0]
	v_mov_b32_e32 v0, v182
	v_mov_b32_e32 v1, v183
	v_mov_b32_e32 v2, v184
	v_mov_b32_e32 v3, v185
	v_mov_b32_e32 v8, v186
	v_mov_b32_e32 v9, v187
	v_mov_b32_e32 v10, v188
	v_mov_b32_e32 v11, v189
	v_pk_mul_f32 v[2:3], v[20:21], v[2:3]
	v_pk_mul_f32 v[0:1], v[18:19], v[0:1]
	v_pk_mul_f32 v[10:11], v[24:25], v[10:11]
	v_pk_mul_f32 v[8:9], v[22:23], v[8:9]
	v_cvt_pk_bf16_f32 v0, v0, v1
	v_cvt_pk_bf16_f32 v1, v2, v3
	v_pk_mov_b32 v[18:19], v[36:37], v[34:35] op_sel:[1,0]
	v_cvt_pk_bf16_f32 v2, v8, v9
	v_cvt_pk_bf16_f32 v3, v10, v11
	global_store_dwordx4 v[16:17], v[0:3], off offset:2048
	s_nop 1
	s_nop 0
	v_pk_mul_f32 v[12:13], v[6:7], v[12:13] op_sel_hi:[0,1]
	v_pk_mul_f32 v[6:7], v[6:7], v[18:19] op_sel_hi:[0,1]
	v_mov_b32_e32 v0, v190
	v_mov_b32_e32 v1, v191
	v_mov_b32_e32 v2, v192
	v_mov_b32_e32 v3, v193
	v_mov_b32_e32 v8, v200
	v_mov_b32_e32 v9, v201
	v_mov_b32_e32 v10, v202
	v_mov_b32_e32 v11, v203
	v_pk_mul_f32 v[2:3], v[4:5], v[2:3]
	v_pk_mul_f32 v[0:1], v[14:15], v[0:1]
	v_pk_mul_f32 v[4:5], v[6:7], v[10:11]
	v_pk_mul_f32 v[6:7], v[12:13], v[8:9]
	v_cvt_pk_bf16_f32 v0, v0, v1
	v_cvt_pk_bf16_f32 v1, v2, v3
	s_nop 0
	v_cvt_pk_bf16_f32 v2, v6, v7
	v_cvt_pk_bf16_f32 v3, v4, v5
	global_store_dwordx4 v[16:17], v[0:3], off offset:3072
	s_nop 1

.LBB0_1291:
	s_or_b64 exec, exec, s[2:3]
	s_waitcnt lgkmcnt(0)
	s_barrier
	s_add_u32 s2, s34, 0x2aa00000
	s_mov_b32 s6, 25
	s_addc_u32 s3, s35, 0
	s_ashr_i32 s7, s6, 31
	s_lshl_b64 s[6:7], s[6:7], 3
	s_add_u32 s0, s0, s6
	s_addc_u32 s1, s1, s7
	s_load_dwordx2 s[0:1], s[0:1], 0x0
	v_and_b32_e32 v114, 63, v164
	s_and_b64 vcc, exec, s[4:5]
	v_lshlrev_b32_e32 v136, 4, v114
	v_lshlrev_b32_e32 v40, 5, v114
	s_cbranch_vccnz .LBB0_1293
	v_mov_b32_e32 v137, 0
	s_ashr_i32 s25, s24, 31
	v_lshl_add_u64 v[0:1], s[2:3], 0, v[136:137]
	s_lshl_b64 s[4:5], s[24:25], 12
	v_lshl_add_u64 v[2:3], v[0:1], 0, s[4:5]
	s_add_i32 s6, s24, s18
	flat_load_dwordx4 v[20:23], v[2:3] offset:1024
	flat_load_dwordx4 v[36:39], v[2:3] offset:2048
	flat_load_dwordx4 v[32:35], v[2:3] offset:3072
	flat_load_dwordx4 v[44:47], v[2:3]
	s_ashr_i32 s7, s6, 31
	s_lshl_b64 s[4:5], s[6:7], 12
	v_lshl_add_u64 v[2:3], v[0:1], 0, s[4:5]
	flat_load_dwordx4 v[48:51], v[2:3]
	flat_load_dwordx4 v[52:55], v[2:3] offset:1024
	flat_load_dwordx4 v[110:113], v[2:3] offset:2048
	flat_load_dwordx4 v[8:11], v[2:3] offset:3072
	v_readlane_b32 s14, v226, 1
	v_readlane_b32 s15, v226, 2
	s_ashr_i32 s15, s14, 31
	s_add_i32 s4, s6, s18
	s_lshl_b64 s[8:9], s[14:15], 12
	s_ashr_i32 s5, s4, 31
	v_lshl_add_u64 v[108:109], v[0:1], 0, s[8:9]
	s_lshl_b64 s[8:9], s[4:5], 12
	v_lshl_add_u64 v[42:43], v[0:1], 0, s[8:9]
	flat_load_dwordx4 v[28:31], v[108:109]
	flat_load_dwordx4 v[24:27], v[108:109] offset:1024
	flat_load_dwordx4 v[16:19], v[42:43]
	flat_load_dwordx4 v[12:15], v[42:43] offset:1024
	flat_load_dwordx4 v[4:7], v[42:43] offset:2048
	flat_load_dwordx4 v[0:3], v[42:43] offset:3072
	s_waitcnt lgkmcnt(0)
	v_add_u32_e32 v204, 0x1000, v40
	global_load_dwordx4 v[166:169], v40, s[0:1]
	global_load_dwordx4 v[170:173], v40, s[0:1] offset:16
	global_load_dwordx4 v[174:177], v40, s[0:1] offset:2048
	global_load_dwordx4 v[178:181], v40, s[0:1] offset:2064
	global_load_dwordx4 v[182:185], v204, s[0:1]
	global_load_dwordx4 v[186:189], v204, s[0:1] offset:16
	global_load_dwordx4 v[190:193], v204, s[0:1] offset:2048
	global_load_dwordx4 v[200:203], v204, s[0:1] offset:2064
	s_mov_b32 s12, 0x358637bd
	s_mov_b32 s8, 0x3a000000
	s_lshl_b64 s[10:11], s[24:25], 13
	s_add_u32 s10, s20, s10
	v_mov_b32_e32 v41, v137
	s_addc_u32 s11, s21, s11
	v_mov_b32_e32 v105, v137
	s_lshl_b64 s[6:7], s[6:7], 13
	s_add_u32 s6, s20, s6
	s_addc_u32 s7, s21, s7
	s_lshl_b64 s[4:5], s[4:5], 13
	s_add_u32 s4, s20, s4
	s_addc_u32 s5, s21, s5
	s_waitcnt vmcnt(0)
	v_mov_b32_e32 v122, v170
	v_mov_b32_e32 v123, v171
	v_mov_b32_e32 v124, v172
	v_mov_b32_e32 v125, v173
	v_mov_b32_e32 v126, v166
	v_mov_b32_e32 v127, v167
	v_mov_b32_e32 v128, v168
	v_mov_b32_e32 v129, v169
	v_lshlrev_b32_e32 v69, 16, v20
	v_lshlrev_b32_e32 v57, 16, v36
	v_and_b32_e32 v59, 0xffff0000, v36
	v_and_b32_e32 v75, 0xffff0000, v44
	v_and_b32_e32 v74, 0xffff0000, v48
	v_lshlrev_b32_e32 v67, 16, v44
	v_lshlrev_b32_e32 v71, 16, v45
	v_and_b32_e32 v79, 0xffff0000, v45
	v_and_b32_e32 v45, 0xffff0000, v37
	v_lshlrev_b32_e32 v63, 16, v37
	v_lshlrev_b32_e32 v66, 16, v48
	v_pk_mul_f32 v[36:37], v[74:75], v[74:75]
	v_lshlrev_b32_e32 v73, 16, v46
	v_and_b32_e32 v87, 0xffff0000, v46
	v_lshlrev_b32_e32 v85, 16, v47
	v_and_b32_e32 v99, 0xffff0000, v47
	v_lshlrev_b32_e32 v70, 16, v49
	v_pk_fma_f32 v[46:47], v[66:67], v[66:67], v[36:37]
	v_and_b32_e32 v78, 0xffff0000, v49
	v_pk_fma_f32 v[46:47], v[70:71], v[70:71], v[46:47]
	v_lshlrev_b32_e32 v72, 16, v50
	v_pk_fma_f32 v[46:47], v[78:79], v[78:79], v[46:47]
	v_and_b32_e32 v86, 0xffff0000, v50
	v_pk_fma_f32 v[46:47], v[72:73], v[72:73], v[46:47]
	v_lshlrev_b32_e32 v84, 16, v51
	v_pk_fma_f32 v[46:47], v[86:87], v[86:87], v[46:47]
	v_and_b32_e32 v98, 0xffff0000, v51
	v_pk_fma_f32 v[46:47], v[84:85], v[84:85], v[46:47]
	v_lshlrev_b32_e32 v68, 16, v52
	v_pk_fma_f32 v[46:47], v[98:99], v[98:99], v[46:47]
	v_and_b32_e32 v61, 0xffff0000, v20
	v_and_b32_e32 v60, 0xffff0000, v52
	v_pk_fma_f32 v[46:47], v[68:69], v[68:69], v[46:47]
	v_lshlrev_b32_e32 v77, 16, v21
	v_lshlrev_b32_e32 v76, 16, v53
	v_pk_fma_f32 v[46:47], v[60:61], v[60:61], v[46:47]
	v_and_b32_e32 v95, 0xffff0000, v21
	v_and_b32_e32 v94, 0xffff0000, v53
	v_pk_fma_f32 v[46:47], v[76:77], v[76:77], v[46:47]
	v_lshlrev_b32_e32 v81, 16, v22
	v_lshlrev_b32_e32 v80, 16, v54
	v_pk_fma_f32 v[46:47], v[94:95], v[94:95], v[46:47]
	v_and_b32_e32 v89, 0xffff0000, v22
	v_and_b32_e32 v88, 0xffff0000, v54
	v_pk_fma_f32 v[46:47], v[80:81], v[80:81], v[46:47]
	v_lshlrev_b32_e32 v91, 16, v23
	v_lshlrev_b32_e32 v90, 16, v55
	v_pk_fma_f32 v[46:47], v[88:89], v[88:89], v[46:47]
	v_and_b32_e32 v97, 0xffff0000, v23
	v_and_b32_e32 v96, 0xffff0000, v55
	v_pk_fma_f32 v[46:47], v[90:91], v[90:91], v[46:47]
	v_lshlrev_b32_e32 v56, 16, v110
	v_pk_fma_f32 v[46:47], v[96:97], v[96:97], v[46:47]
	v_and_b32_e32 v58, 0xffff0000, v110
	v_pk_fma_f32 v[46:47], v[56:57], v[56:57], v[46:47]
	v_lshlrev_b32_e32 v62, 16, v111
	v_pk_fma_f32 v[46:47], v[58:59], v[58:59], v[46:47]
	v_lshlrev_b32_e32 v43, 16, v38
	v_and_b32_e32 v65, 0xffff0000, v38
	v_and_b32_e32 v44, 0xffff0000, v111
	v_lshlrev_b32_e32 v83, 16, v39
	v_and_b32_e32 v93, 0xffff0000, v39
	v_pk_fma_f32 v[38:39], v[62:63], v[62:63], v[46:47]
	v_lshlrev_b32_e32 v42, 16, v112
	v_pk_fma_f32 v[38:39], v[44:45], v[44:45], v[38:39]
	v_and_b32_e32 v64, 0xffff0000, v112
	v_pk_fma_f32 v[38:39], v[42:43], v[42:43], v[38:39]
	v_lshlrev_b32_e32 v82, 16, v113
	v_pk_fma_f32 v[38:39], v[64:65], v[64:65], v[38:39]
	v_and_b32_e32 v92, 0xffff0000, v113
	v_pk_fma_f32 v[38:39], v[82:83], v[82:83], v[38:39]
	v_and_b32_e32 v100, 0xffff0000, v34
	v_pk_fma_f32 v[38:39], v[92:93], v[92:93], v[38:39]
	v_lshlrev_b32_e32 v47, 16, v32
	v_lshlrev_b32_e32 v46, 16, v8
	v_lshlrev_b32_e32 v103, 16, v34
	v_mov_b32_e32 v102, v100
	v_and_b32_e32 v34, 0xffff0000, v10
	v_and_b32_e32 v49, 0xffff0000, v32
	v_and_b32_e32 v48, 0xffff0000, v8
	v_lshlrev_b32_e32 v52, 16, v9
	v_and_b32_e32 v54, 0xffff0000, v9
	v_pk_fma_f32 v[8:9], v[46:47], v[46:47], v[38:39]
	v_lshlrev_b32_e32 v51, 16, v10
	v_pk_mul_f32 v[22:23], v[102:103], v[102:103]
	v_mov_b32_e32 v50, v34
	v_lshlrev_b32_e32 v53, 16, v33
	v_pk_fma_f32 v[8:9], v[48:49], v[48:49], v[8:9]
	v_and_b32_e32 v10, 64, v196
	v_and_b32_e32 v104, 0xffff0000, v35
	v_pk_mul_f32 v[36:37], v[50:51], v[50:51]
	v_and_b32_e32 v55, 0xffff0000, v33
	v_pk_fma_f32 v[8:9], v[52:53], v[52:53], v[8:9]
	v_mov_b32_e32 v33, v23
	v_and_b32_e32 v110, 0xffff0000, v11
	v_add_u32_e32 v10, 64, v10
	v_xor_b32_e32 v23, 1, v196
	v_lshlrev_b32_e32 v107, 16, v35
	v_mov_b32_e32 v106, v104
	v_pk_fma_f32 v[8:9], v[54:55], v[54:55], v[8:9]
	v_mov_b32_e32 v32, v37
	v_lshlrev_b32_e32 v113, 16, v11
	v_mov_b32_e32 v112, v110
	v_cmp_lt_i32_e32 vcc, v23, v10
	v_pk_mul_f32 v[20:21], v[106:107], v[106:107]
	v_pk_add_f32 v[8:9], v[32:33], v[8:9]
	v_pk_mul_f32 v[32:33], v[112:113], v[112:113]
	v_cndmask_b32_e32 v23, v196, v23, vcc
	v_mov_b32_e32 v37, v22
	v_lshlrev_b32_e32 v115, 2, v23
	v_pk_add_f32 v[8:9], v[36:37], v[8:9]
	v_mov_b32_e32 v22, v33
	v_mov_b32_e32 v23, v21
	v_pk_add_f32 v[8:9], v[22:23], v[8:9]
	v_mov_b32_e32 v33, v20
	v_pk_add_f32 v[8:9], v[32:33], v[8:9]
	ds_bpermute_b32 v21, v115, v9
	ds_bpermute_b32 v20, v115, v8
	v_xor_b32_e32 v22, 2, v196
	v_cmp_lt_i32_e32 vcc, v22, v10
	v_mov_b32_e32 v132, v71
	v_mov_b32_e32 v133, v79
	v_cndmask_b32_e32 v22, v196, v22, vcc
	v_lshlrev_b32_e32 v117, 2, v22
	s_waitcnt lgkmcnt(0)
	v_pk_add_f32 v[8:9], v[8:9], v[20:21]
	ds_bpermute_b32 v21, v117, v9
	ds_bpermute_b32 v20, v117, v8
	v_xor_b32_e32 v22, 4, v196
	v_cmp_lt_i32_e32 vcc, v22, v10
	v_mov_b32_e32 v134, v69
	v_mov_b32_e32 v135, v61
	v_cndmask_b32_e32 v22, v196, v22, vcc
	v_lshlrev_b32_e32 v118, 2, v22
	s_waitcnt lgkmcnt(0)
	v_pk_add_f32 v[8:9], v[8:9], v[20:21]
	ds_bpermute_b32 v21, v118, v9
	ds_bpermute_b32 v20, v118, v8
	v_xor_b32_e32 v22, 8, v196
	v_cmp_lt_i32_e32 vcc, v22, v10
	v_mov_b32_e32 v138, v91
	v_mov_b32_e32 v139, v97
	v_cndmask_b32_e32 v22, v196, v22, vcc
	v_lshlrev_b32_e32 v119, 2, v22
	s_waitcnt lgkmcnt(0)
	v_pk_add_f32 v[8:9], v[8:9], v[20:21]
	ds_bpermute_b32 v21, v119, v9
	ds_bpermute_b32 v20, v119, v8
	v_xor_b32_e32 v22, 16, v196
	v_cmp_lt_i32_e32 vcc, v22, v10
	v_mov_b32_e32 v140, v81
	v_mov_b32_e32 v141, v89
	v_cndmask_b32_e32 v22, v196, v22, vcc
	v_lshlrev_b32_e32 v120, 2, v22
	s_waitcnt lgkmcnt(0)
	v_pk_add_f32 v[8:9], v[8:9], v[20:21]
	ds_bpermute_b32 v21, v120, v9
	ds_bpermute_b32 v20, v120, v8
	v_xor_b32_e32 v22, 32, v196
	v_cmp_lt_i32_e32 vcc, v22, v10
	v_mov_b32_e32 v142, v43
	v_mov_b32_e32 v143, v65
	v_cndmask_b32_e32 v10, v196, v22, vcc
	v_lshlrev_b32_e32 v116, 2, v10
	s_waitcnt lgkmcnt(0)
	v_pk_add_f32 v[8:9], v[8:9], v[20:21]
	ds_bpermute_b32 v33, v116, v9
	ds_bpermute_b32 v32, v116, v8
	flat_load_dwordx4 v[36:39], v[108:109] offset:2048
	flat_load_dwordx4 v[20:23], v[108:109] offset:3072
	v_mov_b64_e32 v[108:109], s[12:13]
	v_and_b32_e32 v101, s0, v35
	v_pk_mov_b32 v[104:105], v[106:107], v[104:105] op_sel:[1,0]
	s_waitcnt lgkmcnt(0)
	v_pk_add_f32 v[8:9], v[8:9], v[32:33]
	v_mov_b32_e32 v33, v75
	v_pk_fma_f32 v[130:131], v[8:9], s[8:9], v[108:109] op_sel_hi:[1,0,0]
	s_mov_b32 s9, 0x800000
	v_mul_f32_e32 v8, 0x4b800000, v131
	v_cmp_gt_f32_e32 vcc, s9, v131
	v_pk_mov_b32 v[100:101], v[102:103], v[100:101] op_sel:[1,0]
	v_mov_b32_e32 v71, v78
	v_cndmask_b32_e32 v8, v131, v8, vcc
	v_rsq_f32_e32 v10, v8
	v_lshl_add_u64 v[8:9], s[10:11], 0, v[40:41]
	v_mov_b32_e32 v69, v60
	v_mov_b32_e32 v81, v88
	v_mul_f32_e32 v32, 0x45800000, v10
	v_cndmask_b32_e32 v10, v10, v32, vcc
	v_mov_b32_e32 v32, v67
	v_pk_mul_f32 v[32:33], v[32:33], v[10:11] op_sel_hi:[1,0]
	v_pk_mul_f32 v[132:133], v[132:133], v[10:11] op_sel_hi:[1,0]
	v_pk_mul_f32 v[126:127], v[126:127], v[32:33]
	v_pk_mul_f32 v[128:129], v[128:129], v[132:133]
	v_mov_b32_e32 v32, v73
	v_mov_b32_e32 v33, v87
	v_mov_b32_e32 v132, v85
	v_mov_b32_e32 v133, v99
	v_pk_mul_f32 v[32:33], v[32:33], v[10:11] op_sel_hi:[1,0]
	v_pk_mul_f32 v[132:133], v[132:133], v[10:11] op_sel_hi:[1,0]
	v_pk_mul_f32 v[122:123], v[122:123], v[32:33]
	v_pk_mul_f32 v[124:125], v[124:125], v[132:133]
	global_store_dwordx4 v[8:9], v[126:129], off
	s_nop 1
	global_store_dwordx4 v[8:9], v[122:125], off offset:16
	s_nop 1
	s_nop 0
	v_mov_b32_e32 v132, v77
	v_mov_b32_e32 v133, v95
	v_pk_mul_f32 v[132:133], v[132:133], v[10:11] op_sel_hi:[1,0]
	v_pk_mul_f32 v[134:135], v[134:135], v[10:11] op_sel_hi:[1,0]
	v_pk_mul_f32 v[138:139], v[138:139], v[10:11] op_sel_hi:[1,0]
	v_pk_mul_f32 v[140:141], v[140:141], v[10:11] op_sel_hi:[1,0]
	v_or_b32_e32 v32, 0x1000, v40
	v_mov_b32_e32 v33, v137
	v_pk_mul_f32 v[142:143], v[142:143], v[10:11] op_sel_hi:[1,0]
	v_cmp_gt_f32_e32 vcc, s9, v130
	v_mov_b32_e32 v67, v74
	v_mov_b32_e32 v73, v86
	v_mov_b32_e32 v85, v98
	v_mov_b32_e32 v77, v94
	v_mov_b32_e32 v91, v96
	v_lshlrev_b32_e32 v88, 16, v29
	v_and_b32_e32 v94, 0xffff0000, v29
	v_mov_b32_e32 v43, v64
	v_and_b32_e32 v96, 0xffff0000, v30
	v_and_b32_e32 v98, 0xffff0000, v31
	v_lshlrev_b32_e32 v89, 16, v17
	v_and_b32_e32 v95, 0xffff0000, v17
	v_and_b32_e32 v97, 0xffff0000, v18
	v_and_b32_e32 v99, 0xffff0000, v19
	v_mov_b32_e32 v111, v137
	v_and_b32_e32 v65, 0xffff0000, v7
	s_waitcnt vmcnt(2)
	v_mov_b32_e32 v122, v174
	v_mov_b32_e32 v123, v175
	v_mov_b32_e32 v124, v176
	v_mov_b32_e32 v125, v177
	v_mov_b32_e32 v126, v178
	v_mov_b32_e32 v127, v179
	v_mov_b32_e32 v128, v180
	v_mov_b32_e32 v129, v181
	v_and_b32_e32 v64, 0xffff0000, v39
	v_pk_mul_f32 v[122:123], v[122:123], v[134:135]
	v_pk_mul_f32 v[124:125], v[124:125], v[132:133]
	v_pk_mul_f32 v[126:127], v[126:127], v[140:141]
	v_pk_mul_f32 v[128:129], v[128:129], v[138:139]
	global_store_dwordx4 v[8:9], v[122:125], off offset:2048
	s_nop 1
	global_store_dwordx4 v[8:9], v[126:129], off offset:2064
	s_nop 1
	s_nop 0
	v_mov_b32_e32 v134, v63
	v_mov_b32_e32 v135, v45
	v_mov_b32_e32 v138, v57
	v_mov_b32_e32 v139, v59
	v_mov_b32_e32 v140, v83
	v_mov_b32_e32 v141, v93
	v_pk_mul_f32 v[134:135], v[134:135], v[10:11] op_sel_hi:[1,0]
	v_pk_mul_f32 v[138:139], v[138:139], v[10:11] op_sel_hi:[1,0]
	v_lshl_add_u64 v[132:133], s[10:11], 0, v[32:33]
	v_pk_mul_f32 v[140:141], v[140:141], v[10:11] op_sel_hi:[1,0]
	v_or_b32_e32 v8, 0x1800, v40
	v_mov_b32_e32 v9, v137
	v_mov_b32_e32 v57, v58
	v_mov_b32_e32 v63, v44
	v_mov_b32_e32 v83, v92
	v_and_b32_e32 v59, 0xffff0000, v4
	v_and_b32_e32 v58, 0xffff0000, v36
	v_and_b32_e32 v92, 0xffff0000, v2
	v_and_b32_e32 v93, s0, v3
	v_mov_b32_e32 v122, v182
	v_mov_b32_e32 v123, v183
	v_mov_b32_e32 v124, v184
	v_mov_b32_e32 v125, v185
	v_mov_b32_e32 v126, v186
	v_mov_b32_e32 v127, v187
	v_mov_b32_e32 v128, v188
	v_mov_b32_e32 v129, v189
	v_pk_mul_f32 v[122:123], v[122:123], v[138:139]
	v_pk_mul_f32 v[124:125], v[124:125], v[134:135]
	v_pk_mul_f32 v[126:127], v[126:127], v[142:143]
	v_pk_mul_f32 v[128:129], v[128:129], v[140:141]
	global_store_dwordx4 v[132:133], v[122:125], off
	s_nop 1
	global_store_dwordx4 v[132:133], v[126:129], off offset:16
	s_nop 1
	s_nop 0
	v_mov_b32_e32 v134, v53
	v_mov_b32_e32 v135, v55
	v_mov_b32_e32 v138, v47
	v_mov_b32_e32 v139, v49
	v_pk_mul_f32 v[102:103], v[134:135], v[10:11] op_sel_hi:[1,0]
	v_pk_mul_f32 v[106:107], v[138:139], v[10:11] op_sel_hi:[1,0]
	v_lshl_add_u64 v[132:133], s[10:11], 0, v[8:9]
	v_pk_mul_f32 v[134:135], v[10:11], v[104:105] op_sel_hi:[0,1]
	v_pk_mul_f32 v[104:105], v[10:11], v[100:101] op_sel_hi:[0,1]
	v_mul_f32_e32 v10, 0x4b800000, v130
	v_cndmask_b32_e32 v10, v130, v10, vcc
	v_rsq_f32_e32 v10, v10
	v_mov_b32_e32 v47, v48
	v_mov_b32_e32 v53, v54
	v_mov_b32_e32 v49, v99
	v_mul_f32_e32 v35, 0x45800000, v10
	v_cndmask_b32_e32 v130, v10, v35, vcc
	v_pk_mul_f32 v[74:75], v[70:71], v[130:131] op_sel_hi:[1,0]
	v_pk_mul_f32 v[66:67], v[66:67], v[130:131] op_sel_hi:[1,0]
	v_pk_mul_f32 v[78:79], v[84:85], v[130:131] op_sel_hi:[1,0]
	v_pk_mul_f32 v[84:85], v[72:73], v[130:131] op_sel_hi:[1,0]
	v_pk_mul_f32 v[60:61], v[76:77], v[130:131] op_sel_hi:[1,0]
	v_pk_mul_f32 v[76:77], v[80:81], v[130:131] op_sel_hi:[1,0]
	v_and_b32_e32 v80, 0xffff0000, v25
	v_pk_mul_f32 v[44:45], v[82:83], v[130:131] op_sel_hi:[1,0]
	v_pk_mul_f32 v[42:43], v[42:43], v[130:131] op_sel_hi:[1,0]
	v_and_b32_e32 v10, 0xffff0000, v22
	v_and_b32_e32 v82, 0xffff0000, v27
	v_and_b32_e32 v35, s0, v11
	v_and_b32_e32 v81, 0xffff0000, v13
	v_and_b32_e32 v83, 0xffff0000, v15
	v_mov_b32_e32 v122, v190
	v_mov_b32_e32 v123, v191
	v_mov_b32_e32 v124, v192
	v_mov_b32_e32 v125, v193
	v_mov_b32_e32 v126, v200
	v_mov_b32_e32 v127, v201
	v_mov_b32_e32 v128, v202
	v_mov_b32_e32 v129, v203
	v_pk_mul_f32 v[100:101], v[106:107], v[122:123]
	v_pk_mul_f32 v[102:103], v[102:103], v[124:125]
	v_pk_mul_f32 v[104:105], v[104:105], v[126:127]
	v_pk_mul_f32 v[106:107], v[134:135], v[128:129]
	global_store_dwordx4 v[132:133], v[100:103], off
	s_nop 1
	global_store_dwordx4 v[132:133], v[104:107], off offset:16
	s_nop 1
	s_nop 0
	v_lshl_add_u64 v[122:123], s[6:7], 0, v[40:41]
	v_lshl_add_u64 v[132:133], s[6:7], 0, v[8:9]
	v_mov_b32_e32 v100, v166
	v_mov_b32_e32 v101, v167
	v_mov_b32_e32 v102, v168
	v_mov_b32_e32 v103, v169
	v_mov_b32_e32 v104, v170
	v_mov_b32_e32 v105, v171
	v_mov_b32_e32 v106, v172
	v_mov_b32_e32 v107, v173
	v_pk_mul_f32 v[70:71], v[66:67], v[100:101]
	v_pk_mul_f32 v[72:73], v[74:75], v[102:103]
	v_pk_mul_f32 v[84:85], v[84:85], v[104:105]
	v_pk_mul_f32 v[86:87], v[78:79], v[106:107]
	global_store_dwordx4 v[122:123], v[70:73], off
	s_nop 1
	global_store_dwordx4 v[122:123], v[84:87], off offset:16
	s_nop 1
	s_nop 0
	v_pk_mul_f32 v[66:67], v[68:69], v[130:131] op_sel_hi:[1,0]
	v_pk_mul_f32 v[74:75], v[90:91], v[130:131] op_sel_hi:[1,0]
	v_and_b32_e32 v100, 0xffff0000, v28
	v_and_b32_e32 v78, 0xffff0000, v24
	v_lshl_add_u64 v[106:107], s[6:7], 0, v[32:33]
	v_lshlrev_b32_e32 v90, 16, v31
	v_and_b32_e32 v101, 0xffff0000, v16
	v_lshlrev_b32_e32 v91, 16, v19
	v_and_b32_e32 v79, 0xffff0000, v12
	v_mov_b32_e32 v48, v91
	v_mov_b32_e32 v70, v174
	v_mov_b32_e32 v71, v175
	v_mov_b32_e32 v72, v176
	v_mov_b32_e32 v73, v177
	v_mov_b32_e32 v84, v178
	v_mov_b32_e32 v85, v179
	v_mov_b32_e32 v86, v180
	v_mov_b32_e32 v87, v181
	v_pk_mul_f32 v[66:67], v[66:67], v[70:71]
	v_pk_mul_f32 v[68:69], v[60:61], v[72:73]
	v_pk_mul_f32 v[70:71], v[76:77], v[84:85]
	v_pk_mul_f32 v[72:73], v[74:75], v[86:87]
	global_store_dwordx4 v[122:123], v[66:69], off offset:2048
	s_nop 1
	global_store_dwordx4 v[122:123], v[70:73], off offset:2064
	s_nop 1
	s_nop 0
	v_lshlrev_b32_e32 v84, 16, v28
	v_lshlrev_b32_e32 v68, 16, v24
	v_lshlrev_b32_e32 v72, 16, v25
	v_pk_mul_f32 v[24:25], v[62:63], v[130:131] op_sel_hi:[1,0]
	v_pk_mul_f32 v[28:29], v[56:57], v[130:131] op_sel_hi:[1,0]
	v_lshlrev_b32_e32 v86, 16, v30
	v_lshlrev_b32_e32 v85, 16, v16
	v_and_b32_e32 v67, 0xffff0000, v5
	v_lshlrev_b32_e32 v87, 16, v18
	v_lshlrev_b32_e32 v60, 16, v38
	v_lshlrev_b32_e32 v70, 16, v26
	v_and_b32_e32 v76, 0xffff0000, v26
	v_lshlrev_b32_e32 v74, 16, v27
	v_lshlrev_b32_e32 v27, 16, v22
	v_and_b32_e32 v62, 0xffff0000, v38
	v_lshlrev_b32_e32 v56, 16, v39
	v_lshlrev_b32_e32 v39, 16, v23
	v_mov_b32_e32 v26, v10
	v_lshlrev_b32_e32 v69, 16, v12
	v_lshlrev_b32_e32 v73, 16, v13
	v_lshlrev_b32_e32 v71, 16, v14
	v_and_b32_e32 v77, 0xffff0000, v14
	v_lshlrev_b32_e32 v75, 16, v15
	v_pk_mul_f32 v[16:17], v[26:27], v[26:27]
	v_pk_mov_b32 v[12:13], v[50:51], v[34:35] op_sel:[1,0]
	v_lshlrev_b32_e32 v61, 16, v6
	v_and_b32_e32 v63, 0xffff0000, v6
	v_lshlrev_b32_e32 v57, 16, v7
	v_mov_b32_e32 v18, v17
	v_pk_mov_b32 v[6:7], v[112:113], v[110:111] op_sel:[1,0]
	v_pk_mul_f32 v[12:13], v[130:131], v[12:13] op_sel_hi:[0,1]
	v_and_b32_e32 v66, 0xffff0000, v37
	v_mov_b32_e32 v102, v182
	v_mov_b32_e32 v103, v183
	v_mov_b32_e32 v104, v184
	v_mov_b32_e32 v105, v185
	v_mov_b32_e32 v122, v186
	v_mov_b32_e32 v123, v187
	v_mov_b32_e32 v124, v188
	v_mov_b32_e32 v125, v189
	v_pk_mul_f32 v[28:29], v[28:29], v[102:103]
	v_pk_mul_f32 v[30:31], v[24:25], v[104:105]
	v_pk_mul_f32 v[42:43], v[42:43], v[122:123]
	v_pk_mul_f32 v[44:45], v[44:45], v[124:125]
	global_store_dwordx4 v[106:107], v[28:31], off
	s_nop 1
	global_store_dwordx4 v[106:107], v[42:45], off offset:16
	s_nop 1
	v_lshlrev_b32_e32 v43, 16, v4
	v_lshlrev_b32_e32 v45, 16, v5
	v_pk_mul_f32 v[4:5], v[100:101], v[100:101]
	v_lshlrev_b32_e32 v42, 16, v36
	v_pk_fma_f32 v[4:5], v[84:85], v[84:85], v[4:5]
	v_and_b32_e32 v36, 0xffff0000, v23
	v_pk_fma_f32 v[4:5], v[88:89], v[88:89], v[4:5]
	v_and_b32_e32 v104, 0xffff0000, v3
	v_pk_fma_f32 v[4:5], v[94:95], v[94:95], v[4:5]
	v_mov_b32_e32 v38, v36
	v_pk_fma_f32 v[4:5], v[86:87], v[86:87], v[4:5]
	v_lshlrev_b32_e32 v103, 16, v2
	v_pk_fma_f32 v[4:5], v[96:97], v[96:97], v[4:5]
	v_lshlrev_b32_e32 v107, 16, v3
	v_mov_b32_e32 v102, v92
	v_mov_b32_e32 v106, v104
	v_pk_fma_f32 v[4:5], v[90:91], v[90:91], v[4:5]
	v_lshlrev_b32_e32 v24, 16, v20
	v_and_b32_e32 v28, 0xffff0000, v20
	v_lshlrev_b32_e32 v20, 16, v21
	v_and_b32_e32 v30, 0xffff0000, v21
	v_lshlrev_b32_e32 v25, 16, v0
	v_and_b32_e32 v29, 0xffff0000, v0
	v_lshlrev_b32_e32 v21, 16, v1
	v_and_b32_e32 v31, 0xffff0000, v1
	v_pk_mul_f32 v[0:1], v[38:39], v[38:39]
	v_pk_mul_f32 v[14:15], v[102:103], v[102:103]
	v_pk_mul_f32 v[50:51], v[106:107], v[106:107]
	v_pk_fma_f32 v[4:5], v[98:99], v[98:99], v[4:5]
	v_mov_b32_e32 v34, v1
	v_mov_b32_e32 v19, v15
	v_mov_b32_e32 v17, v14
	v_mov_b32_e32 v35, v51
	v_mov_b32_e32 v1, v50
	v_pk_fma_f32 v[50:51], v[68:69], v[68:69], v[4:5]
	v_pk_mul_f32 v[14:15], v[52:53], v[130:131] op_sel_hi:[1,0]
	v_pk_mul_f32 v[4:5], v[46:47], v[130:131] op_sel_hi:[1,0]
	v_pk_mul_f32 v[46:47], v[130:131], v[6:7] op_sel_hi:[0,1]
	v_lshlrev_b32_e32 v44, 16, v37
	v_mov_b32_e32 v105, v137
	v_mov_b32_e32 v91, v98
	v_mov_b32_e32 v37, v137
	v_mov_b32_e32 v122, v200
	v_mov_b32_e32 v123, v201
	v_mov_b32_e32 v124, v202
	v_mov_b32_e32 v125, v203
	v_mov_b32_e32 v126, v190
	v_mov_b32_e32 v127, v191
	v_mov_b32_e32 v128, v192
	v_mov_b32_e32 v129, v193
	v_pk_mul_f32 v[12:13], v[12:13], v[122:123]
	v_pk_mul_f32 v[4:5], v[4:5], v[126:127]
	v_pk_mul_f32 v[6:7], v[14:15], v[128:129]
	v_pk_mul_f32 v[14:15], v[46:47], v[124:125]
	global_store_dwordx4 v[132:133], v[4:7], off
	s_nop 1
	global_store_dwordx4 v[132:133], v[12:15], off offset:16
	s_nop 1
	s_nop 0
	v_pk_fma_f32 v[46:47], v[78:79], v[78:79], v[50:51]
	s_nop 0
	v_pk_fma_f32 v[46:47], v[72:73], v[72:73], v[46:47]
	s_nop 0
	v_pk_fma_f32 v[46:47], v[80:81], v[80:81], v[46:47]
	s_nop 0
	v_pk_fma_f32 v[46:47], v[70:71], v[70:71], v[46:47]
	s_nop 0
	v_pk_fma_f32 v[46:47], v[76:77], v[76:77], v[46:47]
	s_nop 0
	v_pk_fma_f32 v[46:47], v[74:75], v[74:75], v[46:47]
	s_nop 0
	v_pk_fma_f32 v[46:47], v[82:83], v[82:83], v[46:47]
	s_nop 0
	v_pk_fma_f32 v[46:47], v[42:43], v[42:43], v[46:47]
	s_nop 0
	v_pk_fma_f32 v[46:47], v[58:59], v[58:59], v[46:47]
	s_nop 0
	v_pk_fma_f32 v[46:47], v[44:45], v[44:45], v[46:47]
	s_nop 0
	v_pk_fma_f32 v[46:47], v[66:67], v[66:67], v[46:47]
	s_nop 0
	v_pk_fma_f32 v[46:47], v[60:61], v[60:61], v[46:47]
	s_nop 0
	v_pk_fma_f32 v[46:47], v[62:63], v[62:63], v[46:47]
	s_nop 0
	v_pk_fma_f32 v[46:47], v[56:57], v[56:57], v[46:47]
	s_nop 0
	v_pk_fma_f32 v[46:47], v[64:65], v[64:65], v[46:47]
	s_nop 0
	v_pk_fma_f32 v[46:47], v[24:25], v[24:25], v[46:47]
	s_nop 0
	v_pk_fma_f32 v[46:47], v[28:29], v[28:29], v[46:47]
	s_nop 0
	v_pk_fma_f32 v[46:47], v[20:21], v[20:21], v[46:47]
	s_nop 0
	v_pk_fma_f32 v[46:47], v[30:31], v[30:31], v[46:47]
	s_nop 0
	v_pk_add_f32 v[18:19], v[18:19], v[46:47]
	v_mov_b32_e32 v46, v85
	v_pk_add_f32 v[16:17], v[16:17], v[18:19]
	v_mov_b32_e32 v47, v101
	v_pk_add_f32 v[16:17], v[34:35], v[16:17]
	v_mov_b32_e32 v34, v89
	v_pk_add_f32 v[0:1], v[0:1], v[16:17]
	ds_bpermute_b32 v17, v115, v1
	ds_bpermute_b32 v16, v115, v0
	v_mov_b32_e32 v35, v95
	v_lshl_add_u64 v[18:19], s[4:5], 0, v[40:41]
	v_mov_b32_e32 v85, v100
	v_mov_b32_e32 v89, v94
	s_waitcnt lgkmcnt(0)
	v_pk_add_f32 v[0:1], v[0:1], v[16:17]
	ds_bpermute_b32 v17, v117, v1
	ds_bpermute_b32 v16, v117, v0
	s_waitcnt lgkmcnt(0)
	v_pk_add_f32 v[0:1], v[0:1], v[16:17]
	ds_bpermute_b32 v17, v118, v1
	ds_bpermute_b32 v16, v118, v0
	s_waitcnt lgkmcnt(0)
	v_pk_add_f32 v[0:1], v[0:1], v[16:17]
	ds_bpermute_b32 v17, v119, v1
	ds_bpermute_b32 v16, v119, v0
	s_waitcnt lgkmcnt(0)
	v_pk_add_f32 v[0:1], v[0:1], v[16:17]
	ds_bpermute_b32 v17, v120, v1
	ds_bpermute_b32 v16, v120, v0
	s_waitcnt lgkmcnt(0)
	v_pk_add_f32 v[0:1], v[0:1], v[16:17]
	ds_bpermute_b32 v17, v116, v1
	ds_bpermute_b32 v16, v116, v0
	s_waitcnt lgkmcnt(0)
	v_pk_add_f32 v[0:1], v[0:1], v[16:17]
	s_nop 0
	v_pk_fma_f32 v[16:17], v[0:1], s[8:9], v[108:109] op_sel_hi:[1,0,0]
	v_mov_b32_e32 v1, v97
	v_mul_f32_e32 v0, 0x4b800000, v17
	v_cmp_gt_f32_e32 vcc, s9, v17
	s_nop 1
	v_cndmask_b32_e32 v0, v17, v0, vcc
	v_rsq_f32_e32 v2, v0
	v_mov_b32_e32 v0, v87
	v_mov_b32_e32 v87, v96
	v_mul_f32_e32 v11, 0x45800000, v2
	v_cndmask_b32_e32 v2, v2, v11, vcc
	v_pk_mul_f32 v[34:35], v[34:35], v[2:3] op_sel_hi:[1,0]
	v_pk_mul_f32 v[46:47], v[46:47], v[2:3] op_sel_hi:[1,0]
	v_pk_mul_f32 v[48:49], v[48:49], v[2:3] op_sel_hi:[1,0]
	v_pk_mul_f32 v[0:1], v[0:1], v[2:3] op_sel_hi:[1,0]
	v_mov_b32_e32 v4, v170
	v_mov_b32_e32 v5, v171
	v_mov_b32_e32 v6, v172
	v_mov_b32_e32 v7, v173
	v_mov_b32_e32 v12, v166
	v_mov_b32_e32 v13, v167
	v_mov_b32_e32 v14, v168
	v_mov_b32_e32 v15, v169
	v_pk_mul_f32 v[12:13], v[46:47], v[12:13]
	v_pk_mul_f32 v[14:15], v[34:35], v[14:15]
	v_pk_mul_f32 v[4:5], v[0:1], v[4:5]
	v_pk_mul_f32 v[6:7], v[48:49], v[6:7]
	global_store_dwordx4 v[18:19], v[12:15], off
	s_nop 1
	global_store_dwordx4 v[18:19], v[4:7], off offset:16
	s_nop 1
	s_nop 0
	v_mov_b32_e32 v0, v73
	v_mov_b32_e32 v1, v81
	v_mov_b32_e32 v34, v69
	v_mov_b32_e32 v35, v79
	v_mov_b32_e32 v46, v75
	v_mov_b32_e32 v47, v83
	v_mov_b32_e32 v48, v71
	v_mov_b32_e32 v49, v77
	v_pk_mul_f32 v[0:1], v[0:1], v[2:3] op_sel_hi:[1,0]
	v_pk_mul_f32 v[34:35], v[34:35], v[2:3] op_sel_hi:[1,0]
	v_pk_mul_f32 v[46:47], v[46:47], v[2:3] op_sel_hi:[1,0]
	v_pk_mul_f32 v[48:49], v[48:49], v[2:3] op_sel_hi:[1,0]
	v_mul_f32_e32 v11, 0x4b800000, v16
	v_cmp_gt_f32_e32 vcc, s9, v16
	v_mov_b32_e32 v69, v78
	v_mov_b32_e32 v73, v80
	v_cndmask_b32_e32 v11, v16, v11, vcc
	v_rsq_f32_e32 v11, v11
	v_mov_b32_e32 v71, v76
	v_mov_b32_e32 v75, v82
	v_mov_b32_e32 v4, v174
	v_mov_b32_e32 v5, v175
	v_mov_b32_e32 v6, v176
	v_mov_b32_e32 v7, v177
	v_mov_b32_e32 v12, v178
	v_mov_b32_e32 v13, v179
	v_mov_b32_e32 v14, v180
	v_mov_b32_e32 v15, v181
	v_pk_mul_f32 v[4:5], v[34:35], v[4:5]
	v_pk_mul_f32 v[6:7], v[0:1], v[6:7]
	v_pk_mul_f32 v[12:13], v[48:49], v[12:13]
	v_pk_mul_f32 v[14:15], v[46:47], v[14:15]
	global_store_dwordx4 v[18:19], v[4:7], off offset:2048
	s_nop 1
	global_store_dwordx4 v[18:19], v[12:15], off offset:2064
	s_nop 1
	s_nop 0
	v_mov_b32_e32 v18, v45
	v_mov_b32_e32 v19, v67
	v_mov_b32_e32 v34, v43
	v_mov_b32_e32 v35, v59
	v_mov_b32_e32 v46, v57
	v_mov_b32_e32 v47, v65
	v_mov_b32_e32 v48, v61
	v_mov_b32_e32 v49, v63
	v_pk_mul_f32 v[18:19], v[18:19], v[2:3] op_sel_hi:[1,0]
	v_pk_mul_f32 v[34:35], v[34:35], v[2:3] op_sel_hi:[1,0]
	v_lshl_add_u64 v[0:1], s[4:5], 0, v[32:33]
	v_pk_mul_f32 v[46:47], v[46:47], v[2:3] op_sel_hi:[1,0]
	v_pk_mul_f32 v[48:49], v[48:49], v[2:3] op_sel_hi:[1,0]
	v_mov_b32_e32 v43, v58
	v_mov_b32_e32 v45, v66
	v_mov_b32_e32 v61, v62
	v_mov_b32_e32 v57, v64
	v_mov_b32_e32 v4, v182
	v_mov_b32_e32 v5, v183
	v_mov_b32_e32 v6, v184
	v_mov_b32_e32 v7, v185
	v_mov_b32_e32 v12, v186
	v_mov_b32_e32 v13, v187
	v_mov_b32_e32 v14, v188
	v_mov_b32_e32 v15, v189
	v_pk_mul_f32 v[4:5], v[34:35], v[4:5]
	v_pk_mul_f32 v[6:7], v[18:19], v[6:7]
	v_pk_mul_f32 v[12:13], v[48:49], v[12:13]
	v_pk_mul_f32 v[14:15], v[46:47], v[14:15]
	global_store_dwordx4 v[0:1], v[4:7], off
	s_nop 1
	global_store_dwordx4 v[0:1], v[12:15], off offset:16
	s_nop 1
	s_nop 0
	v_mov_b32_e32 v0, v21
	v_mov_b32_e32 v1, v31
	v_mov_b32_e32 v34, v25
	v_mov_b32_e32 v35, v29
	v_pk_mov_b32 v[46:47], v[106:107], v[104:105] op_sel:[1,0]
	v_pk_mov_b32 v[48:49], v[102:103], v[92:93] op_sel:[1,0]
	v_pk_mul_f32 v[50:51], v[0:1], v[2:3] op_sel_hi:[1,0]
	v_pk_mul_f32 v[0:1], v[34:35], v[2:3] op_sel_hi:[1,0]
	v_lshl_add_u64 v[18:19], s[4:5], 0, v[8:9]
	v_pk_mul_f32 v[34:35], v[2:3], v[46:47] op_sel_hi:[0,1]
	v_pk_mul_f32 v[46:47], v[2:3], v[48:49] op_sel_hi:[0,1]
	s_lshl_b64 s[4:5], s[14:15], 13
	s_add_u32 s4, s20, s4
	s_addc_u32 s5, s21, s5
	v_mov_b32_e32 v25, v28
	v_mov_b32_e32 v21, v30
	s_lshl_b32 s6, s26, 5
	s_add_i32 s24, s24, s6
	v_mov_b32_e32 v4, v190
	v_mov_b32_e32 v5, v191
	v_mov_b32_e32 v6, v192
	v_mov_b32_e32 v7, v193
	v_mov_b32_e32 v12, v200
	v_mov_b32_e32 v13, v201
	v_mov_b32_e32 v14, v202
	v_mov_b32_e32 v15, v203
	v_pk_mul_f32 v[0:1], v[0:1], v[4:5]
	v_pk_mul_f32 v[2:3], v[50:51], v[6:7]
	v_pk_mul_f32 v[4:5], v[46:47], v[12:13]
	v_pk_mul_f32 v[6:7], v[34:35], v[14:15]
	global_store_dwordx4 v[18:19], v[0:3], off
	s_nop 1
	global_store_dwordx4 v[18:19], v[4:7], off offset:16
	s_nop 1
	s_nop 0
	v_mul_f32_e32 v14, 0x45800000, v11
	v_cndmask_b32_e32 v14, v11, v14, vcc
	v_pk_mul_f32 v[16:17], v[88:89], v[14:15] op_sel_hi:[1,0]
	v_pk_mul_f32 v[18:19], v[84:85], v[14:15] op_sel_hi:[1,0]
	v_lshl_add_u64 v[12:13], s[4:5], 0, v[40:41]
	v_pk_mul_f32 v[34:35], v[90:91], v[14:15] op_sel_hi:[1,0]
	v_pk_mul_f32 v[46:47], v[86:87], v[14:15] op_sel_hi:[1,0]
	v_and_b32_e32 v11, s0, v23
	v_pk_mov_b32 v[10:11], v[26:27], v[10:11] op_sel:[1,0]
	v_mov_b32_e32 v0, v166
	v_mov_b32_e32 v1, v167
	v_mov_b32_e32 v2, v168
	v_mov_b32_e32 v3, v169
	v_mov_b32_e32 v4, v170
	v_mov_b32_e32 v5, v171
	v_mov_b32_e32 v6, v172
	v_mov_b32_e32 v7, v173
	v_pk_mul_f32 v[0:1], v[18:19], v[0:1]
	v_pk_mul_f32 v[2:3], v[16:17], v[2:3]
	v_pk_mul_f32 v[4:5], v[46:47], v[4:5]
	v_pk_mul_f32 v[6:7], v[34:35], v[6:7]
	global_store_dwordx4 v[12:13], v[0:3], off
	s_nop 1
	global_store_dwordx4 v[12:13], v[4:7], off offset:16
	s_nop 1
	s_nop 0
	v_pk_mul_f32 v[16:17], v[72:73], v[14:15] op_sel_hi:[1,0]
	v_pk_mul_f32 v[18:19], v[68:69], v[14:15] op_sel_hi:[1,0]
	v_pk_mul_f32 v[34:35], v[74:75], v[14:15] op_sel_hi:[1,0]
	v_pk_mul_f32 v[46:47], v[70:71], v[14:15] op_sel_hi:[1,0]
	v_pk_mul_f32 v[10:11], v[14:15], v[10:11] op_sel_hi:[0,1]
	v_mov_b32_e32 v0, v174
	v_mov_b32_e32 v1, v175
	v_mov_b32_e32 v2, v176
	v_mov_b32_e32 v3, v177
	v_mov_b32_e32 v4, v178
	v_mov_b32_e32 v5, v179
	v_mov_b32_e32 v6, v180
	v_mov_b32_e32 v7, v181
	v_pk_mul_f32 v[0:1], v[18:19], v[0:1]
	v_pk_mul_f32 v[2:3], v[16:17], v[2:3]
	v_pk_mul_f32 v[4:5], v[46:47], v[4:5]
	v_pk_mul_f32 v[6:7], v[34:35], v[6:7]
	global_store_dwordx4 v[12:13], v[0:3], off offset:2048
	s_nop 1
	global_store_dwordx4 v[12:13], v[4:7], off offset:2064
	s_nop 1
	s_nop 0
	v_pk_mul_f32 v[16:17], v[44:45], v[14:15] op_sel_hi:[1,0]
	v_pk_mul_f32 v[18:19], v[42:43], v[14:15] op_sel_hi:[1,0]
	v_lshl_add_u64 v[12:13], s[4:5], 0, v[32:33]
	v_pk_mul_f32 v[32:33], v[56:57], v[14:15] op_sel_hi:[1,0]
	v_pk_mul_f32 v[34:35], v[60:61], v[14:15] op_sel_hi:[1,0]
	v_mov_b32_e32 v0, v182
	v_mov_b32_e32 v1, v183
	v_mov_b32_e32 v2, v184
	v_mov_b32_e32 v3, v185
	v_mov_b32_e32 v4, v186
	v_mov_b32_e32 v5, v187
	v_mov_b32_e32 v6, v188
	v_mov_b32_e32 v7, v189
	v_pk_mul_f32 v[0:1], v[18:19], v[0:1]
	v_pk_mul_f32 v[2:3], v[16:17], v[2:3]
	v_pk_mul_f32 v[4:5], v[34:35], v[4:5]
	v_pk_mul_f32 v[6:7], v[32:33], v[6:7]
	global_store_dwordx4 v[12:13], v[0:3], off
	s_nop 1
	global_store_dwordx4 v[12:13], v[4:7], off offset:16
	s_nop 1
	s_nop 0
	v_pk_mov_b32 v[12:13], v[38:39], v[36:37] op_sel:[1,0]
	v_pk_mul_f32 v[16:17], v[20:21], v[14:15] op_sel_hi:[1,0]
	v_pk_mul_f32 v[18:19], v[24:25], v[14:15] op_sel_hi:[1,0]
	v_lshl_add_u64 v[8:9], s[4:5], 0, v[8:9]
	v_pk_mul_f32 v[12:13], v[14:15], v[12:13] op_sel_hi:[0,1]
	v_mov_b32_e32 v0, v190
	v_mov_b32_e32 v1, v191
	v_mov_b32_e32 v2, v192
	v_mov_b32_e32 v3, v193
	v_mov_b32_e32 v4, v200
	v_mov_b32_e32 v5, v201
	v_mov_b32_e32 v6, v202
	v_mov_b32_e32 v7, v203
	v_pk_mul_f32 v[0:1], v[18:19], v[0:1]
	v_pk_mul_f32 v[2:3], v[16:17], v[2:3]
	v_pk_mul_f32 v[4:5], v[10:11], v[4:5]
	v_pk_mul_f32 v[6:7], v[12:13], v[6:7]
	global_store_dwordx4 v[8:9], v[0:3], off
	s_nop 1
	global_store_dwordx4 v[8:9], v[4:7], off offset:16
	s_nop 1
